# v053 + one static s_setprio 1 for waves 0-3 around each GEMM K loop
# speedup vs baseline: 1.0006x; 1.0006x over previous
.Lkprio_311:
.LBB0_311:
	v_add_u32_e32 v164, 0x10000, v143
	v_add_u32_e32 v180, 0x14000, v143
	ds_read_b128 v[138:141], v164
	ds_read_b128 v[156:159], v164 offset:1024
	ds_read_b128 v[160:163], v164 offset:2048
	ds_read_b128 v[164:167], v164 offset:3072
	ds_read_b128 v[168:171], v180
	ds_read_b128 v[172:175], v180 offset:1024
	ds_read_b128 v[176:179], v180 offset:2048
	ds_read_b128 v[204:207], v180 offset:3072
	ds_read_b128 v[208:211], v155
	ds_read_b128 v[212:215], v155 offset:1024
	ds_read_b128 v[216:219], v155 offset:2048
	ds_read_b128 v[220:223], v155 offset:3072
	ds_read_b128 v[224:227], v155 offset:4096
	ds_read_b128 v[228:231], v155 offset:5120
	ds_read_b128 v[232:235], v155 offset:6144
	ds_read_b128 v[236:239], v155 offset:7168
	s_add_u32 s4, s62, 0xfffc0080
	s_addc_u32 s5, s63, -1
	s_add_i32 s84, 0, 0x10000
	s_cmp_eq_u32 s82, 12
	s_cselect_b32 s65, s33, s5
	s_cselect_b32 s64, s36, s4
	s_cselect_b32 s35, s53, s79
	s_cselect_b32 s34, s55, s75
	s_add_i32 s4, 0, 0x14000
	v_lshl_add_u64 v[180:181], s[62:63], 0, v[134:135]
	s_add_i32 m0, s68, 0xc000
	s_nop 0
	global_load_lds_dwordx4 v[180:181], off
	v_lshl_add_u64 v[180:181], s[62:63], 0, v[136:137]
	s_add_i32 m0, s68, 0xe000
	s_nop 0
	global_load_lds_dwordx4 v[180:181], off
	s_waitcnt vmcnt(8)
	s_waitcnt lgkmcnt(0)
	s_barrier
	v_mfma_f32_16x16x32_bf16 v[124:127], v[138:141], v[208:211], v[124:127]
	v_mfma_f32_16x16x32_bf16 v[120:123], v[160:163], v[208:211], v[120:123]
	v_mfma_f32_16x16x32_bf16 v[108:111], v[138:141], v[216:219], v[108:111]
	v_mfma_f32_16x16x32_bf16 v[104:107], v[160:163], v[216:219], v[104:107]
	v_mfma_f32_16x16x32_bf16 v[92:95], v[138:141], v[224:227], v[92:95]
	v_mfma_f32_16x16x32_bf16 v[88:91], v[160:163], v[224:227], v[88:91]
	v_mfma_f32_16x16x32_bf16 v[76:79], v[138:141], v[232:235], v[76:79]
	v_mfma_f32_16x16x32_bf16 v[72:75], v[160:163], v[232:235], v[72:75]
	v_mfma_f32_16x16x32_bf16 v[124:127], v[156:159], v[212:215], v[124:127]
	v_mfma_f32_16x16x32_bf16 v[120:123], v[164:167], v[212:215], v[120:123]
	v_mfma_f32_16x16x32_bf16 v[108:111], v[156:159], v[220:223], v[108:111]
	v_mfma_f32_16x16x32_bf16 v[104:107], v[164:167], v[220:223], v[104:107]
	v_mfma_f32_16x16x32_bf16 v[92:95], v[156:159], v[228:231], v[92:95]
	v_mfma_f32_16x16x32_bf16 v[88:91], v[164:167], v[228:231], v[88:91]
	v_mfma_f32_16x16x32_bf16 v[76:79], v[156:159], v[236:239], v[76:79]
	v_mfma_f32_16x16x32_bf16 v[72:75], v[164:167], v[236:239], v[72:75]
	v_mfma_f32_16x16x32_bf16 v[116:119], v[168:171], v[208:211], v[116:119]
	v_mfma_f32_16x16x32_bf16 v[112:115], v[176:179], v[208:211], v[112:115]
	v_mfma_f32_16x16x32_bf16 v[100:103], v[168:171], v[216:219], v[100:103]
	v_mfma_f32_16x16x32_bf16 v[96:99], v[176:179], v[216:219], v[96:99]
	v_mfma_f32_16x16x32_bf16 v[84:87], v[168:171], v[224:227], v[84:87]
	v_mfma_f32_16x16x32_bf16 v[80:83], v[176:179], v[224:227], v[80:83]
	v_mfma_f32_16x16x32_bf16 v[68:71], v[168:171], v[232:235], v[68:71]
	v_mfma_f32_16x16x32_bf16 v[64:67], v[176:179], v[232:235], v[64:67]
	v_mfma_f32_16x16x32_bf16 v[116:119], v[172:175], v[212:215], v[116:119]
	v_mfma_f32_16x16x32_bf16 v[112:115], v[204:207], v[212:215], v[112:115]
	v_mfma_f32_16x16x32_bf16 v[100:103], v[172:175], v[220:223], v[100:103]
	v_mfma_f32_16x16x32_bf16 v[96:99], v[204:207], v[220:223], v[96:99]
	v_mfma_f32_16x16x32_bf16 v[84:87], v[172:175], v[228:231], v[84:87]
	v_mfma_f32_16x16x32_bf16 v[80:83], v[204:207], v[228:231], v[80:83]
	v_mfma_f32_16x16x32_bf16 v[68:71], v[172:175], v[236:239], v[68:71]
	v_mfma_f32_16x16x32_bf16 v[64:67], v[204:207], v[236:239], v[64:67]
	s_barrier
	s_add_i32 s5, s84, s28
	v_lshl_add_u64 v[180:181], s[34:35], 0, v[144:145]
	s_mov_b32 m0, s5
	ds_read_b128 v[208:211], v155 offset:16384
	ds_read_b128 v[212:215], v155 offset:17408
	ds_read_b128 v[216:219], v155 offset:18432
	ds_read_b128 v[220:223], v155 offset:19456
	ds_read_b128 v[224:227], v155 offset:20480
	ds_read_b128 v[228:231], v155 offset:21504
	ds_read_b128 v[232:235], v155 offset:22528
	ds_read_b128 v[236:239], v155 offset:23552
	global_load_lds_dwordx4 v[180:181], off
	s_add_i32 m0, s5, 0x2000
	s_add_u32 s88, s34, 0x40000
	v_lshl_add_u64 v[240:241], s[34:35], 0, v[128:129]
	s_addc_u32 s89, s35, 0
	s_add_i32 s4, s4, s28
	global_load_lds_dwordx4 v[240:241], off
	v_lshl_add_u64 v[242:243], s[88:89], 0, v[144:145]
	s_mov_b32 m0, s4
	v_lshl_add_u64 v[244:245], s[64:65], 0, v[130:131]
	global_load_lds_dwordx4 v[242:243], off
	v_lshl_add_u64 v[242:243], s[88:89], 0, v[128:129]
	s_add_i32 m0, s4, 0x2000
	s_nop 0
	global_load_lds_dwordx4 v[242:243], off
	v_lshl_add_u64 v[242:243], s[64:65], 0, v[132:133]
	s_mov_b32 m0, s68
	s_nop 0
	global_load_lds_dwordx4 v[242:243], off
	s_mov_b32 m0, s69
	s_nop 0
	global_load_lds_dwordx4 v[244:245], off
	s_waitcnt vmcnt(8)
	s_waitcnt lgkmcnt(0)
	s_barrier
	v_mfma_f32_16x16x32_bf16 v[60:63], v[138:141], v[208:211], v[60:63]
	v_mfma_f32_16x16x32_bf16 v[56:59], v[160:163], v[208:211], v[56:59]
	v_mfma_f32_16x16x32_bf16 v[44:47], v[138:141], v[216:219], v[44:47]
	v_mfma_f32_16x16x32_bf16 v[40:43], v[160:163], v[216:219], v[40:43]
	v_mfma_f32_16x16x32_bf16 v[28:31], v[138:141], v[224:227], v[28:31]
	v_mfma_f32_16x16x32_bf16 v[24:27], v[160:163], v[224:227], v[24:27]
	v_mfma_f32_16x16x32_bf16 v[12:15], v[138:141], v[232:235], v[12:15]
	v_mfma_f32_16x16x32_bf16 v[8:11], v[160:163], v[232:235], v[8:11]
	v_mfma_f32_16x16x32_bf16 v[60:63], v[156:159], v[212:215], v[60:63]
	v_mfma_f32_16x16x32_bf16 v[56:59], v[164:167], v[212:215], v[56:59]
	v_mfma_f32_16x16x32_bf16 v[44:47], v[156:159], v[220:223], v[44:47]
	v_mfma_f32_16x16x32_bf16 v[40:43], v[164:167], v[220:223], v[40:43]
	v_mfma_f32_16x16x32_bf16 v[28:31], v[156:159], v[228:231], v[28:31]
	v_mfma_f32_16x16x32_bf16 v[24:27], v[164:167], v[228:231], v[24:27]
	v_mfma_f32_16x16x32_bf16 v[12:15], v[156:159], v[236:239], v[12:15]
	v_mfma_f32_16x16x32_bf16 v[8:11], v[164:167], v[236:239], v[8:11]
	v_mfma_f32_16x16x32_bf16 v[52:55], v[168:171], v[208:211], v[52:55]
	v_mfma_f32_16x16x32_bf16 v[48:51], v[176:179], v[208:211], v[48:51]
	v_mfma_f32_16x16x32_bf16 v[36:39], v[168:171], v[216:219], v[36:39]
	v_mfma_f32_16x16x32_bf16 v[32:35], v[176:179], v[216:219], v[32:35]
	v_mfma_f32_16x16x32_bf16 v[20:23], v[168:171], v[224:227], v[20:23]
	v_mfma_f32_16x16x32_bf16 v[16:19], v[176:179], v[224:227], v[16:19]
	v_mfma_f32_16x16x32_bf16 v[4:7], v[168:171], v[232:235], v[4:7]
	v_mfma_f32_16x16x32_bf16 v[0:3], v[176:179], v[232:235], v[0:3]
	v_mfma_f32_16x16x32_bf16 v[52:55], v[172:175], v[212:215], v[52:55]
	v_mfma_f32_16x16x32_bf16 v[48:51], v[204:207], v[212:215], v[48:51]
	v_mfma_f32_16x16x32_bf16 v[36:39], v[172:175], v[220:223], v[36:39]
	v_mfma_f32_16x16x32_bf16 v[32:35], v[204:207], v[220:223], v[32:35]
	v_mfma_f32_16x16x32_bf16 v[20:23], v[172:175], v[228:231], v[20:23]
	v_mfma_f32_16x16x32_bf16 v[16:19], v[204:207], v[228:231], v[16:19]
	v_mfma_f32_16x16x32_bf16 v[4:7], v[172:175], v[236:239], v[4:7]
	v_mfma_f32_16x16x32_bf16 v[0:3], v[204:207], v[236:239], v[0:3]
	s_barrier
	v_add_u32_e32 v164, 0x18000, v143
	v_add_u32_e32 v202, 0x1c000, v143
	ds_read_b128 v[138:141], v164
	ds_read_b128 v[156:159], v164 offset:1024
	ds_read_b128 v[160:163], v164 offset:2048
	ds_read_b128 v[164:167], v164 offset:3072
	ds_read_b128 v[168:171], v202
	ds_read_b128 v[172:175], v202 offset:1024
	ds_read_b128 v[176:179], v202 offset:2048
	ds_read_b128 v[204:207], v202 offset:3072
	ds_read_b128 v[208:211], v155 offset:32768
	ds_read_b128 v[212:215], v155 offset:33792
	ds_read_b128 v[216:219], v155 offset:34816
	ds_read_b128 v[220:223], v155 offset:35840
	ds_read_b128 v[224:227], v155 offset:36864
	ds_read_b128 v[228:231], v155 offset:37888
	ds_read_b128 v[232:235], v155 offset:38912
	ds_read_b128 v[236:239], v155 offset:39936
	s_add_i32 s4, 0, 0x18000
	s_add_i32 s5, 0, 0x1c000
	s_add_u32 s64, s64, 0x40000
	s_addc_u32 s65, s65, 0
	s_mov_b32 m0, s70
	v_lshl_add_u64 v[246:247], s[64:65], 0, v[132:133]
	global_load_lds_dwordx4 v[246:247], off
	v_lshl_add_u64 v[246:247], s[64:65], 0, v[130:131]
	s_mov_b32 m0, s71
	s_nop 0
	global_load_lds_dwordx4 v[246:247], off
	s_waitcnt vmcnt(8)
	s_waitcnt lgkmcnt(0)
	s_barrier
	v_mfma_f32_16x16x32_bf16 v[124:127], v[138:141], v[208:211], v[124:127]
	v_mfma_f32_16x16x32_bf16 v[120:123], v[160:163], v[208:211], v[120:123]
	v_mfma_f32_16x16x32_bf16 v[108:111], v[138:141], v[216:219], v[108:111]
	v_mfma_f32_16x16x32_bf16 v[104:107], v[160:163], v[216:219], v[104:107]
	v_mfma_f32_16x16x32_bf16 v[92:95], v[138:141], v[224:227], v[92:95]
	v_mfma_f32_16x16x32_bf16 v[88:91], v[160:163], v[224:227], v[88:91]
	v_mfma_f32_16x16x32_bf16 v[76:79], v[138:141], v[232:235], v[76:79]
	v_mfma_f32_16x16x32_bf16 v[72:75], v[160:163], v[232:235], v[72:75]
	v_mfma_f32_16x16x32_bf16 v[124:127], v[156:159], v[212:215], v[124:127]
	v_mfma_f32_16x16x32_bf16 v[120:123], v[164:167], v[212:215], v[120:123]
	v_mfma_f32_16x16x32_bf16 v[108:111], v[156:159], v[220:223], v[108:111]
	v_mfma_f32_16x16x32_bf16 v[104:107], v[164:167], v[220:223], v[104:107]
	v_mfma_f32_16x16x32_bf16 v[92:95], v[156:159], v[228:231], v[92:95]
	v_mfma_f32_16x16x32_bf16 v[88:91], v[164:167], v[228:231], v[88:91]
	v_mfma_f32_16x16x32_bf16 v[76:79], v[156:159], v[236:239], v[76:79]
	v_mfma_f32_16x16x32_bf16 v[72:75], v[164:167], v[236:239], v[72:75]
	v_mfma_f32_16x16x32_bf16 v[116:119], v[168:171], v[208:211], v[116:119]
	v_mfma_f32_16x16x32_bf16 v[112:115], v[176:179], v[208:211], v[112:115]
	v_mfma_f32_16x16x32_bf16 v[100:103], v[168:171], v[216:219], v[100:103]
	v_mfma_f32_16x16x32_bf16 v[96:99], v[176:179], v[216:219], v[96:99]
	v_mfma_f32_16x16x32_bf16 v[84:87], v[168:171], v[224:227], v[84:87]
	v_mfma_f32_16x16x32_bf16 v[80:83], v[176:179], v[224:227], v[80:83]
	v_mfma_f32_16x16x32_bf16 v[68:71], v[168:171], v[232:235], v[68:71]
	v_mfma_f32_16x16x32_bf16 v[64:67], v[176:179], v[232:235], v[64:67]
	v_mfma_f32_16x16x32_bf16 v[116:119], v[172:175], v[212:215], v[116:119]
	v_mfma_f32_16x16x32_bf16 v[112:115], v[204:207], v[212:215], v[112:115]
	v_mfma_f32_16x16x32_bf16 v[100:103], v[172:175], v[220:223], v[100:103]
	v_mfma_f32_16x16x32_bf16 v[96:99], v[204:207], v[220:223], v[96:99]
	v_mfma_f32_16x16x32_bf16 v[84:87], v[172:175], v[228:231], v[84:87]
	v_mfma_f32_16x16x32_bf16 v[80:83], v[204:207], v[228:231], v[80:83]
	v_mfma_f32_16x16x32_bf16 v[68:71], v[172:175], v[236:239], v[68:71]
	v_mfma_f32_16x16x32_bf16 v[64:67], v[204:207], v[236:239], v[64:67]
	s_barrier
	s_add_i32 s4, s4, s28
	v_lshl_add_u64 v[180:181], v[180:181], 0, s[26:27]
	s_mov_b32 m0, s4
	ds_read_b128 v[208:211], v155 offset:49152
	ds_read_b128 v[212:215], v155 offset:50176
	ds_read_b128 v[216:219], v155 offset:51200
	ds_read_b128 v[220:223], v155 offset:52224
	ds_read_b128 v[224:227], v155 offset:53248
	ds_read_b128 v[228:231], v155 offset:54272
	ds_read_b128 v[232:235], v155 offset:55296
	ds_read_b128 v[236:239], v155 offset:56320
	global_load_lds_dwordx4 v[180:181], off
	s_add_i32 m0, s4, 0x2000
	s_add_u32 s34, s34, 0x40080
	v_lshl_add_u64 v[180:181], v[240:241], 0, s[26:27]
	s_addc_u32 s35, s35, 0
	s_add_i32 s4, s5, s28
	global_load_lds_dwordx4 v[180:181], off
	v_lshl_add_u64 v[180:181], s[34:35], 0, v[144:145]
	s_mov_b32 m0, s4
	s_nop 0
	global_load_lds_dwordx4 v[180:181], off
	v_lshl_add_u64 v[180:181], s[34:35], 0, v[128:129]
	s_add_i32 m0, s4, 0x2000
	s_nop 0
	global_load_lds_dwordx4 v[180:181], off
	v_lshl_add_u64 v[180:181], v[242:243], 0, s[26:27]
	s_mov_b32 m0, s72
	s_nop 0
	global_load_lds_dwordx4 v[180:181], off
	v_lshl_add_u64 v[180:181], v[244:245], 0, s[26:27]
	s_mov_b32 m0, s73
	s_nop 0
	global_load_lds_dwordx4 v[180:181], off
	s_add_i32 s82, s82, 2
	s_add_u32 s62, s62, 0x100
	s_addc_u32 s63, s63, 0
	s_add_u32 s75, s75, 0x100
	s_addc_u32 s79, s79, 0
	s_cmp_gt_u32 s82, 13
	s_waitcnt vmcnt(8)
	s_waitcnt lgkmcnt(0)
	s_barrier
	v_mfma_f32_16x16x32_bf16 v[60:63], v[138:141], v[208:211], v[60:63]
	v_mfma_f32_16x16x32_bf16 v[56:59], v[160:163], v[208:211], v[56:59]
	v_mfma_f32_16x16x32_bf16 v[44:47], v[138:141], v[216:219], v[44:47]
	v_mfma_f32_16x16x32_bf16 v[40:43], v[160:163], v[216:219], v[40:43]
	v_mfma_f32_16x16x32_bf16 v[28:31], v[138:141], v[224:227], v[28:31]
	v_mfma_f32_16x16x32_bf16 v[24:27], v[160:163], v[224:227], v[24:27]
	v_mfma_f32_16x16x32_bf16 v[12:15], v[138:141], v[232:235], v[12:15]
	v_mfma_f32_16x16x32_bf16 v[8:11], v[160:163], v[232:235], v[8:11]
	v_mfma_f32_16x16x32_bf16 v[60:63], v[156:159], v[212:215], v[60:63]
	v_mfma_f32_16x16x32_bf16 v[56:59], v[164:167], v[212:215], v[56:59]
	v_mfma_f32_16x16x32_bf16 v[44:47], v[156:159], v[220:223], v[44:47]
	v_mfma_f32_16x16x32_bf16 v[40:43], v[164:167], v[220:223], v[40:43]
	v_mfma_f32_16x16x32_bf16 v[28:31], v[156:159], v[228:231], v[28:31]
	v_mfma_f32_16x16x32_bf16 v[24:27], v[164:167], v[228:231], v[24:27]
	v_mfma_f32_16x16x32_bf16 v[12:15], v[156:159], v[236:239], v[12:15]
	v_mfma_f32_16x16x32_bf16 v[8:11], v[164:167], v[236:239], v[8:11]
	v_mfma_f32_16x16x32_bf16 v[52:55], v[168:171], v[208:211], v[52:55]
	v_mfma_f32_16x16x32_bf16 v[48:51], v[176:179], v[208:211], v[48:51]
	v_mfma_f32_16x16x32_bf16 v[36:39], v[168:171], v[216:219], v[36:39]
	v_mfma_f32_16x16x32_bf16 v[32:35], v[176:179], v[216:219], v[32:35]
	v_mfma_f32_16x16x32_bf16 v[20:23], v[168:171], v[224:227], v[20:23]
	v_mfma_f32_16x16x32_bf16 v[16:19], v[176:179], v[224:227], v[16:19]
	v_mfma_f32_16x16x32_bf16 v[4:7], v[168:171], v[232:235], v[4:7]
	v_mfma_f32_16x16x32_bf16 v[0:3], v[176:179], v[232:235], v[0:3]
	v_mfma_f32_16x16x32_bf16 v[52:55], v[172:175], v[212:215], v[52:55]
	v_mfma_f32_16x16x32_bf16 v[48:51], v[204:207], v[212:215], v[48:51]
	v_mfma_f32_16x16x32_bf16 v[36:39], v[172:175], v[220:223], v[36:39]
	v_mfma_f32_16x16x32_bf16 v[32:35], v[204:207], v[220:223], v[32:35]
	v_mfma_f32_16x16x32_bf16 v[20:23], v[172:175], v[228:231], v[20:23]
	v_mfma_f32_16x16x32_bf16 v[16:19], v[204:207], v[228:231], v[16:19]
	v_mfma_f32_16x16x32_bf16 v[4:7], v[172:175], v[236:239], v[4:7]
	v_mfma_f32_16x16x32_bf16 v[0:3], v[204:207], v[236:239], v[0:3]
	s_barrier
	s_cbranch_scc0 .LBB0_311
	s_setprio 0
	v_lshl_add_u32 v140, s2, 8, v142
	v_ashrrev_i32_e32 v141, 31, v140
	v_lshl_add_u64 v[156:157], v[140:141], 4, s[48:49]
	global_load_dwordx4 v[208:211], v[156:157], off
	global_load_dwordx4 v[212:215], v[156:157], off offset:256
	global_load_dwordx4 v[216:219], v[156:157], off offset:512
	global_load_dwordx4 v[220:223], v[156:157], off offset:768
	global_load_dwordx4 v[224:227], v[156:157], off offset:2048
	global_load_dwordx4 v[228:231], v[156:157], off offset:2304
	global_load_dwordx4 v[232:235], v[156:157], off offset:2560
	global_load_dwordx4 v[236:239], v[156:157], off offset:2816
	s_and_b64 vcc, exec, s[50:51]
	s_cbranch_vccz .LBB0_314
	s_barrier

.Lkprio_406:
.LBB0_406:
	v_add_u32_e32 v142, 0x10000, v160
	ds_read_b128 v[138:141], v142
	ds_read_b128 v[154:157], v142 offset:1024
	ds_read_b128 v[172:175], v142 offset:2048
	ds_read_b128 v[176:179], v142 offset:3072
	v_add_u32_e32 v142, 0x14000, v160
	ds_read_b128 v[204:207], v142
	ds_read_b128 v[208:211], v142 offset:1024
	ds_read_b128 v[212:215], v142 offset:2048
	ds_read_b128 v[216:219], v142 offset:3072
	ds_read_b128 v[220:223], v170
	ds_read_b128 v[224:227], v170 offset:1024
	ds_read_b128 v[228:231], v170 offset:2048
	ds_read_b128 v[232:235], v170 offset:3072
	ds_read_b128 v[236:239], v170 offset:4096
	ds_read_b128 v[240:243], v170 offset:5120
	ds_read_b128 v[244:247], v170 offset:6144
	ds_read_b128 v[248:251], v170 offset:7168
	s_add_u32 s62, s60, 0x100
	s_addc_u32 s63, s61, 0
	s_add_i32 s4, 0, 0x10000
	s_cmp_eq_u32 s29, 40
	s_cselect_b32 s65, s45, s63
	s_cselect_b32 s64, s44, s62
	s_cselect_b32 s35, s59, s28
	s_cselect_b32 s34, s58, s3
	s_add_i32 s5, 0, 0x14000
	v_lshl_add_u64 v[142:143], s[60:61], 0, v[134:135]
	s_add_i32 m0, s36, 0xc000
	s_nop 0
	global_load_lds_dwordx4 v[142:143], off
	v_lshl_add_u64 v[142:143], s[60:61], 0, v[136:137]
	s_add_i32 m0, s36, 0xe000
	s_nop 0
	global_load_lds_dwordx4 v[142:143], off
	s_waitcnt vmcnt(8)
	s_waitcnt lgkmcnt(0)
	s_barrier
	v_mfma_f32_16x16x32_bf16 v[124:127], v[138:141], v[220:223], v[124:127]
	v_mfma_f32_16x16x32_bf16 v[120:123], v[172:175], v[220:223], v[120:123]
	v_mfma_f32_16x16x32_bf16 v[108:111], v[138:141], v[228:231], v[108:111]
	v_mfma_f32_16x16x32_bf16 v[104:107], v[172:175], v[228:231], v[104:107]
	v_mfma_f32_16x16x32_bf16 v[92:95], v[138:141], v[236:239], v[92:95]
	v_mfma_f32_16x16x32_bf16 v[88:91], v[172:175], v[236:239], v[88:91]
	v_mfma_f32_16x16x32_bf16 v[76:79], v[138:141], v[244:247], v[76:79]
	v_mfma_f32_16x16x32_bf16 v[72:75], v[172:175], v[244:247], v[72:75]
	v_mfma_f32_16x16x32_bf16 v[124:127], v[154:157], v[224:227], v[124:127]
	v_mfma_f32_16x16x32_bf16 v[120:123], v[176:179], v[224:227], v[120:123]
	v_mfma_f32_16x16x32_bf16 v[108:111], v[154:157], v[232:235], v[108:111]
	v_mfma_f32_16x16x32_bf16 v[104:107], v[176:179], v[232:235], v[104:107]
	v_mfma_f32_16x16x32_bf16 v[92:95], v[154:157], v[240:243], v[92:95]
	v_mfma_f32_16x16x32_bf16 v[88:91], v[176:179], v[240:243], v[88:91]
	v_mfma_f32_16x16x32_bf16 v[76:79], v[154:157], v[248:251], v[76:79]
	v_mfma_f32_16x16x32_bf16 v[72:75], v[176:179], v[248:251], v[72:75]
	v_mfma_f32_16x16x32_bf16 v[116:119], v[204:207], v[220:223], v[116:119]
	v_mfma_f32_16x16x32_bf16 v[112:115], v[212:215], v[220:223], v[112:115]
	v_mfma_f32_16x16x32_bf16 v[100:103], v[204:207], v[228:231], v[100:103]
	v_mfma_f32_16x16x32_bf16 v[96:99], v[212:215], v[228:231], v[96:99]
	v_mfma_f32_16x16x32_bf16 v[84:87], v[204:207], v[236:239], v[84:87]
	v_mfma_f32_16x16x32_bf16 v[80:83], v[212:215], v[236:239], v[80:83]
	v_mfma_f32_16x16x32_bf16 v[68:71], v[204:207], v[244:247], v[68:71]
	v_mfma_f32_16x16x32_bf16 v[64:67], v[212:215], v[244:247], v[64:67]
	v_mfma_f32_16x16x32_bf16 v[116:119], v[208:211], v[224:227], v[116:119]
	v_mfma_f32_16x16x32_bf16 v[112:115], v[216:219], v[224:227], v[112:115]
	v_mfma_f32_16x16x32_bf16 v[100:103], v[208:211], v[232:235], v[100:103]
	v_mfma_f32_16x16x32_bf16 v[96:99], v[216:219], v[232:235], v[96:99]
	v_mfma_f32_16x16x32_bf16 v[84:87], v[208:211], v[240:243], v[84:87]
	v_mfma_f32_16x16x32_bf16 v[80:83], v[216:219], v[240:243], v[80:83]
	v_mfma_f32_16x16x32_bf16 v[68:71], v[208:211], v[248:251], v[68:71]
	v_mfma_f32_16x16x32_bf16 v[64:67], v[216:219], v[248:251], v[64:67]
	s_barrier
	s_add_i32 s4, s4, s33
	v_lshl_add_u64 v[142:143], s[34:35], 0, v[128:129]
	s_mov_b32 m0, s4
	ds_read_b128 v[220:223], v170 offset:16384
	ds_read_b128 v[224:227], v170 offset:17408
	ds_read_b128 v[228:231], v170 offset:18432
	ds_read_b128 v[232:235], v170 offset:19456
	ds_read_b128 v[236:239], v170 offset:20480
	ds_read_b128 v[240:243], v170 offset:21504
	ds_read_b128 v[244:247], v170 offset:22528
	ds_read_b128 v[248:251], v170 offset:23552
	global_load_lds_dwordx4 v[142:143], off
	s_add_i32 m0, s4, 0x2000
	s_add_u32 s60, s34, 0xb0000
	v_lshl_add_u64 v[158:159], s[34:35], 0, v[130:131]
	s_addc_u32 s61, s35, 0
	s_add_i32 s4, s5, s33
	global_load_lds_dwordx4 v[158:159], off
	v_lshl_add_u64 v[180:181], s[60:61], 0, v[128:129]
	s_mov_b32 m0, s4
	v_lshl_add_u64 v[202:203], s[64:65], 0, v[130:131]
	global_load_lds_dwordx4 v[180:181], off
	v_lshl_add_u64 v[180:181], s[60:61], 0, v[130:131]
	s_add_i32 m0, s4, 0x2000
	s_nop 0
	global_load_lds_dwordx4 v[180:181], off
	v_lshl_add_u64 v[180:181], s[64:65], 0, v[128:129]
	s_mov_b32 m0, s36
	s_nop 0
	global_load_lds_dwordx4 v[180:181], off
	s_mov_b32 m0, s70
	s_nop 0
	global_load_lds_dwordx4 v[202:203], off
	s_waitcnt vmcnt(8)
	s_waitcnt lgkmcnt(0)
	s_barrier
	v_mfma_f32_16x16x32_bf16 v[60:63], v[138:141], v[220:223], v[60:63]
	v_mfma_f32_16x16x32_bf16 v[56:59], v[172:175], v[220:223], v[56:59]
	v_mfma_f32_16x16x32_bf16 v[44:47], v[138:141], v[228:231], v[44:47]
	v_mfma_f32_16x16x32_bf16 v[40:43], v[172:175], v[228:231], v[40:43]
	v_mfma_f32_16x16x32_bf16 v[28:31], v[138:141], v[236:239], v[28:31]
	v_mfma_f32_16x16x32_bf16 v[24:27], v[172:175], v[236:239], v[24:27]
	v_mfma_f32_16x16x32_bf16 v[12:15], v[138:141], v[244:247], v[12:15]
	v_mfma_f32_16x16x32_bf16 v[8:11], v[172:175], v[244:247], v[8:11]
	v_mfma_f32_16x16x32_bf16 v[60:63], v[154:157], v[224:227], v[60:63]
	v_mfma_f32_16x16x32_bf16 v[56:59], v[176:179], v[224:227], v[56:59]
	v_mfma_f32_16x16x32_bf16 v[44:47], v[154:157], v[232:235], v[44:47]
	v_mfma_f32_16x16x32_bf16 v[40:43], v[176:179], v[232:235], v[40:43]
	v_mfma_f32_16x16x32_bf16 v[28:31], v[154:157], v[240:243], v[28:31]
	v_mfma_f32_16x16x32_bf16 v[24:27], v[176:179], v[240:243], v[24:27]
	v_mfma_f32_16x16x32_bf16 v[12:15], v[154:157], v[248:251], v[12:15]
	v_mfma_f32_16x16x32_bf16 v[8:11], v[176:179], v[248:251], v[8:11]
	v_mfma_f32_16x16x32_bf16 v[52:55], v[204:207], v[220:223], v[52:55]
	v_mfma_f32_16x16x32_bf16 v[48:51], v[212:215], v[220:223], v[48:51]
	v_mfma_f32_16x16x32_bf16 v[36:39], v[204:207], v[228:231], v[36:39]
	v_mfma_f32_16x16x32_bf16 v[32:35], v[212:215], v[228:231], v[32:35]
	v_mfma_f32_16x16x32_bf16 v[20:23], v[204:207], v[236:239], v[20:23]
	v_mfma_f32_16x16x32_bf16 v[16:19], v[212:215], v[236:239], v[16:19]
	v_mfma_f32_16x16x32_bf16 v[4:7], v[204:207], v[244:247], v[4:7]
	v_mfma_f32_16x16x32_bf16 v[0:3], v[212:215], v[244:247], v[0:3]
	v_mfma_f32_16x16x32_bf16 v[52:55], v[208:211], v[224:227], v[52:55]
	v_mfma_f32_16x16x32_bf16 v[48:51], v[216:219], v[224:227], v[48:51]
	v_mfma_f32_16x16x32_bf16 v[36:39], v[208:211], v[232:235], v[36:39]
	v_mfma_f32_16x16x32_bf16 v[32:35], v[216:219], v[232:235], v[32:35]
	v_mfma_f32_16x16x32_bf16 v[20:23], v[208:211], v[240:243], v[20:23]
	v_mfma_f32_16x16x32_bf16 v[16:19], v[216:219], v[240:243], v[16:19]
	v_mfma_f32_16x16x32_bf16 v[4:7], v[208:211], v[248:251], v[4:7]
	v_mfma_f32_16x16x32_bf16 v[0:3], v[216:219], v[248:251], v[0:3]
	s_barrier
	v_add_u32_e32 v144, 0x18000, v160
	ds_read_b128 v[138:141], v144
	ds_read_b128 v[154:157], v144 offset:1024
	ds_read_b128 v[172:175], v144 offset:2048
	ds_read_b128 v[176:179], v144 offset:3072
	v_add_u32_e32 v144, 0x1c000, v160
	ds_read_b128 v[204:207], v144
	ds_read_b128 v[208:211], v144 offset:1024
	ds_read_b128 v[212:215], v144 offset:2048
	ds_read_b128 v[216:219], v144 offset:3072
	ds_read_b128 v[220:223], v170 offset:32768
	ds_read_b128 v[224:227], v170 offset:33792
	ds_read_b128 v[228:231], v170 offset:34816
	ds_read_b128 v[232:235], v170 offset:35840
	ds_read_b128 v[236:239], v170 offset:36864
	ds_read_b128 v[240:243], v170 offset:37888
	ds_read_b128 v[244:247], v170 offset:38912
	ds_read_b128 v[248:251], v170 offset:39936
	s_add_i32 s4, 0, 0x18000
	s_add_i32 s5, 0, 0x1c000
	s_add_u32 s60, s64, 0xb0000
	s_addc_u32 s61, s65, 0
	s_mov_b32 m0, s71
	v_lshl_add_u64 v[252:253], s[60:61], 0, v[128:129]
	global_load_lds_dwordx4 v[252:253], off
	v_lshl_add_u64 v[252:253], s[60:61], 0, v[130:131]
	s_mov_b32 m0, s72
	s_nop 0
	global_load_lds_dwordx4 v[252:253], off
	s_waitcnt vmcnt(8)
	s_waitcnt lgkmcnt(0)
	s_barrier
	v_mfma_f32_16x16x32_bf16 v[124:127], v[138:141], v[220:223], v[124:127]
	v_mfma_f32_16x16x32_bf16 v[120:123], v[172:175], v[220:223], v[120:123]
	v_mfma_f32_16x16x32_bf16 v[108:111], v[138:141], v[228:231], v[108:111]
	v_mfma_f32_16x16x32_bf16 v[104:107], v[172:175], v[228:231], v[104:107]
	v_mfma_f32_16x16x32_bf16 v[92:95], v[138:141], v[236:239], v[92:95]
	v_mfma_f32_16x16x32_bf16 v[88:91], v[172:175], v[236:239], v[88:91]
	v_mfma_f32_16x16x32_bf16 v[76:79], v[138:141], v[244:247], v[76:79]
	v_mfma_f32_16x16x32_bf16 v[72:75], v[172:175], v[244:247], v[72:75]
	v_mfma_f32_16x16x32_bf16 v[124:127], v[154:157], v[224:227], v[124:127]
	v_mfma_f32_16x16x32_bf16 v[120:123], v[176:179], v[224:227], v[120:123]
	v_mfma_f32_16x16x32_bf16 v[108:111], v[154:157], v[232:235], v[108:111]
	v_mfma_f32_16x16x32_bf16 v[104:107], v[176:179], v[232:235], v[104:107]
	v_mfma_f32_16x16x32_bf16 v[92:95], v[154:157], v[240:243], v[92:95]
	v_mfma_f32_16x16x32_bf16 v[88:91], v[176:179], v[240:243], v[88:91]
	v_mfma_f32_16x16x32_bf16 v[76:79], v[154:157], v[248:251], v[76:79]
	v_mfma_f32_16x16x32_bf16 v[72:75], v[176:179], v[248:251], v[72:75]
	v_mfma_f32_16x16x32_bf16 v[116:119], v[204:207], v[220:223], v[116:119]
	v_mfma_f32_16x16x32_bf16 v[112:115], v[212:215], v[220:223], v[112:115]
	v_mfma_f32_16x16x32_bf16 v[100:103], v[204:207], v[228:231], v[100:103]
	v_mfma_f32_16x16x32_bf16 v[96:99], v[212:215], v[228:231], v[96:99]
	v_mfma_f32_16x16x32_bf16 v[84:87], v[204:207], v[236:239], v[84:87]
	v_mfma_f32_16x16x32_bf16 v[80:83], v[212:215], v[236:239], v[80:83]
	v_mfma_f32_16x16x32_bf16 v[68:71], v[204:207], v[244:247], v[68:71]
	v_mfma_f32_16x16x32_bf16 v[64:67], v[212:215], v[244:247], v[64:67]
	v_mfma_f32_16x16x32_bf16 v[116:119], v[208:211], v[224:227], v[116:119]
	v_mfma_f32_16x16x32_bf16 v[112:115], v[216:219], v[224:227], v[112:115]
	v_mfma_f32_16x16x32_bf16 v[100:103], v[208:211], v[232:235], v[100:103]
	v_mfma_f32_16x16x32_bf16 v[96:99], v[216:219], v[232:235], v[96:99]
	v_mfma_f32_16x16x32_bf16 v[84:87], v[208:211], v[240:243], v[84:87]
	v_mfma_f32_16x16x32_bf16 v[80:83], v[216:219], v[240:243], v[80:83]
	v_mfma_f32_16x16x32_bf16 v[68:71], v[208:211], v[248:251], v[68:71]
	v_mfma_f32_16x16x32_bf16 v[64:67], v[216:219], v[248:251], v[64:67]
	s_barrier
	s_add_i32 s4, s4, s33
	v_lshl_add_u64 v[142:143], v[142:143], 0, s[26:27]
	s_mov_b32 m0, s4
	ds_read_b128 v[220:223], v170 offset:49152
	ds_read_b128 v[224:227], v170 offset:50176
	ds_read_b128 v[228:231], v170 offset:51200
	ds_read_b128 v[232:235], v170 offset:52224
	ds_read_b128 v[236:239], v170 offset:53248
	ds_read_b128 v[240:243], v170 offset:54272
	ds_read_b128 v[244:247], v170 offset:55296
	ds_read_b128 v[248:251], v170 offset:56320
	global_load_lds_dwordx4 v[142:143], off
	s_add_i32 m0, s4, 0x2000
	s_add_u32 s34, s34, 0xb0080
	v_lshl_add_u64 v[142:143], v[158:159], 0, s[26:27]
	s_addc_u32 s35, s35, 0
	s_add_i32 s4, s5, s33
	global_load_lds_dwordx4 v[142:143], off
	v_lshl_add_u64 v[142:143], s[34:35], 0, v[128:129]
	s_mov_b32 m0, s4
	s_nop 0
	global_load_lds_dwordx4 v[142:143], off
	v_lshl_add_u64 v[142:143], s[34:35], 0, v[130:131]
	s_add_i32 m0, s4, 0x2000
	s_nop 0
	global_load_lds_dwordx4 v[142:143], off
	v_lshl_add_u64 v[142:143], v[180:181], 0, s[26:27]
	s_mov_b32 m0, s73
	s_nop 0
	global_load_lds_dwordx4 v[142:143], off
	v_lshl_add_u64 v[142:143], v[202:203], 0, s[26:27]
	s_mov_b32 m0, s74
	s_nop 0
	global_load_lds_dwordx4 v[142:143], off
	s_add_i32 s29, s29, 2
	s_add_u32 s3, s3, 0x100
	s_addc_u32 s28, s28, 0
	s_cmp_gt_u32 s29, 41
	s_mov_b64 s[60:61], s[62:63]
	s_waitcnt vmcnt(8)
	s_waitcnt lgkmcnt(0)
	s_barrier
	v_mfma_f32_16x16x32_bf16 v[60:63], v[138:141], v[220:223], v[60:63]
	v_mfma_f32_16x16x32_bf16 v[56:59], v[172:175], v[220:223], v[56:59]
	v_mfma_f32_16x16x32_bf16 v[44:47], v[138:141], v[228:231], v[44:47]
	v_mfma_f32_16x16x32_bf16 v[40:43], v[172:175], v[228:231], v[40:43]
	v_mfma_f32_16x16x32_bf16 v[28:31], v[138:141], v[236:239], v[28:31]
	v_mfma_f32_16x16x32_bf16 v[24:27], v[172:175], v[236:239], v[24:27]
	v_mfma_f32_16x16x32_bf16 v[12:15], v[138:141], v[244:247], v[12:15]
	v_mfma_f32_16x16x32_bf16 v[8:11], v[172:175], v[244:247], v[8:11]
	v_mfma_f32_16x16x32_bf16 v[60:63], v[154:157], v[224:227], v[60:63]
	v_mfma_f32_16x16x32_bf16 v[56:59], v[176:179], v[224:227], v[56:59]
	v_mfma_f32_16x16x32_bf16 v[44:47], v[154:157], v[232:235], v[44:47]
	v_mfma_f32_16x16x32_bf16 v[40:43], v[176:179], v[232:235], v[40:43]
	v_mfma_f32_16x16x32_bf16 v[28:31], v[154:157], v[240:243], v[28:31]
	v_mfma_f32_16x16x32_bf16 v[24:27], v[176:179], v[240:243], v[24:27]
	v_mfma_f32_16x16x32_bf16 v[12:15], v[154:157], v[248:251], v[12:15]
	v_mfma_f32_16x16x32_bf16 v[8:11], v[176:179], v[248:251], v[8:11]
	v_mfma_f32_16x16x32_bf16 v[52:55], v[204:207], v[220:223], v[52:55]
	v_mfma_f32_16x16x32_bf16 v[48:51], v[212:215], v[220:223], v[48:51]
	v_mfma_f32_16x16x32_bf16 v[36:39], v[204:207], v[228:231], v[36:39]
	v_mfma_f32_16x16x32_bf16 v[32:35], v[212:215], v[228:231], v[32:35]
	v_mfma_f32_16x16x32_bf16 v[20:23], v[204:207], v[236:239], v[20:23]
	v_mfma_f32_16x16x32_bf16 v[16:19], v[212:215], v[236:239], v[16:19]
	v_mfma_f32_16x16x32_bf16 v[4:7], v[204:207], v[244:247], v[4:7]
	v_mfma_f32_16x16x32_bf16 v[0:3], v[212:215], v[244:247], v[0:3]
	v_mfma_f32_16x16x32_bf16 v[52:55], v[208:211], v[224:227], v[52:55]
	v_mfma_f32_16x16x32_bf16 v[48:51], v[216:219], v[224:227], v[48:51]
	v_mfma_f32_16x16x32_bf16 v[36:39], v[208:211], v[232:235], v[36:39]
	v_mfma_f32_16x16x32_bf16 v[32:35], v[216:219], v[232:235], v[32:35]
	v_mfma_f32_16x16x32_bf16 v[20:23], v[208:211], v[240:243], v[20:23]
	v_mfma_f32_16x16x32_bf16 v[16:19], v[216:219], v[240:243], v[16:19]
	v_mfma_f32_16x16x32_bf16 v[4:7], v[208:211], v[248:251], v[4:7]
	v_mfma_f32_16x16x32_bf16 v[0:3], v[216:219], v[248:251], v[0:3]
	s_barrier
	s_cbranch_scc0 .LBB0_406
	s_setprio 0
	s_and_b64 vcc, exec, s[54:55]
	s_cbranch_vccz .LBB0_409
	s_barrier

.Lkprio_456:
.LBB0_456:
	v_add_u32_e32 v140, 0x10000, v166
	v_add_u32_e32 v144, 0x14000, v166
	ds_read_b128 v[128:131], v140
	ds_read_b128 v[132:135], v140 offset:1024
	ds_read_b128 v[136:139], v140 offset:2048
	ds_read_b128 v[140:143], v140 offset:3072
	ds_read_b128 v[178:181], v144
	ds_read_b128 v[204:207], v144 offset:1024
	ds_read_b128 v[208:211], v144 offset:2048
	ds_read_b128 v[212:215], v144 offset:3072
	ds_read_b128 v[216:219], v176
	ds_read_b128 v[220:223], v176 offset:1024
	ds_read_b128 v[224:227], v176 offset:2048
	ds_read_b128 v[228:231], v176 offset:3072
	ds_read_b128 v[232:235], v176 offset:4096
	ds_read_b128 v[236:239], v176 offset:5120
	ds_read_b128 v[240:243], v176 offset:6144
	ds_read_b128 v[244:247], v176 offset:7168
	s_add_u32 s60, s58, 0x100
	s_addc_u32 s61, s59, 0
	s_add_i32 s4, 0, 0x10000
	s_cmp_eq_u32 s51, 40
	s_cselect_b32 s63, s45, s61
	s_cselect_b32 s62, s44, s60
	s_cselect_b32 s35, s47, s29
	s_cselect_b32 s34, s46, s28
	s_add_i32 s5, 0, 0x14000
	v_lshl_add_u64 v[164:165], s[58:59], 0, v[160:161]
	s_add_i32 m0, s36, 0xc000
	s_nop 0
	global_load_lds_dwordx4 v[164:165], off
	v_lshl_add_u64 v[164:165], s[58:59], 0, v[162:163]
	s_add_i32 m0, s36, 0xe000
	s_nop 0
	global_load_lds_dwordx4 v[164:165], off
	s_waitcnt vmcnt(8)
	s_waitcnt lgkmcnt(0)
	s_barrier
	v_mfma_f32_16x16x32_bf16 v[124:127], v[128:131], v[216:219], v[124:127]
	v_mfma_f32_16x16x32_bf16 v[120:123], v[136:139], v[216:219], v[120:123]
	v_mfma_f32_16x16x32_bf16 v[108:111], v[128:131], v[224:227], v[108:111]
	v_mfma_f32_16x16x32_bf16 v[104:107], v[136:139], v[224:227], v[104:107]
	v_mfma_f32_16x16x32_bf16 v[92:95], v[128:131], v[232:235], v[92:95]
	v_mfma_f32_16x16x32_bf16 v[88:91], v[136:139], v[232:235], v[88:91]
	v_mfma_f32_16x16x32_bf16 v[76:79], v[128:131], v[240:243], v[76:79]
	v_mfma_f32_16x16x32_bf16 v[72:75], v[136:139], v[240:243], v[72:75]
	v_mfma_f32_16x16x32_bf16 v[124:127], v[132:135], v[220:223], v[124:127]
	v_mfma_f32_16x16x32_bf16 v[120:123], v[140:143], v[220:223], v[120:123]
	v_mfma_f32_16x16x32_bf16 v[108:111], v[132:135], v[228:231], v[108:111]
	v_mfma_f32_16x16x32_bf16 v[104:107], v[140:143], v[228:231], v[104:107]
	v_mfma_f32_16x16x32_bf16 v[92:95], v[132:135], v[236:239], v[92:95]
	v_mfma_f32_16x16x32_bf16 v[88:91], v[140:143], v[236:239], v[88:91]
	v_mfma_f32_16x16x32_bf16 v[76:79], v[132:135], v[244:247], v[76:79]
	v_mfma_f32_16x16x32_bf16 v[72:75], v[140:143], v[244:247], v[72:75]
	v_mfma_f32_16x16x32_bf16 v[116:119], v[178:181], v[216:219], v[116:119]
	v_mfma_f32_16x16x32_bf16 v[112:115], v[208:211], v[216:219], v[112:115]
	v_mfma_f32_16x16x32_bf16 v[100:103], v[178:181], v[224:227], v[100:103]
	v_mfma_f32_16x16x32_bf16 v[96:99], v[208:211], v[224:227], v[96:99]
	v_mfma_f32_16x16x32_bf16 v[84:87], v[178:181], v[232:235], v[84:87]
	v_mfma_f32_16x16x32_bf16 v[80:83], v[208:211], v[232:235], v[80:83]
	v_mfma_f32_16x16x32_bf16 v[68:71], v[178:181], v[240:243], v[68:71]
	v_mfma_f32_16x16x32_bf16 v[64:67], v[208:211], v[240:243], v[64:67]
	v_mfma_f32_16x16x32_bf16 v[116:119], v[204:207], v[220:223], v[116:119]
	v_mfma_f32_16x16x32_bf16 v[112:115], v[212:215], v[220:223], v[112:115]
	v_mfma_f32_16x16x32_bf16 v[100:103], v[204:207], v[228:231], v[100:103]
	v_mfma_f32_16x16x32_bf16 v[96:99], v[212:215], v[228:231], v[96:99]
	v_mfma_f32_16x16x32_bf16 v[84:87], v[204:207], v[236:239], v[84:87]
	v_mfma_f32_16x16x32_bf16 v[80:83], v[212:215], v[236:239], v[80:83]
	v_mfma_f32_16x16x32_bf16 v[68:71], v[204:207], v[244:247], v[68:71]
	v_mfma_f32_16x16x32_bf16 v[64:67], v[212:215], v[244:247], v[64:67]
	s_barrier
	s_add_i32 s4, s4, s33
	v_lshl_add_u64 v[164:165], s[34:35], 0, v[154:155]
	s_mov_b32 m0, s4
	ds_read_b128 v[216:219], v176 offset:16384
	ds_read_b128 v[220:223], v176 offset:17408
	ds_read_b128 v[224:227], v176 offset:18432
	ds_read_b128 v[228:231], v176 offset:19456
	ds_read_b128 v[232:235], v176 offset:20480
	ds_read_b128 v[236:239], v176 offset:21504
	ds_read_b128 v[240:243], v176 offset:22528
	ds_read_b128 v[244:247], v176 offset:23552
	global_load_lds_dwordx4 v[164:165], off
	s_add_i32 m0, s4, 0x2000
	s_add_u32 s58, s34, 0xb0000
	v_lshl_add_u64 v[248:249], s[34:35], 0, v[156:157]
	s_addc_u32 s59, s35, 0
	s_add_i32 s4, s5, s33
	global_load_lds_dwordx4 v[248:249], off
	v_lshl_add_u64 v[250:251], s[58:59], 0, v[154:155]
	s_mov_b32 m0, s4
	v_lshl_add_u64 v[252:253], s[62:63], 0, v[156:157]
	global_load_lds_dwordx4 v[250:251], off
	v_lshl_add_u64 v[250:251], s[58:59], 0, v[156:157]
	s_add_i32 m0, s4, 0x2000
	s_nop 0
	global_load_lds_dwordx4 v[250:251], off
	v_lshl_add_u64 v[250:251], s[62:63], 0, v[154:155]
	s_mov_b32 m0, s36
	s_nop 0
	global_load_lds_dwordx4 v[250:251], off
	s_mov_b32 m0, s64
	s_nop 0
	global_load_lds_dwordx4 v[252:253], off
	s_waitcnt vmcnt(8)
	s_waitcnt lgkmcnt(0)
	s_barrier
	v_mfma_f32_16x16x32_bf16 v[60:63], v[128:131], v[216:219], v[60:63]
	v_mfma_f32_16x16x32_bf16 v[56:59], v[136:139], v[216:219], v[56:59]
	v_mfma_f32_16x16x32_bf16 v[44:47], v[128:131], v[224:227], v[44:47]
	v_mfma_f32_16x16x32_bf16 v[40:43], v[136:139], v[224:227], v[40:43]
	v_mfma_f32_16x16x32_bf16 v[28:31], v[128:131], v[232:235], v[28:31]
	v_mfma_f32_16x16x32_bf16 v[24:27], v[136:139], v[232:235], v[24:27]
	v_mfma_f32_16x16x32_bf16 v[12:15], v[128:131], v[240:243], v[12:15]
	v_mfma_f32_16x16x32_bf16 v[8:11], v[136:139], v[240:243], v[8:11]
	v_mfma_f32_16x16x32_bf16 v[60:63], v[132:135], v[220:223], v[60:63]
	v_mfma_f32_16x16x32_bf16 v[56:59], v[140:143], v[220:223], v[56:59]
	v_mfma_f32_16x16x32_bf16 v[44:47], v[132:135], v[228:231], v[44:47]
	v_mfma_f32_16x16x32_bf16 v[40:43], v[140:143], v[228:231], v[40:43]
	v_mfma_f32_16x16x32_bf16 v[28:31], v[132:135], v[236:239], v[28:31]
	v_mfma_f32_16x16x32_bf16 v[24:27], v[140:143], v[236:239], v[24:27]
	v_mfma_f32_16x16x32_bf16 v[12:15], v[132:135], v[244:247], v[12:15]
	v_mfma_f32_16x16x32_bf16 v[8:11], v[140:143], v[244:247], v[8:11]
	v_mfma_f32_16x16x32_bf16 v[52:55], v[178:181], v[216:219], v[52:55]
	v_mfma_f32_16x16x32_bf16 v[48:51], v[208:211], v[216:219], v[48:51]
	v_mfma_f32_16x16x32_bf16 v[36:39], v[178:181], v[224:227], v[36:39]
	v_mfma_f32_16x16x32_bf16 v[32:35], v[208:211], v[224:227], v[32:35]
	v_mfma_f32_16x16x32_bf16 v[20:23], v[178:181], v[232:235], v[20:23]
	v_mfma_f32_16x16x32_bf16 v[16:19], v[208:211], v[232:235], v[16:19]
	v_mfma_f32_16x16x32_bf16 v[4:7], v[178:181], v[240:243], v[4:7]
	v_mfma_f32_16x16x32_bf16 v[0:3], v[208:211], v[240:243], v[0:3]
	v_mfma_f32_16x16x32_bf16 v[52:55], v[204:207], v[220:223], v[52:55]
	v_mfma_f32_16x16x32_bf16 v[48:51], v[212:215], v[220:223], v[48:51]
	v_mfma_f32_16x16x32_bf16 v[36:39], v[204:207], v[228:231], v[36:39]
	v_mfma_f32_16x16x32_bf16 v[32:35], v[212:215], v[228:231], v[32:35]
	v_mfma_f32_16x16x32_bf16 v[20:23], v[204:207], v[236:239], v[20:23]
	v_mfma_f32_16x16x32_bf16 v[16:19], v[212:215], v[236:239], v[16:19]
	v_mfma_f32_16x16x32_bf16 v[4:7], v[204:207], v[244:247], v[4:7]
	v_mfma_f32_16x16x32_bf16 v[0:3], v[212:215], v[244:247], v[0:3]
	s_barrier
	v_add_u32_e32 v140, 0x18000, v166
	v_add_u32_e32 v144, 0x1c000, v166
	ds_read_b128 v[128:131], v140
	ds_read_b128 v[132:135], v140 offset:1024
	ds_read_b128 v[136:139], v140 offset:2048
	ds_read_b128 v[140:143], v140 offset:3072
	ds_read_b128 v[178:181], v144
	ds_read_b128 v[204:207], v144 offset:1024
	ds_read_b128 v[208:211], v144 offset:2048
	ds_read_b128 v[212:215], v144 offset:3072
	ds_read_b128 v[216:219], v176 offset:32768
	ds_read_b128 v[220:223], v176 offset:33792
	ds_read_b128 v[224:227], v176 offset:34816
	ds_read_b128 v[228:231], v176 offset:35840
	ds_read_b128 v[232:235], v176 offset:36864
	ds_read_b128 v[236:239], v176 offset:37888
	ds_read_b128 v[240:243], v176 offset:38912
	ds_read_b128 v[244:247], v176 offset:39936
	s_add_i32 s4, 0, 0x18000
	s_add_i32 s5, 0, 0x1c000
	s_add_u32 s58, s62, 0xb0000
	s_addc_u32 s59, s63, 0
	s_mov_b32 m0, s65
	v_lshl_add_u64 v[202:203], s[58:59], 0, v[154:155]
	global_load_lds_dwordx4 v[202:203], off
	v_lshl_add_u64 v[202:203], s[58:59], 0, v[156:157]
	s_mov_b32 m0, s70
	s_nop 0
	global_load_lds_dwordx4 v[202:203], off
	s_waitcnt vmcnt(8)
	s_waitcnt lgkmcnt(0)
	s_barrier
	v_mfma_f32_16x16x32_bf16 v[124:127], v[128:131], v[216:219], v[124:127]
	v_mfma_f32_16x16x32_bf16 v[120:123], v[136:139], v[216:219], v[120:123]
	v_mfma_f32_16x16x32_bf16 v[108:111], v[128:131], v[224:227], v[108:111]
	v_mfma_f32_16x16x32_bf16 v[104:107], v[136:139], v[224:227], v[104:107]
	v_mfma_f32_16x16x32_bf16 v[92:95], v[128:131], v[232:235], v[92:95]
	v_mfma_f32_16x16x32_bf16 v[88:91], v[136:139], v[232:235], v[88:91]
	v_mfma_f32_16x16x32_bf16 v[76:79], v[128:131], v[240:243], v[76:79]
	v_mfma_f32_16x16x32_bf16 v[72:75], v[136:139], v[240:243], v[72:75]
	v_mfma_f32_16x16x32_bf16 v[124:127], v[132:135], v[220:223], v[124:127]
	v_mfma_f32_16x16x32_bf16 v[120:123], v[140:143], v[220:223], v[120:123]
	v_mfma_f32_16x16x32_bf16 v[108:111], v[132:135], v[228:231], v[108:111]
	v_mfma_f32_16x16x32_bf16 v[104:107], v[140:143], v[228:231], v[104:107]
	v_mfma_f32_16x16x32_bf16 v[92:95], v[132:135], v[236:239], v[92:95]
	v_mfma_f32_16x16x32_bf16 v[88:91], v[140:143], v[236:239], v[88:91]
	v_mfma_f32_16x16x32_bf16 v[76:79], v[132:135], v[244:247], v[76:79]
	v_mfma_f32_16x16x32_bf16 v[72:75], v[140:143], v[244:247], v[72:75]
	v_mfma_f32_16x16x32_bf16 v[116:119], v[178:181], v[216:219], v[116:119]
	v_mfma_f32_16x16x32_bf16 v[112:115], v[208:211], v[216:219], v[112:115]
	v_mfma_f32_16x16x32_bf16 v[100:103], v[178:181], v[224:227], v[100:103]
	v_mfma_f32_16x16x32_bf16 v[96:99], v[208:211], v[224:227], v[96:99]
	v_mfma_f32_16x16x32_bf16 v[84:87], v[178:181], v[232:235], v[84:87]
	v_mfma_f32_16x16x32_bf16 v[80:83], v[208:211], v[232:235], v[80:83]
	v_mfma_f32_16x16x32_bf16 v[68:71], v[178:181], v[240:243], v[68:71]
	v_mfma_f32_16x16x32_bf16 v[64:67], v[208:211], v[240:243], v[64:67]
	v_mfma_f32_16x16x32_bf16 v[116:119], v[204:207], v[220:223], v[116:119]
	v_mfma_f32_16x16x32_bf16 v[112:115], v[212:215], v[220:223], v[112:115]
	v_mfma_f32_16x16x32_bf16 v[100:103], v[204:207], v[228:231], v[100:103]
	v_mfma_f32_16x16x32_bf16 v[96:99], v[212:215], v[228:231], v[96:99]
	v_mfma_f32_16x16x32_bf16 v[84:87], v[204:207], v[236:239], v[84:87]
	v_mfma_f32_16x16x32_bf16 v[80:83], v[212:215], v[236:239], v[80:83]
	v_mfma_f32_16x16x32_bf16 v[68:71], v[204:207], v[244:247], v[68:71]
	v_mfma_f32_16x16x32_bf16 v[64:67], v[212:215], v[244:247], v[64:67]
	s_barrier
	s_add_i32 s4, s4, s33
	v_lshl_add_u64 v[164:165], v[164:165], 0, s[26:27]
	s_mov_b32 m0, s4
	ds_read_b128 v[216:219], v176 offset:49152
	ds_read_b128 v[220:223], v176 offset:50176
	ds_read_b128 v[224:227], v176 offset:51200
	ds_read_b128 v[228:231], v176 offset:52224
	ds_read_b128 v[232:235], v176 offset:53248
	ds_read_b128 v[236:239], v176 offset:54272
	ds_read_b128 v[240:243], v176 offset:55296
	ds_read_b128 v[244:247], v176 offset:56320
	global_load_lds_dwordx4 v[164:165], off
	s_add_i32 m0, s4, 0x2000
	s_add_u32 s34, s34, 0xb0080
	v_lshl_add_u64 v[164:165], v[248:249], 0, s[26:27]
	s_addc_u32 s35, s35, 0
	s_add_i32 s4, s5, s33
	global_load_lds_dwordx4 v[164:165], off
	v_lshl_add_u64 v[164:165], s[34:35], 0, v[154:155]
	s_mov_b32 m0, s4
	s_nop 0
	global_load_lds_dwordx4 v[164:165], off
	v_lshl_add_u64 v[164:165], s[34:35], 0, v[156:157]
	s_add_i32 m0, s4, 0x2000
	s_nop 0
	global_load_lds_dwordx4 v[164:165], off
	v_lshl_add_u64 v[164:165], v[250:251], 0, s[26:27]
	s_mov_b32 m0, s71
	s_nop 0
	global_load_lds_dwordx4 v[164:165], off
	v_lshl_add_u64 v[164:165], v[252:253], 0, s[26:27]
	s_mov_b32 m0, s72
	s_nop 0
	global_load_lds_dwordx4 v[164:165], off
	s_add_i32 s51, s51, 2
	s_add_u32 s28, s28, 0x100
	s_addc_u32 s29, s29, 0
	s_cmp_gt_u32 s51, 41
	s_mov_b64 s[58:59], s[60:61]
	s_waitcnt vmcnt(8)
	s_waitcnt lgkmcnt(0)
	s_barrier
	v_mfma_f32_16x16x32_bf16 v[60:63], v[128:131], v[216:219], v[60:63]
	v_mfma_f32_16x16x32_bf16 v[56:59], v[136:139], v[216:219], v[56:59]
	v_mfma_f32_16x16x32_bf16 v[44:47], v[128:131], v[224:227], v[44:47]
	v_mfma_f32_16x16x32_bf16 v[40:43], v[136:139], v[224:227], v[40:43]
	v_mfma_f32_16x16x32_bf16 v[28:31], v[128:131], v[232:235], v[28:31]
	v_mfma_f32_16x16x32_bf16 v[24:27], v[136:139], v[232:235], v[24:27]
	v_mfma_f32_16x16x32_bf16 v[12:15], v[128:131], v[240:243], v[12:15]
	v_mfma_f32_16x16x32_bf16 v[8:11], v[136:139], v[240:243], v[8:11]
	v_mfma_f32_16x16x32_bf16 v[60:63], v[132:135], v[220:223], v[60:63]
	v_mfma_f32_16x16x32_bf16 v[56:59], v[140:143], v[220:223], v[56:59]
	v_mfma_f32_16x16x32_bf16 v[44:47], v[132:135], v[228:231], v[44:47]
	v_mfma_f32_16x16x32_bf16 v[40:43], v[140:143], v[228:231], v[40:43]
	v_mfma_f32_16x16x32_bf16 v[28:31], v[132:135], v[236:239], v[28:31]
	v_mfma_f32_16x16x32_bf16 v[24:27], v[140:143], v[236:239], v[24:27]
	v_mfma_f32_16x16x32_bf16 v[12:15], v[132:135], v[244:247], v[12:15]
	v_mfma_f32_16x16x32_bf16 v[8:11], v[140:143], v[244:247], v[8:11]
	v_mfma_f32_16x16x32_bf16 v[52:55], v[178:181], v[216:219], v[52:55]
	v_mfma_f32_16x16x32_bf16 v[48:51], v[208:211], v[216:219], v[48:51]
	v_mfma_f32_16x16x32_bf16 v[36:39], v[178:181], v[224:227], v[36:39]
	v_mfma_f32_16x16x32_bf16 v[32:35], v[208:211], v[224:227], v[32:35]
	v_mfma_f32_16x16x32_bf16 v[20:23], v[178:181], v[232:235], v[20:23]
	v_mfma_f32_16x16x32_bf16 v[16:19], v[208:211], v[232:235], v[16:19]
	v_mfma_f32_16x16x32_bf16 v[4:7], v[178:181], v[240:243], v[4:7]
	v_mfma_f32_16x16x32_bf16 v[0:3], v[208:211], v[240:243], v[0:3]
	v_mfma_f32_16x16x32_bf16 v[52:55], v[204:207], v[220:223], v[52:55]
	v_mfma_f32_16x16x32_bf16 v[48:51], v[212:215], v[220:223], v[48:51]
	v_mfma_f32_16x16x32_bf16 v[36:39], v[204:207], v[228:231], v[36:39]
	v_mfma_f32_16x16x32_bf16 v[32:35], v[212:215], v[228:231], v[32:35]
	v_mfma_f32_16x16x32_bf16 v[20:23], v[204:207], v[236:239], v[20:23]
	v_mfma_f32_16x16x32_bf16 v[16:19], v[212:215], v[236:239], v[16:19]
	v_mfma_f32_16x16x32_bf16 v[4:7], v[204:207], v[244:247], v[4:7]
	v_mfma_f32_16x16x32_bf16 v[0:3], v[212:215], v[244:247], v[0:3]
	s_barrier
	s_cbranch_scc0 .LBB0_456
	s_setprio 0
	s_and_b64 vcc, exec, s[54:55]
	s_cbranch_vccz .LBB0_459
	s_barrier

.Lkprio_605:
.LBB0_605:
	v_add_u32_e32 v140, 0x10000, v203
	v_add_u32_e32 v144, 0x14000, v203
	ds_read_b128 v[128:131], v140
	ds_read_b128 v[132:135], v140 offset:1024
	ds_read_b128 v[136:139], v140 offset:2048
	ds_read_b128 v[140:143], v140 offset:3072
	ds_read_b128 v[168:171], v144
	ds_read_b128 v[172:175], v144 offset:1024
	ds_read_b128 v[176:179], v144 offset:2048
	ds_read_b128 v[206:209], v144 offset:3072
	ds_read_b128 v[210:213], v205
	ds_read_b128 v[214:217], v205 offset:1024
	ds_read_b128 v[218:221], v205 offset:2048
	ds_read_b128 v[222:225], v205 offset:3072
	ds_read_b128 v[226:229], v205 offset:4096
	ds_read_b128 v[230:233], v205 offset:5120
	ds_read_b128 v[234:237], v205 offset:6144
	ds_read_b128 v[238:241], v205 offset:7168
	s_add_u32 s4, s0, 0xfffc0080
	s_addc_u32 s5, s1, -1
	s_add_i32 s89, 0, 0x10000
	s_cmp_eq_u32 s88, 12
	s_cselect_b32 s43, s3, s5
	s_cselect_b32 s42, s36, s4
	s_cselect_b32 s35, s39, s84
	s_cselect_b32 s34, s71, s79
	s_add_i32 s4, 0, 0x14000
	v_lshl_add_u64 v[180:181], s[0:1], 0, v[164:165]
	s_add_i32 m0, s69, 0xc000
	s_nop 0
	global_load_lds_dwordx4 v[180:181], off
	v_lshl_add_u64 v[180:181], s[0:1], 0, v[166:167]
	s_add_i32 m0, s69, 0xe000
	s_nop 0
	global_load_lds_dwordx4 v[180:181], off
	s_waitcnt vmcnt(8)
	s_waitcnt lgkmcnt(0)
	s_barrier
	v_mfma_f32_16x16x32_bf16 v[124:127], v[128:131], v[210:213], v[124:127]
	v_mfma_f32_16x16x32_bf16 v[120:123], v[136:139], v[210:213], v[120:123]
	v_mfma_f32_16x16x32_bf16 v[112:115], v[128:131], v[218:221], v[112:115]
	v_mfma_f32_16x16x32_bf16 v[108:111], v[136:139], v[218:221], v[108:111]
	v_mfma_f32_16x16x32_bf16 v[100:103], v[128:131], v[226:229], v[100:103]
	v_mfma_f32_16x16x32_bf16 v[92:95], v[136:139], v[226:229], v[92:95]
	v_mfma_f32_16x16x32_bf16 v[84:87], v[128:131], v[234:237], v[84:87]
	v_mfma_f32_16x16x32_bf16 v[76:79], v[136:139], v[234:237], v[76:79]
	v_mfma_f32_16x16x32_bf16 v[124:127], v[132:135], v[214:217], v[124:127]
	v_mfma_f32_16x16x32_bf16 v[120:123], v[140:143], v[214:217], v[120:123]
	v_mfma_f32_16x16x32_bf16 v[112:115], v[132:135], v[222:225], v[112:115]
	v_mfma_f32_16x16x32_bf16 v[108:111], v[140:143], v[222:225], v[108:111]
	v_mfma_f32_16x16x32_bf16 v[100:103], v[132:135], v[230:233], v[100:103]
	v_mfma_f32_16x16x32_bf16 v[92:95], v[140:143], v[230:233], v[92:95]
	v_mfma_f32_16x16x32_bf16 v[84:87], v[132:135], v[238:241], v[84:87]
	v_mfma_f32_16x16x32_bf16 v[76:79], v[140:143], v[238:241], v[76:79]
	v_mfma_f32_16x16x32_bf16 v[116:119], v[168:171], v[210:213], v[116:119]
	v_mfma_f32_16x16x32_bf16 v[104:107], v[176:179], v[210:213], v[104:107]
	v_mfma_f32_16x16x32_bf16 v[96:99], v[168:171], v[218:221], v[96:99]
	v_mfma_f32_16x16x32_bf16 v[88:91], v[176:179], v[218:221], v[88:91]
	v_mfma_f32_16x16x32_bf16 v[80:83], v[168:171], v[226:229], v[80:83]
	v_mfma_f32_16x16x32_bf16 v[72:75], v[176:179], v[226:229], v[72:75]
	v_mfma_f32_16x16x32_bf16 v[68:71], v[168:171], v[234:237], v[68:71]
	v_mfma_f32_16x16x32_bf16 v[64:67], v[176:179], v[234:237], v[64:67]
	v_mfma_f32_16x16x32_bf16 v[116:119], v[172:175], v[214:217], v[116:119]
	v_mfma_f32_16x16x32_bf16 v[104:107], v[206:209], v[214:217], v[104:107]
	v_mfma_f32_16x16x32_bf16 v[96:99], v[172:175], v[222:225], v[96:99]
	v_mfma_f32_16x16x32_bf16 v[88:91], v[206:209], v[222:225], v[88:91]
	v_mfma_f32_16x16x32_bf16 v[80:83], v[172:175], v[230:233], v[80:83]
	v_mfma_f32_16x16x32_bf16 v[72:75], v[206:209], v[230:233], v[72:75]
	v_mfma_f32_16x16x32_bf16 v[68:71], v[172:175], v[238:241], v[68:71]
	v_mfma_f32_16x16x32_bf16 v[64:67], v[206:209], v[238:241], v[64:67]
	s_barrier
	s_add_i32 s5, s89, s28
	v_lshl_add_u64 v[180:181], s[34:35], 0, v[156:157]
	s_mov_b32 m0, s5
	ds_read_b128 v[210:213], v205 offset:16384
	ds_read_b128 v[214:217], v205 offset:17408
	ds_read_b128 v[218:221], v205 offset:18432
	ds_read_b128 v[222:225], v205 offset:19456
	ds_read_b128 v[226:229], v205 offset:20480
	ds_read_b128 v[230:233], v205 offset:21504
	ds_read_b128 v[234:237], v205 offset:22528
	ds_read_b128 v[238:241], v205 offset:23552
	global_load_lds_dwordx4 v[180:181], off
	s_add_i32 m0, s5, 0x2000
	s_add_u32 s90, s34, 0x40000
	v_lshl_add_u64 v[242:243], s[34:35], 0, v[160:161]
	s_addc_u32 s91, s35, 0
	s_add_i32 s4, s4, s28
	global_load_lds_dwordx4 v[242:243], off
	v_lshl_add_u64 v[244:245], s[90:91], 0, v[156:157]
	s_mov_b32 m0, s4
	v_lshl_add_u64 v[246:247], s[42:43], 0, v[158:159]
	global_load_lds_dwordx4 v[244:245], off
	v_lshl_add_u64 v[244:245], s[90:91], 0, v[160:161]
	s_add_i32 m0, s4, 0x2000
	s_nop 0
	global_load_lds_dwordx4 v[244:245], off
	v_lshl_add_u64 v[244:245], s[42:43], 0, v[154:155]
	s_mov_b32 m0, s69
	s_nop 0
	global_load_lds_dwordx4 v[244:245], off
	s_mov_b32 m0, s62
	s_nop 0
	global_load_lds_dwordx4 v[246:247], off
	s_waitcnt vmcnt(8)
	s_waitcnt lgkmcnt(0)
	s_barrier
	v_mfma_f32_16x16x32_bf16 v[60:63], v[128:131], v[210:213], v[60:63]
	v_mfma_f32_16x16x32_bf16 v[56:59], v[136:139], v[210:213], v[56:59]
	v_mfma_f32_16x16x32_bf16 v[52:55], v[128:131], v[218:221], v[52:55]
	v_mfma_f32_16x16x32_bf16 v[44:47], v[136:139], v[218:221], v[44:47]
	v_mfma_f32_16x16x32_bf16 v[36:39], v[128:131], v[226:229], v[36:39]
	v_mfma_f32_16x16x32_bf16 v[28:31], v[136:139], v[226:229], v[28:31]
	v_mfma_f32_16x16x32_bf16 v[20:23], v[128:131], v[234:237], v[20:23]
	v_mfma_f32_16x16x32_bf16 v[12:15], v[136:139], v[234:237], v[12:15]
	v_mfma_f32_16x16x32_bf16 v[60:63], v[132:135], v[214:217], v[60:63]
	v_mfma_f32_16x16x32_bf16 v[56:59], v[140:143], v[214:217], v[56:59]
	v_mfma_f32_16x16x32_bf16 v[52:55], v[132:135], v[222:225], v[52:55]
	v_mfma_f32_16x16x32_bf16 v[44:47], v[140:143], v[222:225], v[44:47]
	v_mfma_f32_16x16x32_bf16 v[36:39], v[132:135], v[230:233], v[36:39]
	v_mfma_f32_16x16x32_bf16 v[28:31], v[140:143], v[230:233], v[28:31]
	v_mfma_f32_16x16x32_bf16 v[20:23], v[132:135], v[238:241], v[20:23]
	v_mfma_f32_16x16x32_bf16 v[12:15], v[140:143], v[238:241], v[12:15]
	v_mfma_f32_16x16x32_bf16 v[48:51], v[168:171], v[210:213], v[48:51]
	v_mfma_f32_16x16x32_bf16 v[40:43], v[176:179], v[210:213], v[40:43]
	v_mfma_f32_16x16x32_bf16 v[32:35], v[168:171], v[218:221], v[32:35]
	v_mfma_f32_16x16x32_bf16 v[24:27], v[176:179], v[218:221], v[24:27]
	v_mfma_f32_16x16x32_bf16 v[16:19], v[168:171], v[226:229], v[16:19]
	v_mfma_f32_16x16x32_bf16 v[8:11], v[176:179], v[226:229], v[8:11]
	v_mfma_f32_16x16x32_bf16 v[4:7], v[168:171], v[234:237], v[4:7]
	v_mfma_f32_16x16x32_bf16 v[0:3], v[176:179], v[234:237], v[0:3]
	v_mfma_f32_16x16x32_bf16 v[48:51], v[172:175], v[214:217], v[48:51]
	v_mfma_f32_16x16x32_bf16 v[40:43], v[206:209], v[214:217], v[40:43]
	v_mfma_f32_16x16x32_bf16 v[32:35], v[172:175], v[222:225], v[32:35]
	v_mfma_f32_16x16x32_bf16 v[24:27], v[206:209], v[222:225], v[24:27]
	v_mfma_f32_16x16x32_bf16 v[16:19], v[172:175], v[230:233], v[16:19]
	v_mfma_f32_16x16x32_bf16 v[8:11], v[206:209], v[230:233], v[8:11]
	v_mfma_f32_16x16x32_bf16 v[4:7], v[172:175], v[238:241], v[4:7]
	v_mfma_f32_16x16x32_bf16 v[0:3], v[206:209], v[238:241], v[0:3]
	s_barrier
	v_add_u32_e32 v140, 0x18000, v203
	v_add_u32_e32 v144, 0x1c000, v203
	ds_read_b128 v[128:131], v140
	ds_read_b128 v[132:135], v140 offset:1024
	ds_read_b128 v[136:139], v140 offset:2048
	ds_read_b128 v[140:143], v140 offset:3072
	ds_read_b128 v[168:171], v144
	ds_read_b128 v[172:175], v144 offset:1024
	ds_read_b128 v[176:179], v144 offset:2048
	ds_read_b128 v[206:209], v144 offset:3072
	ds_read_b128 v[210:213], v205 offset:32768
	ds_read_b128 v[214:217], v205 offset:33792
	ds_read_b128 v[218:221], v205 offset:34816
	ds_read_b128 v[222:225], v205 offset:35840
	ds_read_b128 v[226:229], v205 offset:36864
	ds_read_b128 v[230:233], v205 offset:37888
	ds_read_b128 v[234:237], v205 offset:38912
	ds_read_b128 v[238:241], v205 offset:39936
	s_add_i32 s4, 0, 0x18000
	s_add_i32 s5, 0, 0x1c000
	s_add_u32 s42, s42, 0x40000
	s_addc_u32 s43, s43, 0
	s_mov_b32 m0, s63
	v_lshl_add_u64 v[248:249], s[42:43], 0, v[154:155]
	global_load_lds_dwordx4 v[248:249], off
	v_lshl_add_u64 v[248:249], s[42:43], 0, v[158:159]
	s_mov_b32 m0, s50
	s_nop 0
	global_load_lds_dwordx4 v[248:249], off
	s_waitcnt vmcnt(8)
	s_waitcnt lgkmcnt(0)
	s_barrier
	v_mfma_f32_16x16x32_bf16 v[124:127], v[128:131], v[210:213], v[124:127]
	v_mfma_f32_16x16x32_bf16 v[120:123], v[136:139], v[210:213], v[120:123]
	v_mfma_f32_16x16x32_bf16 v[112:115], v[128:131], v[218:221], v[112:115]
	v_mfma_f32_16x16x32_bf16 v[108:111], v[136:139], v[218:221], v[108:111]
	v_mfma_f32_16x16x32_bf16 v[100:103], v[128:131], v[226:229], v[100:103]
	v_mfma_f32_16x16x32_bf16 v[92:95], v[136:139], v[226:229], v[92:95]
	v_mfma_f32_16x16x32_bf16 v[84:87], v[128:131], v[234:237], v[84:87]
	v_mfma_f32_16x16x32_bf16 v[76:79], v[136:139], v[234:237], v[76:79]
	v_mfma_f32_16x16x32_bf16 v[124:127], v[132:135], v[214:217], v[124:127]
	v_mfma_f32_16x16x32_bf16 v[120:123], v[140:143], v[214:217], v[120:123]
	v_mfma_f32_16x16x32_bf16 v[112:115], v[132:135], v[222:225], v[112:115]
	v_mfma_f32_16x16x32_bf16 v[108:111], v[140:143], v[222:225], v[108:111]
	v_mfma_f32_16x16x32_bf16 v[100:103], v[132:135], v[230:233], v[100:103]
	v_mfma_f32_16x16x32_bf16 v[92:95], v[140:143], v[230:233], v[92:95]
	v_mfma_f32_16x16x32_bf16 v[84:87], v[132:135], v[238:241], v[84:87]
	v_mfma_f32_16x16x32_bf16 v[76:79], v[140:143], v[238:241], v[76:79]
	v_mfma_f32_16x16x32_bf16 v[116:119], v[168:171], v[210:213], v[116:119]
	v_mfma_f32_16x16x32_bf16 v[104:107], v[176:179], v[210:213], v[104:107]
	v_mfma_f32_16x16x32_bf16 v[96:99], v[168:171], v[218:221], v[96:99]
	v_mfma_f32_16x16x32_bf16 v[88:91], v[176:179], v[218:221], v[88:91]
	v_mfma_f32_16x16x32_bf16 v[80:83], v[168:171], v[226:229], v[80:83]
	v_mfma_f32_16x16x32_bf16 v[72:75], v[176:179], v[226:229], v[72:75]
	v_mfma_f32_16x16x32_bf16 v[68:71], v[168:171], v[234:237], v[68:71]
	v_mfma_f32_16x16x32_bf16 v[64:67], v[176:179], v[234:237], v[64:67]
	v_mfma_f32_16x16x32_bf16 v[116:119], v[172:175], v[214:217], v[116:119]
	v_mfma_f32_16x16x32_bf16 v[104:107], v[206:209], v[214:217], v[104:107]
	v_mfma_f32_16x16x32_bf16 v[96:99], v[172:175], v[222:225], v[96:99]
	v_mfma_f32_16x16x32_bf16 v[88:91], v[206:209], v[222:225], v[88:91]
	v_mfma_f32_16x16x32_bf16 v[80:83], v[172:175], v[230:233], v[80:83]
	v_mfma_f32_16x16x32_bf16 v[72:75], v[206:209], v[230:233], v[72:75]
	v_mfma_f32_16x16x32_bf16 v[68:71], v[172:175], v[238:241], v[68:71]
	v_mfma_f32_16x16x32_bf16 v[64:67], v[206:209], v[238:241], v[64:67]
	s_barrier
	s_add_i32 s4, s4, s28
	v_lshl_add_u64 v[180:181], v[180:181], 0, s[26:27]
	s_mov_b32 m0, s4
	ds_read_b128 v[210:213], v205 offset:49152
	ds_read_b128 v[214:217], v205 offset:50176
	ds_read_b128 v[218:221], v205 offset:51200
	ds_read_b128 v[222:225], v205 offset:52224
	ds_read_b128 v[226:229], v205 offset:53248
	ds_read_b128 v[230:233], v205 offset:54272
	ds_read_b128 v[234:237], v205 offset:55296
	ds_read_b128 v[238:241], v205 offset:56320
	global_load_lds_dwordx4 v[180:181], off
	s_add_i32 m0, s4, 0x2000
	s_add_u32 s34, s34, 0x40080
	v_lshl_add_u64 v[180:181], v[242:243], 0, s[26:27]
	s_addc_u32 s35, s35, 0
	s_add_i32 s4, s5, s28
	global_load_lds_dwordx4 v[180:181], off
	v_lshl_add_u64 v[180:181], s[34:35], 0, v[156:157]
	s_mov_b32 m0, s4
	s_nop 0
	global_load_lds_dwordx4 v[180:181], off
	v_lshl_add_u64 v[180:181], s[34:35], 0, v[160:161]
	s_add_i32 m0, s4, 0x2000
	s_nop 0
	global_load_lds_dwordx4 v[180:181], off
	v_lshl_add_u64 v[180:181], v[244:245], 0, s[26:27]
	s_mov_b32 m0, s51
	s_nop 0
	global_load_lds_dwordx4 v[180:181], off
	v_lshl_add_u64 v[180:181], v[246:247], 0, s[26:27]
	s_mov_b32 m0, s64
	s_nop 0
	global_load_lds_dwordx4 v[180:181], off
	s_add_i32 s88, s88, 2
	s_add_u32 s0, s0, 0x100
	s_addc_u32 s1, s1, 0
	s_add_u32 s79, s79, 0x100
	s_addc_u32 s84, s84, 0
	s_cmp_gt_u32 s88, 13
	s_waitcnt vmcnt(8)
	s_waitcnt lgkmcnt(0)
	s_barrier
	v_mfma_f32_16x16x32_bf16 v[60:63], v[128:131], v[210:213], v[60:63]
	v_mfma_f32_16x16x32_bf16 v[56:59], v[136:139], v[210:213], v[56:59]
	v_mfma_f32_16x16x32_bf16 v[52:55], v[128:131], v[218:221], v[52:55]
	v_mfma_f32_16x16x32_bf16 v[44:47], v[136:139], v[218:221], v[44:47]
	v_mfma_f32_16x16x32_bf16 v[36:39], v[128:131], v[226:229], v[36:39]
	v_mfma_f32_16x16x32_bf16 v[28:31], v[136:139], v[226:229], v[28:31]
	v_mfma_f32_16x16x32_bf16 v[20:23], v[128:131], v[234:237], v[20:23]
	v_mfma_f32_16x16x32_bf16 v[12:15], v[136:139], v[234:237], v[12:15]
	v_mfma_f32_16x16x32_bf16 v[60:63], v[132:135], v[214:217], v[60:63]
	v_mfma_f32_16x16x32_bf16 v[56:59], v[140:143], v[214:217], v[56:59]
	v_mfma_f32_16x16x32_bf16 v[52:55], v[132:135], v[222:225], v[52:55]
	v_mfma_f32_16x16x32_bf16 v[44:47], v[140:143], v[222:225], v[44:47]
	v_mfma_f32_16x16x32_bf16 v[36:39], v[132:135], v[230:233], v[36:39]
	v_mfma_f32_16x16x32_bf16 v[28:31], v[140:143], v[230:233], v[28:31]
	v_mfma_f32_16x16x32_bf16 v[20:23], v[132:135], v[238:241], v[20:23]
	v_mfma_f32_16x16x32_bf16 v[12:15], v[140:143], v[238:241], v[12:15]
	v_mfma_f32_16x16x32_bf16 v[48:51], v[168:171], v[210:213], v[48:51]
	v_mfma_f32_16x16x32_bf16 v[40:43], v[176:179], v[210:213], v[40:43]
	v_mfma_f32_16x16x32_bf16 v[32:35], v[168:171], v[218:221], v[32:35]
	v_mfma_f32_16x16x32_bf16 v[24:27], v[176:179], v[218:221], v[24:27]
	v_mfma_f32_16x16x32_bf16 v[16:19], v[168:171], v[226:229], v[16:19]
	v_mfma_f32_16x16x32_bf16 v[8:11], v[176:179], v[226:229], v[8:11]
	v_mfma_f32_16x16x32_bf16 v[4:7], v[168:171], v[234:237], v[4:7]
	v_mfma_f32_16x16x32_bf16 v[0:3], v[176:179], v[234:237], v[0:3]
	v_mfma_f32_16x16x32_bf16 v[48:51], v[172:175], v[214:217], v[48:51]
	v_mfma_f32_16x16x32_bf16 v[40:43], v[206:209], v[214:217], v[40:43]
	v_mfma_f32_16x16x32_bf16 v[32:35], v[172:175], v[222:225], v[32:35]
	v_mfma_f32_16x16x32_bf16 v[24:27], v[206:209], v[222:225], v[24:27]
	v_mfma_f32_16x16x32_bf16 v[16:19], v[172:175], v[230:233], v[16:19]
	v_mfma_f32_16x16x32_bf16 v[8:11], v[206:209], v[230:233], v[8:11]
	v_mfma_f32_16x16x32_bf16 v[4:7], v[172:175], v[238:241], v[4:7]
	v_mfma_f32_16x16x32_bf16 v[0:3], v[206:209], v[238:241], v[0:3]
	s_barrier
	s_cbranch_scc0 .LBB0_605
	s_setprio 0
	s_and_b64 vcc, exec, s[66:67]
	s_cbranch_vccz .LBB0_608
	s_barrier

.Lkprio_1005:
.LBB0_1005:
	v_add_u32_e32 v138, 0x10000, v141
	ds_read_b128 v[154:157], v138
	ds_read_b128 v[158:161], v138 offset:1024
	ds_read_b128 v[162:165], v138 offset:2048
	ds_read_b128 v[166:169], v138 offset:3072
	v_add_u32_e32 v138, 0x14000, v141
	ds_read_b128 v[170:173], v138
	ds_read_b128 v[174:177], v138 offset:1024
	ds_read_b128 v[178:181], v138 offset:2048
	ds_read_b128 v[204:207], v138 offset:3072
	ds_read_b128 v[208:211], v143
	ds_read_b128 v[212:215], v143 offset:1024
	ds_read_b128 v[216:219], v143 offset:2048
	ds_read_b128 v[220:223], v143 offset:3072
	ds_read_b128 v[224:227], v143 offset:4096
	ds_read_b128 v[228:231], v143 offset:5120
	ds_read_b128 v[232:235], v143 offset:6144
	ds_read_b128 v[236:239], v143 offset:7168
	s_add_u32 s4, s54, 0xfffe0080
	s_addc_u32 s5, s55, -1
	s_add_i32 s72, 0, 0x10000
	s_cmp_eq_u32 s71, 4
	s_cselect_b32 s59, s29, s5
	s_cselect_b32 s58, s47, s4
	s_cselect_b32 s35, s45, s70
	s_cselect_b32 s34, s68, s69
	s_add_i32 s73, 0, 0x14000
	v_lshl_add_u64 v[138:139], s[54:55], 0, v[134:135]
	s_add_i32 m0, s53, 0xc000
	s_nop 0
	global_load_lds_dwordx4 v[138:139], off
	v_lshl_add_u64 v[138:139], s[54:55], 0, v[136:137]
	s_add_i32 m0, s53, 0xe000
	s_nop 0
	global_load_lds_dwordx4 v[138:139], off
	s_waitcnt vmcnt(8)
	s_waitcnt lgkmcnt(0)
	s_barrier
	v_mfma_f32_16x16x32_bf16 v[120:123], v[154:157], v[208:211], v[120:123]
	v_mfma_f32_16x16x32_bf16 v[124:127], v[162:165], v[208:211], v[124:127]
	v_mfma_f32_16x16x32_bf16 v[104:107], v[154:157], v[216:219], v[104:107]
	v_mfma_f32_16x16x32_bf16 v[108:111], v[162:165], v[216:219], v[108:111]
	v_mfma_f32_16x16x32_bf16 v[88:91], v[154:157], v[224:227], v[88:91]
	v_mfma_f32_16x16x32_bf16 v[92:95], v[162:165], v[224:227], v[92:95]
	v_mfma_f32_16x16x32_bf16 v[72:75], v[154:157], v[232:235], v[72:75]
	v_mfma_f32_16x16x32_bf16 v[76:79], v[162:165], v[232:235], v[76:79]
	v_mfma_f32_16x16x32_bf16 v[120:123], v[158:161], v[212:215], v[120:123]
	v_mfma_f32_16x16x32_bf16 v[124:127], v[166:169], v[212:215], v[124:127]
	v_mfma_f32_16x16x32_bf16 v[104:107], v[158:161], v[220:223], v[104:107]
	v_mfma_f32_16x16x32_bf16 v[108:111], v[166:169], v[220:223], v[108:111]
	v_mfma_f32_16x16x32_bf16 v[88:91], v[158:161], v[228:231], v[88:91]
	v_mfma_f32_16x16x32_bf16 v[92:95], v[166:169], v[228:231], v[92:95]
	v_mfma_f32_16x16x32_bf16 v[72:75], v[158:161], v[236:239], v[72:75]
	v_mfma_f32_16x16x32_bf16 v[76:79], v[166:169], v[236:239], v[76:79]
	v_mfma_f32_16x16x32_bf16 v[112:115], v[170:173], v[208:211], v[112:115]
	v_mfma_f32_16x16x32_bf16 v[116:119], v[178:181], v[208:211], v[116:119]
	v_mfma_f32_16x16x32_bf16 v[96:99], v[170:173], v[216:219], v[96:99]
	v_mfma_f32_16x16x32_bf16 v[100:103], v[178:181], v[216:219], v[100:103]
	v_mfma_f32_16x16x32_bf16 v[80:83], v[170:173], v[224:227], v[80:83]
	v_mfma_f32_16x16x32_bf16 v[84:87], v[178:181], v[224:227], v[84:87]
	v_mfma_f32_16x16x32_bf16 v[64:67], v[170:173], v[232:235], v[64:67]
	v_mfma_f32_16x16x32_bf16 v[68:71], v[178:181], v[232:235], v[68:71]
	v_mfma_f32_16x16x32_bf16 v[112:115], v[174:177], v[212:215], v[112:115]
	v_mfma_f32_16x16x32_bf16 v[116:119], v[204:207], v[212:215], v[116:119]
	v_mfma_f32_16x16x32_bf16 v[96:99], v[174:177], v[220:223], v[96:99]
	v_mfma_f32_16x16x32_bf16 v[100:103], v[204:207], v[220:223], v[100:103]
	v_mfma_f32_16x16x32_bf16 v[80:83], v[174:177], v[228:231], v[80:83]
	v_mfma_f32_16x16x32_bf16 v[84:87], v[204:207], v[228:231], v[84:87]
	v_mfma_f32_16x16x32_bf16 v[64:67], v[174:177], v[236:239], v[64:67]
	v_mfma_f32_16x16x32_bf16 v[68:71], v[204:207], v[236:239], v[68:71]
	s_barrier
	s_add_i32 s4, s72, s30
	v_lshl_add_u64 v[138:139], s[34:35], 0, v[144:145]
	s_mov_b32 m0, s4
	ds_read_b128 v[208:211], v143 offset:16384
	ds_read_b128 v[212:215], v143 offset:17408
	ds_read_b128 v[216:219], v143 offset:18432
	ds_read_b128 v[220:223], v143 offset:19456
	ds_read_b128 v[224:227], v143 offset:20480
	ds_read_b128 v[228:231], v143 offset:21504
	ds_read_b128 v[232:235], v143 offset:22528
	ds_read_b128 v[236:239], v143 offset:23552
	global_load_lds_dwordx4 v[138:139], off
	s_add_i32 m0, s4, 0x2000
	s_add_u32 s4, s34, 0x20000
	v_lshl_add_u64 v[202:203], s[34:35], 0, v[132:133]
	s_addc_u32 s5, s35, 0
	s_add_i32 s72, s73, s30
	global_load_lds_dwordx4 v[202:203], off
	v_lshl_add_u64 v[240:241], s[4:5], 0, v[144:145]
	s_mov_b32 m0, s72
	v_lshl_add_u64 v[242:243], s[58:59], 0, v[130:131]
	global_load_lds_dwordx4 v[240:241], off
	v_lshl_add_u64 v[240:241], s[4:5], 0, v[132:133]
	s_add_i32 m0, s72, 0x2000
	s_nop 0
	global_load_lds_dwordx4 v[240:241], off
	v_lshl_add_u64 v[240:241], s[58:59], 0, v[128:129]
	s_mov_b32 m0, s53
	s_nop 0
	global_load_lds_dwordx4 v[240:241], off
	s_mov_b32 m0, s62
	s_nop 0
	global_load_lds_dwordx4 v[242:243], off
	s_waitcnt vmcnt(8)
	s_waitcnt lgkmcnt(0)
	s_barrier
	v_mfma_f32_16x16x32_bf16 v[56:59], v[154:157], v[208:211], v[56:59]
	v_mfma_f32_16x16x32_bf16 v[60:63], v[162:165], v[208:211], v[60:63]
	v_mfma_f32_16x16x32_bf16 v[40:43], v[154:157], v[216:219], v[40:43]
	v_mfma_f32_16x16x32_bf16 v[44:47], v[162:165], v[216:219], v[44:47]
	v_mfma_f32_16x16x32_bf16 v[24:27], v[154:157], v[224:227], v[24:27]
	v_mfma_f32_16x16x32_bf16 v[28:31], v[162:165], v[224:227], v[28:31]
	v_mfma_f32_16x16x32_bf16 v[8:11], v[154:157], v[232:235], v[8:11]
	v_mfma_f32_16x16x32_bf16 v[12:15], v[162:165], v[232:235], v[12:15]
	v_mfma_f32_16x16x32_bf16 v[56:59], v[158:161], v[212:215], v[56:59]
	v_mfma_f32_16x16x32_bf16 v[60:63], v[166:169], v[212:215], v[60:63]
	v_mfma_f32_16x16x32_bf16 v[40:43], v[158:161], v[220:223], v[40:43]
	v_mfma_f32_16x16x32_bf16 v[44:47], v[166:169], v[220:223], v[44:47]
	v_mfma_f32_16x16x32_bf16 v[24:27], v[158:161], v[228:231], v[24:27]
	v_mfma_f32_16x16x32_bf16 v[28:31], v[166:169], v[228:231], v[28:31]
	v_mfma_f32_16x16x32_bf16 v[8:11], v[158:161], v[236:239], v[8:11]
	v_mfma_f32_16x16x32_bf16 v[12:15], v[166:169], v[236:239], v[12:15]
	v_mfma_f32_16x16x32_bf16 v[48:51], v[170:173], v[208:211], v[48:51]
	v_mfma_f32_16x16x32_bf16 v[52:55], v[178:181], v[208:211], v[52:55]
	v_mfma_f32_16x16x32_bf16 v[32:35], v[170:173], v[216:219], v[32:35]
	v_mfma_f32_16x16x32_bf16 v[36:39], v[178:181], v[216:219], v[36:39]
	v_mfma_f32_16x16x32_bf16 v[16:19], v[170:173], v[224:227], v[16:19]
	v_mfma_f32_16x16x32_bf16 v[20:23], v[178:181], v[224:227], v[20:23]
	v_mfma_f32_16x16x32_bf16 v[0:3], v[170:173], v[232:235], v[0:3]
	v_mfma_f32_16x16x32_bf16 v[4:7], v[178:181], v[232:235], v[4:7]
	v_mfma_f32_16x16x32_bf16 v[48:51], v[174:177], v[212:215], v[48:51]
	v_mfma_f32_16x16x32_bf16 v[52:55], v[204:207], v[212:215], v[52:55]
	v_mfma_f32_16x16x32_bf16 v[32:35], v[174:177], v[220:223], v[32:35]
	v_mfma_f32_16x16x32_bf16 v[36:39], v[204:207], v[220:223], v[36:39]
	v_mfma_f32_16x16x32_bf16 v[16:19], v[174:177], v[228:231], v[16:19]
	v_mfma_f32_16x16x32_bf16 v[20:23], v[204:207], v[228:231], v[20:23]
	v_mfma_f32_16x16x32_bf16 v[0:3], v[174:177], v[236:239], v[0:3]
	v_mfma_f32_16x16x32_bf16 v[4:7], v[204:207], v[236:239], v[4:7]
	s_barrier
	v_add_u32_e32 v166, 0x18000, v141
	v_add_u32_e32 v204, 0x1c000, v141
	ds_read_b128 v[154:157], v166
	ds_read_b128 v[158:161], v166 offset:1024
	ds_read_b128 v[162:165], v166 offset:2048
	ds_read_b128 v[166:169], v166 offset:3072
	ds_read_b128 v[170:173], v204
	ds_read_b128 v[174:177], v204 offset:1024
	ds_read_b128 v[178:181], v204 offset:2048
	ds_read_b128 v[204:207], v204 offset:3072
	ds_read_b128 v[208:211], v143 offset:32768
	ds_read_b128 v[212:215], v143 offset:33792
	ds_read_b128 v[216:219], v143 offset:34816
	ds_read_b128 v[220:223], v143 offset:35840
	ds_read_b128 v[224:227], v143 offset:36864
	ds_read_b128 v[228:231], v143 offset:37888
	ds_read_b128 v[232:235], v143 offset:38912
	ds_read_b128 v[236:239], v143 offset:39936
	s_add_i32 s72, 0, 0x18000
	s_add_i32 s73, 0, 0x1c000
	s_add_u32 s4, s58, 0x20000
	s_addc_u32 s5, s59, 0
	s_mov_b32 m0, s63
	v_lshl_add_u64 v[244:245], s[4:5], 0, v[128:129]
	global_load_lds_dwordx4 v[244:245], off
	v_lshl_add_u64 v[244:245], s[4:5], 0, v[130:131]
	s_mov_b32 m0, s64
	s_nop 0
	global_load_lds_dwordx4 v[244:245], off
	s_waitcnt vmcnt(8)
	s_waitcnt lgkmcnt(0)
	s_barrier
	v_mfma_f32_16x16x32_bf16 v[120:123], v[154:157], v[208:211], v[120:123]
	v_mfma_f32_16x16x32_bf16 v[124:127], v[162:165], v[208:211], v[124:127]
	v_mfma_f32_16x16x32_bf16 v[104:107], v[154:157], v[216:219], v[104:107]
	v_mfma_f32_16x16x32_bf16 v[108:111], v[162:165], v[216:219], v[108:111]
	v_mfma_f32_16x16x32_bf16 v[88:91], v[154:157], v[224:227], v[88:91]
	v_mfma_f32_16x16x32_bf16 v[92:95], v[162:165], v[224:227], v[92:95]
	v_mfma_f32_16x16x32_bf16 v[72:75], v[154:157], v[232:235], v[72:75]
	v_mfma_f32_16x16x32_bf16 v[76:79], v[162:165], v[232:235], v[76:79]
	v_mfma_f32_16x16x32_bf16 v[120:123], v[158:161], v[212:215], v[120:123]
	v_mfma_f32_16x16x32_bf16 v[124:127], v[166:169], v[212:215], v[124:127]
	v_mfma_f32_16x16x32_bf16 v[104:107], v[158:161], v[220:223], v[104:107]
	v_mfma_f32_16x16x32_bf16 v[108:111], v[166:169], v[220:223], v[108:111]
	v_mfma_f32_16x16x32_bf16 v[88:91], v[158:161], v[228:231], v[88:91]
	v_mfma_f32_16x16x32_bf16 v[92:95], v[166:169], v[228:231], v[92:95]
	v_mfma_f32_16x16x32_bf16 v[72:75], v[158:161], v[236:239], v[72:75]
	v_mfma_f32_16x16x32_bf16 v[76:79], v[166:169], v[236:239], v[76:79]
	v_mfma_f32_16x16x32_bf16 v[112:115], v[170:173], v[208:211], v[112:115]
	v_mfma_f32_16x16x32_bf16 v[116:119], v[178:181], v[208:211], v[116:119]
	v_mfma_f32_16x16x32_bf16 v[96:99], v[170:173], v[216:219], v[96:99]
	v_mfma_f32_16x16x32_bf16 v[100:103], v[178:181], v[216:219], v[100:103]
	v_mfma_f32_16x16x32_bf16 v[80:83], v[170:173], v[224:227], v[80:83]
	v_mfma_f32_16x16x32_bf16 v[84:87], v[178:181], v[224:227], v[84:87]
	v_mfma_f32_16x16x32_bf16 v[64:67], v[170:173], v[232:235], v[64:67]
	v_mfma_f32_16x16x32_bf16 v[68:71], v[178:181], v[232:235], v[68:71]
	v_mfma_f32_16x16x32_bf16 v[112:115], v[174:177], v[212:215], v[112:115]
	v_mfma_f32_16x16x32_bf16 v[116:119], v[204:207], v[212:215], v[116:119]
	v_mfma_f32_16x16x32_bf16 v[96:99], v[174:177], v[220:223], v[96:99]
	v_mfma_f32_16x16x32_bf16 v[100:103], v[204:207], v[220:223], v[100:103]
	v_mfma_f32_16x16x32_bf16 v[80:83], v[174:177], v[228:231], v[80:83]
	v_mfma_f32_16x16x32_bf16 v[84:87], v[204:207], v[228:231], v[84:87]
	v_mfma_f32_16x16x32_bf16 v[64:67], v[174:177], v[236:239], v[64:67]
	v_mfma_f32_16x16x32_bf16 v[68:71], v[204:207], v[236:239], v[68:71]
	s_barrier
	s_add_i32 s4, s72, s30
	v_lshl_add_u64 v[138:139], v[138:139], 0, s[26:27]
	s_mov_b32 m0, s4
	ds_read_b128 v[208:211], v143 offset:49152
	ds_read_b128 v[212:215], v143 offset:50176
	ds_read_b128 v[216:219], v143 offset:51200
	ds_read_b128 v[220:223], v143 offset:52224
	ds_read_b128 v[224:227], v143 offset:53248
	ds_read_b128 v[228:231], v143 offset:54272
	ds_read_b128 v[232:235], v143 offset:55296
	ds_read_b128 v[236:239], v143 offset:56320
	global_load_lds_dwordx4 v[138:139], off
	s_add_i32 m0, s4, 0x2000
	s_add_u32 s4, s34, 0x20080
	v_lshl_add_u64 v[138:139], v[202:203], 0, s[26:27]
	s_addc_u32 s5, s35, 0
	s_add_i32 s34, s73, s30
	global_load_lds_dwordx4 v[138:139], off
	v_lshl_add_u64 v[138:139], s[4:5], 0, v[144:145]
	s_mov_b32 m0, s34
	s_nop 0
	global_load_lds_dwordx4 v[138:139], off
	v_lshl_add_u64 v[138:139], s[4:5], 0, v[132:133]
	s_add_i32 m0, s34, 0x2000
	s_nop 0
	global_load_lds_dwordx4 v[138:139], off
	v_lshl_add_u64 v[138:139], v[240:241], 0, s[26:27]
	s_mov_b32 m0, s65
	s_nop 0
	global_load_lds_dwordx4 v[138:139], off
	v_lshl_add_u64 v[138:139], v[242:243], 0, s[26:27]
	s_mov_b32 m0, s66
	s_nop 0
	global_load_lds_dwordx4 v[138:139], off
	s_add_i32 s71, s71, 2
	s_add_u32 s54, s54, 0x100
	s_addc_u32 s55, s55, 0
	s_add_u32 s69, s69, 0x100
	s_addc_u32 s70, s70, 0
	s_cmp_gt_u32 s71, 5
	s_waitcnt vmcnt(8)
	s_waitcnt lgkmcnt(0)
	s_barrier
	v_mfma_f32_16x16x32_bf16 v[56:59], v[154:157], v[208:211], v[56:59]
	v_mfma_f32_16x16x32_bf16 v[60:63], v[162:165], v[208:211], v[60:63]
	v_mfma_f32_16x16x32_bf16 v[40:43], v[154:157], v[216:219], v[40:43]
	v_mfma_f32_16x16x32_bf16 v[44:47], v[162:165], v[216:219], v[44:47]
	v_mfma_f32_16x16x32_bf16 v[24:27], v[154:157], v[224:227], v[24:27]
	v_mfma_f32_16x16x32_bf16 v[28:31], v[162:165], v[224:227], v[28:31]
	v_mfma_f32_16x16x32_bf16 v[8:11], v[154:157], v[232:235], v[8:11]
	v_mfma_f32_16x16x32_bf16 v[12:15], v[162:165], v[232:235], v[12:15]
	v_mfma_f32_16x16x32_bf16 v[56:59], v[158:161], v[212:215], v[56:59]
	v_mfma_f32_16x16x32_bf16 v[60:63], v[166:169], v[212:215], v[60:63]
	v_mfma_f32_16x16x32_bf16 v[40:43], v[158:161], v[220:223], v[40:43]
	v_mfma_f32_16x16x32_bf16 v[44:47], v[166:169], v[220:223], v[44:47]
	v_mfma_f32_16x16x32_bf16 v[24:27], v[158:161], v[228:231], v[24:27]
	v_mfma_f32_16x16x32_bf16 v[28:31], v[166:169], v[228:231], v[28:31]
	v_mfma_f32_16x16x32_bf16 v[8:11], v[158:161], v[236:239], v[8:11]
	v_mfma_f32_16x16x32_bf16 v[12:15], v[166:169], v[236:239], v[12:15]
	v_mfma_f32_16x16x32_bf16 v[48:51], v[170:173], v[208:211], v[48:51]
	v_mfma_f32_16x16x32_bf16 v[52:55], v[178:181], v[208:211], v[52:55]
	v_mfma_f32_16x16x32_bf16 v[32:35], v[170:173], v[216:219], v[32:35]
	v_mfma_f32_16x16x32_bf16 v[36:39], v[178:181], v[216:219], v[36:39]
	v_mfma_f32_16x16x32_bf16 v[16:19], v[170:173], v[224:227], v[16:19]
	v_mfma_f32_16x16x32_bf16 v[20:23], v[178:181], v[224:227], v[20:23]
	v_mfma_f32_16x16x32_bf16 v[0:3], v[170:173], v[232:235], v[0:3]
	v_mfma_f32_16x16x32_bf16 v[4:7], v[178:181], v[232:235], v[4:7]
	v_mfma_f32_16x16x32_bf16 v[48:51], v[174:177], v[212:215], v[48:51]
	v_mfma_f32_16x16x32_bf16 v[52:55], v[204:207], v[212:215], v[52:55]
	v_mfma_f32_16x16x32_bf16 v[32:35], v[174:177], v[220:223], v[32:35]
	v_mfma_f32_16x16x32_bf16 v[36:39], v[204:207], v[220:223], v[36:39]
	v_mfma_f32_16x16x32_bf16 v[16:19], v[174:177], v[228:231], v[16:19]
	v_mfma_f32_16x16x32_bf16 v[20:23], v[204:207], v[228:231], v[20:23]
	v_mfma_f32_16x16x32_bf16 v[0:3], v[174:177], v[236:239], v[0:3]
	v_mfma_f32_16x16x32_bf16 v[4:7], v[204:207], v[236:239], v[4:7]
	s_barrier
	s_cbranch_scc0 .LBB0_1005
	s_setprio 0
	v_readlane_b32 s68, v255, 7
	s_and_b64 vcc, exec, s[42:43]
	v_readlane_b32 s69, v255, 8
	s_cbranch_vccz .LBB0_1008
	s_barrier

.Lkprio_1093:
.LBB0_1093:
	v_add_u32_e32 v164, 0x10000, v143
	v_add_u32_e32 v180, 0x14000, v143
	ds_read_b128 v[138:141], v164
	ds_read_b128 v[156:159], v164 offset:1024
	ds_read_b128 v[160:163], v164 offset:2048
	ds_read_b128 v[164:167], v164 offset:3072
	ds_read_b128 v[168:171], v180
	ds_read_b128 v[172:175], v180 offset:1024
	ds_read_b128 v[176:179], v180 offset:2048
	ds_read_b128 v[204:207], v180 offset:3072
	ds_read_b128 v[208:211], v155
	ds_read_b128 v[212:215], v155 offset:1024
	ds_read_b128 v[216:219], v155 offset:2048
	ds_read_b128 v[220:223], v155 offset:3072
	ds_read_b128 v[224:227], v155 offset:4096
	ds_read_b128 v[228:231], v155 offset:5120
	ds_read_b128 v[232:235], v155 offset:6144
	ds_read_b128 v[236:239], v155 offset:7168
	s_add_u32 s4, s58, 0xfffe0080
	s_addc_u32 s5, s59, -1
	s_add_i32 s74, 0, 0x10000
	s_cmp_eq_u32 s73, 4
	s_cselect_b32 s61, s33, s5
	s_cselect_b32 s60, s36, s4
	s_cselect_b32 s35, s49, s72
	s_cselect_b32 s34, s51, s71
	s_add_i32 s75, 0, 0x14000
	v_lshl_add_u64 v[180:181], s[58:59], 0, v[134:135]
	s_add_i32 m0, s64, 0xc000
	s_nop 0
	global_load_lds_dwordx4 v[180:181], off
	v_lshl_add_u64 v[180:181], s[58:59], 0, v[136:137]
	s_add_i32 m0, s64, 0xe000
	s_nop 0
	global_load_lds_dwordx4 v[180:181], off
	s_waitcnt vmcnt(8)
	s_waitcnt lgkmcnt(0)
	s_barrier
	v_mfma_f32_16x16x32_bf16 v[124:127], v[138:141], v[208:211], v[124:127]
	v_mfma_f32_16x16x32_bf16 v[120:123], v[160:163], v[208:211], v[120:123]
	v_mfma_f32_16x16x32_bf16 v[108:111], v[138:141], v[216:219], v[108:111]
	v_mfma_f32_16x16x32_bf16 v[104:107], v[160:163], v[216:219], v[104:107]
	v_mfma_f32_16x16x32_bf16 v[92:95], v[138:141], v[224:227], v[92:95]
	v_mfma_f32_16x16x32_bf16 v[88:91], v[160:163], v[224:227], v[88:91]
	v_mfma_f32_16x16x32_bf16 v[76:79], v[138:141], v[232:235], v[76:79]
	v_mfma_f32_16x16x32_bf16 v[72:75], v[160:163], v[232:235], v[72:75]
	v_mfma_f32_16x16x32_bf16 v[124:127], v[156:159], v[212:215], v[124:127]
	v_mfma_f32_16x16x32_bf16 v[120:123], v[164:167], v[212:215], v[120:123]
	v_mfma_f32_16x16x32_bf16 v[108:111], v[156:159], v[220:223], v[108:111]
	v_mfma_f32_16x16x32_bf16 v[104:107], v[164:167], v[220:223], v[104:107]
	v_mfma_f32_16x16x32_bf16 v[92:95], v[156:159], v[228:231], v[92:95]
	v_mfma_f32_16x16x32_bf16 v[88:91], v[164:167], v[228:231], v[88:91]
	v_mfma_f32_16x16x32_bf16 v[76:79], v[156:159], v[236:239], v[76:79]
	v_mfma_f32_16x16x32_bf16 v[72:75], v[164:167], v[236:239], v[72:75]
	v_mfma_f32_16x16x32_bf16 v[116:119], v[168:171], v[208:211], v[116:119]
	v_mfma_f32_16x16x32_bf16 v[112:115], v[176:179], v[208:211], v[112:115]
	v_mfma_f32_16x16x32_bf16 v[100:103], v[168:171], v[216:219], v[100:103]
	v_mfma_f32_16x16x32_bf16 v[96:99], v[176:179], v[216:219], v[96:99]
	v_mfma_f32_16x16x32_bf16 v[84:87], v[168:171], v[224:227], v[84:87]
	v_mfma_f32_16x16x32_bf16 v[80:83], v[176:179], v[224:227], v[80:83]
	v_mfma_f32_16x16x32_bf16 v[68:71], v[168:171], v[232:235], v[68:71]
	v_mfma_f32_16x16x32_bf16 v[64:67], v[176:179], v[232:235], v[64:67]
	v_mfma_f32_16x16x32_bf16 v[116:119], v[172:175], v[212:215], v[116:119]
	v_mfma_f32_16x16x32_bf16 v[112:115], v[204:207], v[212:215], v[112:115]
	v_mfma_f32_16x16x32_bf16 v[100:103], v[172:175], v[220:223], v[100:103]
	v_mfma_f32_16x16x32_bf16 v[96:99], v[204:207], v[220:223], v[96:99]
	v_mfma_f32_16x16x32_bf16 v[84:87], v[172:175], v[228:231], v[84:87]
	v_mfma_f32_16x16x32_bf16 v[80:83], v[204:207], v[228:231], v[80:83]
	v_mfma_f32_16x16x32_bf16 v[68:71], v[172:175], v[236:239], v[68:71]
	v_mfma_f32_16x16x32_bf16 v[64:67], v[204:207], v[236:239], v[64:67]
	s_barrier
	s_add_i32 s4, s74, s28
	v_lshl_add_u64 v[180:181], s[34:35], 0, v[144:145]
	s_mov_b32 m0, s4
	ds_read_b128 v[208:211], v155 offset:16384
	ds_read_b128 v[212:215], v155 offset:17408
	ds_read_b128 v[216:219], v155 offset:18432
	ds_read_b128 v[220:223], v155 offset:19456
	ds_read_b128 v[224:227], v155 offset:20480
	ds_read_b128 v[228:231], v155 offset:21504
	ds_read_b128 v[232:235], v155 offset:22528
	ds_read_b128 v[236:239], v155 offset:23552
	global_load_lds_dwordx4 v[180:181], off
	s_add_i32 m0, s4, 0x2000
	s_add_u32 s4, s34, 0x20000
	v_lshl_add_u64 v[202:203], s[34:35], 0, v[132:133]
	s_addc_u32 s5, s35, 0
	s_add_i32 s74, s75, s28
	global_load_lds_dwordx4 v[202:203], off
	v_lshl_add_u64 v[240:241], s[4:5], 0, v[144:145]
	s_mov_b32 m0, s74
	v_lshl_add_u64 v[242:243], s[60:61], 0, v[130:131]
	global_load_lds_dwordx4 v[240:241], off
	v_lshl_add_u64 v[240:241], s[4:5], 0, v[132:133]
	s_add_i32 m0, s74, 0x2000
	s_nop 0
	global_load_lds_dwordx4 v[240:241], off
	v_lshl_add_u64 v[240:241], s[60:61], 0, v[128:129]
	s_mov_b32 m0, s64
	s_nop 0
	global_load_lds_dwordx4 v[240:241], off
	s_mov_b32 m0, s65
	s_nop 0
	global_load_lds_dwordx4 v[242:243], off
	s_waitcnt vmcnt(8)
	s_waitcnt lgkmcnt(0)
	s_barrier
	v_mfma_f32_16x16x32_bf16 v[60:63], v[138:141], v[208:211], v[60:63]
	v_mfma_f32_16x16x32_bf16 v[56:59], v[160:163], v[208:211], v[56:59]
	v_mfma_f32_16x16x32_bf16 v[44:47], v[138:141], v[216:219], v[44:47]
	v_mfma_f32_16x16x32_bf16 v[40:43], v[160:163], v[216:219], v[40:43]
	v_mfma_f32_16x16x32_bf16 v[28:31], v[138:141], v[224:227], v[28:31]
	v_mfma_f32_16x16x32_bf16 v[24:27], v[160:163], v[224:227], v[24:27]
	v_mfma_f32_16x16x32_bf16 v[12:15], v[138:141], v[232:235], v[12:15]
	v_mfma_f32_16x16x32_bf16 v[8:11], v[160:163], v[232:235], v[8:11]
	v_mfma_f32_16x16x32_bf16 v[60:63], v[156:159], v[212:215], v[60:63]
	v_mfma_f32_16x16x32_bf16 v[56:59], v[164:167], v[212:215], v[56:59]
	v_mfma_f32_16x16x32_bf16 v[44:47], v[156:159], v[220:223], v[44:47]
	v_mfma_f32_16x16x32_bf16 v[40:43], v[164:167], v[220:223], v[40:43]
	v_mfma_f32_16x16x32_bf16 v[28:31], v[156:159], v[228:231], v[28:31]
	v_mfma_f32_16x16x32_bf16 v[24:27], v[164:167], v[228:231], v[24:27]
	v_mfma_f32_16x16x32_bf16 v[12:15], v[156:159], v[236:239], v[12:15]
	v_mfma_f32_16x16x32_bf16 v[8:11], v[164:167], v[236:239], v[8:11]
	v_mfma_f32_16x16x32_bf16 v[52:55], v[168:171], v[208:211], v[52:55]
	v_mfma_f32_16x16x32_bf16 v[48:51], v[176:179], v[208:211], v[48:51]
	v_mfma_f32_16x16x32_bf16 v[36:39], v[168:171], v[216:219], v[36:39]
	v_mfma_f32_16x16x32_bf16 v[32:35], v[176:179], v[216:219], v[32:35]
	v_mfma_f32_16x16x32_bf16 v[20:23], v[168:171], v[224:227], v[20:23]
	v_mfma_f32_16x16x32_bf16 v[16:19], v[176:179], v[224:227], v[16:19]
	v_mfma_f32_16x16x32_bf16 v[4:7], v[168:171], v[232:235], v[4:7]
	v_mfma_f32_16x16x32_bf16 v[0:3], v[176:179], v[232:235], v[0:3]
	v_mfma_f32_16x16x32_bf16 v[52:55], v[172:175], v[212:215], v[52:55]
	v_mfma_f32_16x16x32_bf16 v[48:51], v[204:207], v[212:215], v[48:51]
	v_mfma_f32_16x16x32_bf16 v[36:39], v[172:175], v[220:223], v[36:39]
	v_mfma_f32_16x16x32_bf16 v[32:35], v[204:207], v[220:223], v[32:35]
	v_mfma_f32_16x16x32_bf16 v[20:23], v[172:175], v[228:231], v[20:23]
	v_mfma_f32_16x16x32_bf16 v[16:19], v[204:207], v[228:231], v[16:19]
	v_mfma_f32_16x16x32_bf16 v[4:7], v[172:175], v[236:239], v[4:7]
	v_mfma_f32_16x16x32_bf16 v[0:3], v[204:207], v[236:239], v[0:3]
	s_barrier
	v_add_u32_e32 v164, 0x18000, v143
	v_add_u32_e32 v204, 0x1c000, v143
	ds_read_b128 v[138:141], v164
	ds_read_b128 v[156:159], v164 offset:1024
	ds_read_b128 v[160:163], v164 offset:2048
	ds_read_b128 v[164:167], v164 offset:3072
	ds_read_b128 v[168:171], v204
	ds_read_b128 v[172:175], v204 offset:1024
	ds_read_b128 v[176:179], v204 offset:2048
	ds_read_b128 v[204:207], v204 offset:3072
	ds_read_b128 v[208:211], v155 offset:32768
	ds_read_b128 v[212:215], v155 offset:33792
	ds_read_b128 v[216:219], v155 offset:34816
	ds_read_b128 v[220:223], v155 offset:35840
	ds_read_b128 v[224:227], v155 offset:36864
	ds_read_b128 v[228:231], v155 offset:37888
	ds_read_b128 v[232:235], v155 offset:38912
	ds_read_b128 v[236:239], v155 offset:39936
	s_add_i32 s74, 0, 0x18000
	s_add_i32 s75, 0, 0x1c000
	s_add_u32 s4, s60, 0x20000
	s_addc_u32 s5, s61, 0
	s_mov_b32 m0, s66
	v_lshl_add_u64 v[244:245], s[4:5], 0, v[128:129]
	global_load_lds_dwordx4 v[244:245], off
	v_lshl_add_u64 v[244:245], s[4:5], 0, v[130:131]
	s_mov_b32 m0, s67
	s_nop 0
	global_load_lds_dwordx4 v[244:245], off
	s_waitcnt vmcnt(8)
	s_waitcnt lgkmcnt(0)
	s_barrier
	v_mfma_f32_16x16x32_bf16 v[124:127], v[138:141], v[208:211], v[124:127]
	v_mfma_f32_16x16x32_bf16 v[120:123], v[160:163], v[208:211], v[120:123]
	v_mfma_f32_16x16x32_bf16 v[108:111], v[138:141], v[216:219], v[108:111]
	v_mfma_f32_16x16x32_bf16 v[104:107], v[160:163], v[216:219], v[104:107]
	v_mfma_f32_16x16x32_bf16 v[92:95], v[138:141], v[224:227], v[92:95]
	v_mfma_f32_16x16x32_bf16 v[88:91], v[160:163], v[224:227], v[88:91]
	v_mfma_f32_16x16x32_bf16 v[76:79], v[138:141], v[232:235], v[76:79]
	v_mfma_f32_16x16x32_bf16 v[72:75], v[160:163], v[232:235], v[72:75]
	v_mfma_f32_16x16x32_bf16 v[124:127], v[156:159], v[212:215], v[124:127]
	v_mfma_f32_16x16x32_bf16 v[120:123], v[164:167], v[212:215], v[120:123]
	v_mfma_f32_16x16x32_bf16 v[108:111], v[156:159], v[220:223], v[108:111]
	v_mfma_f32_16x16x32_bf16 v[104:107], v[164:167], v[220:223], v[104:107]
	v_mfma_f32_16x16x32_bf16 v[92:95], v[156:159], v[228:231], v[92:95]
	v_mfma_f32_16x16x32_bf16 v[88:91], v[164:167], v[228:231], v[88:91]
	v_mfma_f32_16x16x32_bf16 v[76:79], v[156:159], v[236:239], v[76:79]
	v_mfma_f32_16x16x32_bf16 v[72:75], v[164:167], v[236:239], v[72:75]
	v_mfma_f32_16x16x32_bf16 v[116:119], v[168:171], v[208:211], v[116:119]
	v_mfma_f32_16x16x32_bf16 v[112:115], v[176:179], v[208:211], v[112:115]
	v_mfma_f32_16x16x32_bf16 v[100:103], v[168:171], v[216:219], v[100:103]
	v_mfma_f32_16x16x32_bf16 v[96:99], v[176:179], v[216:219], v[96:99]
	v_mfma_f32_16x16x32_bf16 v[84:87], v[168:171], v[224:227], v[84:87]
	v_mfma_f32_16x16x32_bf16 v[80:83], v[176:179], v[224:227], v[80:83]
	v_mfma_f32_16x16x32_bf16 v[68:71], v[168:171], v[232:235], v[68:71]
	v_mfma_f32_16x16x32_bf16 v[64:67], v[176:179], v[232:235], v[64:67]
	v_mfma_f32_16x16x32_bf16 v[116:119], v[172:175], v[212:215], v[116:119]
	v_mfma_f32_16x16x32_bf16 v[112:115], v[204:207], v[212:215], v[112:115]
	v_mfma_f32_16x16x32_bf16 v[100:103], v[172:175], v[220:223], v[100:103]
	v_mfma_f32_16x16x32_bf16 v[96:99], v[204:207], v[220:223], v[96:99]
	v_mfma_f32_16x16x32_bf16 v[84:87], v[172:175], v[228:231], v[84:87]
	v_mfma_f32_16x16x32_bf16 v[80:83], v[204:207], v[228:231], v[80:83]
	v_mfma_f32_16x16x32_bf16 v[68:71], v[172:175], v[236:239], v[68:71]
	v_mfma_f32_16x16x32_bf16 v[64:67], v[204:207], v[236:239], v[64:67]
	s_barrier
	s_add_i32 s4, s74, s28
	v_lshl_add_u64 v[180:181], v[180:181], 0, s[26:27]
	s_mov_b32 m0, s4
	ds_read_b128 v[208:211], v155 offset:49152
	ds_read_b128 v[212:215], v155 offset:50176
	ds_read_b128 v[216:219], v155 offset:51200
	ds_read_b128 v[220:223], v155 offset:52224
	ds_read_b128 v[224:227], v155 offset:53248
	ds_read_b128 v[228:231], v155 offset:54272
	ds_read_b128 v[232:235], v155 offset:55296
	ds_read_b128 v[236:239], v155 offset:56320
	global_load_lds_dwordx4 v[180:181], off
	s_add_i32 m0, s4, 0x2000
	s_add_u32 s4, s34, 0x20080
	v_lshl_add_u64 v[180:181], v[202:203], 0, s[26:27]
	s_addc_u32 s5, s35, 0
	s_add_i32 s34, s75, s28
	global_load_lds_dwordx4 v[180:181], off
	v_lshl_add_u64 v[180:181], s[4:5], 0, v[144:145]
	s_mov_b32 m0, s34
	s_nop 0
	global_load_lds_dwordx4 v[180:181], off
	v_lshl_add_u64 v[180:181], s[4:5], 0, v[132:133]
	s_add_i32 m0, s34, 0x2000
	s_nop 0
	global_load_lds_dwordx4 v[180:181], off
	v_lshl_add_u64 v[180:181], v[240:241], 0, s[26:27]
	s_mov_b32 m0, s68
	s_nop 0
	global_load_lds_dwordx4 v[180:181], off
	v_lshl_add_u64 v[180:181], v[242:243], 0, s[26:27]
	s_mov_b32 m0, s69
	s_nop 0
	global_load_lds_dwordx4 v[180:181], off
	s_add_i32 s73, s73, 2
	s_add_u32 s58, s58, 0x100
	s_addc_u32 s59, s59, 0
	s_add_u32 s71, s71, 0x100
	s_addc_u32 s72, s72, 0
	s_cmp_gt_u32 s73, 5
	s_waitcnt vmcnt(8)
	s_waitcnt lgkmcnt(0)
	s_barrier
	v_mfma_f32_16x16x32_bf16 v[60:63], v[138:141], v[208:211], v[60:63]
	v_mfma_f32_16x16x32_bf16 v[56:59], v[160:163], v[208:211], v[56:59]
	v_mfma_f32_16x16x32_bf16 v[44:47], v[138:141], v[216:219], v[44:47]
	v_mfma_f32_16x16x32_bf16 v[40:43], v[160:163], v[216:219], v[40:43]
	v_mfma_f32_16x16x32_bf16 v[28:31], v[138:141], v[224:227], v[28:31]
	v_mfma_f32_16x16x32_bf16 v[24:27], v[160:163], v[224:227], v[24:27]
	v_mfma_f32_16x16x32_bf16 v[12:15], v[138:141], v[232:235], v[12:15]
	v_mfma_f32_16x16x32_bf16 v[8:11], v[160:163], v[232:235], v[8:11]
	v_mfma_f32_16x16x32_bf16 v[60:63], v[156:159], v[212:215], v[60:63]
	v_mfma_f32_16x16x32_bf16 v[56:59], v[164:167], v[212:215], v[56:59]
	v_mfma_f32_16x16x32_bf16 v[44:47], v[156:159], v[220:223], v[44:47]
	v_mfma_f32_16x16x32_bf16 v[40:43], v[164:167], v[220:223], v[40:43]
	v_mfma_f32_16x16x32_bf16 v[28:31], v[156:159], v[228:231], v[28:31]
	v_mfma_f32_16x16x32_bf16 v[24:27], v[164:167], v[228:231], v[24:27]
	v_mfma_f32_16x16x32_bf16 v[12:15], v[156:159], v[236:239], v[12:15]
	v_mfma_f32_16x16x32_bf16 v[8:11], v[164:167], v[236:239], v[8:11]
	v_mfma_f32_16x16x32_bf16 v[52:55], v[168:171], v[208:211], v[52:55]
	v_mfma_f32_16x16x32_bf16 v[48:51], v[176:179], v[208:211], v[48:51]
	v_mfma_f32_16x16x32_bf16 v[36:39], v[168:171], v[216:219], v[36:39]
	v_mfma_f32_16x16x32_bf16 v[32:35], v[176:179], v[216:219], v[32:35]
	v_mfma_f32_16x16x32_bf16 v[20:23], v[168:171], v[224:227], v[20:23]
	v_mfma_f32_16x16x32_bf16 v[16:19], v[176:179], v[224:227], v[16:19]
	v_mfma_f32_16x16x32_bf16 v[4:7], v[168:171], v[232:235], v[4:7]
	v_mfma_f32_16x16x32_bf16 v[0:3], v[176:179], v[232:235], v[0:3]
	v_mfma_f32_16x16x32_bf16 v[52:55], v[172:175], v[212:215], v[52:55]
	v_mfma_f32_16x16x32_bf16 v[48:51], v[204:207], v[212:215], v[48:51]
	v_mfma_f32_16x16x32_bf16 v[36:39], v[172:175], v[220:223], v[36:39]
	v_mfma_f32_16x16x32_bf16 v[32:35], v[204:207], v[220:223], v[32:35]
	v_mfma_f32_16x16x32_bf16 v[20:23], v[172:175], v[228:231], v[20:23]
	v_mfma_f32_16x16x32_bf16 v[16:19], v[204:207], v[228:231], v[16:19]
	v_mfma_f32_16x16x32_bf16 v[4:7], v[172:175], v[236:239], v[4:7]
	v_mfma_f32_16x16x32_bf16 v[0:3], v[204:207], v[236:239], v[0:3]
	s_barrier
	s_cbranch_scc0 .LBB0_1093
	s_setprio 0
	s_and_b64 vcc, exec, s[46:47]
	s_cbranch_vccz .LBB0_1096
	s_barrier

.Lkprio_1117:
.LBB0_1117:
	v_add_u32_e32 v164, 0x10000, v143
	v_add_u32_e32 v180, 0x14000, v143
	ds_read_b128 v[138:141], v164
	ds_read_b128 v[156:159], v164 offset:1024
	ds_read_b128 v[160:163], v164 offset:2048
	ds_read_b128 v[164:167], v164 offset:3072
	ds_read_b128 v[168:171], v180
	ds_read_b128 v[172:175], v180 offset:1024
	ds_read_b128 v[176:179], v180 offset:2048
	ds_read_b128 v[204:207], v180 offset:3072
	ds_read_b128 v[208:211], v155
	ds_read_b128 v[212:215], v155 offset:1024
	ds_read_b128 v[216:219], v155 offset:2048
	ds_read_b128 v[220:223], v155 offset:3072
	ds_read_b128 v[224:227], v155 offset:4096
	ds_read_b128 v[228:231], v155 offset:5120
	ds_read_b128 v[232:235], v155 offset:6144
	ds_read_b128 v[236:239], v155 offset:7168
	s_add_u32 s4, s54, 0xfffe0080
	s_addc_u32 s5, s55, -1
	s_add_i32 s74, 0, 0x10000
	s_cmp_eq_u32 s73, 4
	s_cselect_b32 s59, s33, s5
	s_cselect_b32 s58, s36, s4
	s_cselect_b32 s35, s47, s72
	s_cselect_b32 s34, s49, s71
	s_add_i32 s75, 0, 0x14000
	v_lshl_add_u64 v[180:181], s[54:55], 0, v[134:135]
	s_add_i32 m0, s64, 0xc000
	s_nop 0
	global_load_lds_dwordx4 v[180:181], off
	v_lshl_add_u64 v[180:181], s[54:55], 0, v[136:137]
	s_add_i32 m0, s64, 0xe000
	s_nop 0
	global_load_lds_dwordx4 v[180:181], off
	s_waitcnt vmcnt(8)
	s_waitcnt lgkmcnt(0)
	s_barrier
	v_mfma_f32_16x16x32_bf16 v[124:127], v[138:141], v[208:211], v[124:127]
	v_mfma_f32_16x16x32_bf16 v[120:123], v[160:163], v[208:211], v[120:123]
	v_mfma_f32_16x16x32_bf16 v[108:111], v[138:141], v[216:219], v[108:111]
	v_mfma_f32_16x16x32_bf16 v[104:107], v[160:163], v[216:219], v[104:107]
	v_mfma_f32_16x16x32_bf16 v[92:95], v[138:141], v[224:227], v[92:95]
	v_mfma_f32_16x16x32_bf16 v[88:91], v[160:163], v[224:227], v[88:91]
	v_mfma_f32_16x16x32_bf16 v[76:79], v[138:141], v[232:235], v[76:79]
	v_mfma_f32_16x16x32_bf16 v[72:75], v[160:163], v[232:235], v[72:75]
	v_mfma_f32_16x16x32_bf16 v[124:127], v[156:159], v[212:215], v[124:127]
	v_mfma_f32_16x16x32_bf16 v[120:123], v[164:167], v[212:215], v[120:123]
	v_mfma_f32_16x16x32_bf16 v[108:111], v[156:159], v[220:223], v[108:111]
	v_mfma_f32_16x16x32_bf16 v[104:107], v[164:167], v[220:223], v[104:107]
	v_mfma_f32_16x16x32_bf16 v[92:95], v[156:159], v[228:231], v[92:95]
	v_mfma_f32_16x16x32_bf16 v[88:91], v[164:167], v[228:231], v[88:91]
	v_mfma_f32_16x16x32_bf16 v[76:79], v[156:159], v[236:239], v[76:79]
	v_mfma_f32_16x16x32_bf16 v[72:75], v[164:167], v[236:239], v[72:75]
	v_mfma_f32_16x16x32_bf16 v[116:119], v[168:171], v[208:211], v[116:119]
	v_mfma_f32_16x16x32_bf16 v[112:115], v[176:179], v[208:211], v[112:115]
	v_mfma_f32_16x16x32_bf16 v[100:103], v[168:171], v[216:219], v[100:103]
	v_mfma_f32_16x16x32_bf16 v[96:99], v[176:179], v[216:219], v[96:99]
	v_mfma_f32_16x16x32_bf16 v[84:87], v[168:171], v[224:227], v[84:87]
	v_mfma_f32_16x16x32_bf16 v[80:83], v[176:179], v[224:227], v[80:83]
	v_mfma_f32_16x16x32_bf16 v[68:71], v[168:171], v[232:235], v[68:71]
	v_mfma_f32_16x16x32_bf16 v[64:67], v[176:179], v[232:235], v[64:67]
	v_mfma_f32_16x16x32_bf16 v[116:119], v[172:175], v[212:215], v[116:119]
	v_mfma_f32_16x16x32_bf16 v[112:115], v[204:207], v[212:215], v[112:115]
	v_mfma_f32_16x16x32_bf16 v[100:103], v[172:175], v[220:223], v[100:103]
	v_mfma_f32_16x16x32_bf16 v[96:99], v[204:207], v[220:223], v[96:99]
	v_mfma_f32_16x16x32_bf16 v[84:87], v[172:175], v[228:231], v[84:87]
	v_mfma_f32_16x16x32_bf16 v[80:83], v[204:207], v[228:231], v[80:83]
	v_mfma_f32_16x16x32_bf16 v[68:71], v[172:175], v[236:239], v[68:71]
	v_mfma_f32_16x16x32_bf16 v[64:67], v[204:207], v[236:239], v[64:67]
	s_barrier
	s_add_i32 s4, s74, s63
	v_lshl_add_u64 v[180:181], s[34:35], 0, v[144:145]
	s_mov_b32 m0, s4
	ds_read_b128 v[208:211], v155 offset:16384
	ds_read_b128 v[212:215], v155 offset:17408
	ds_read_b128 v[216:219], v155 offset:18432
	ds_read_b128 v[220:223], v155 offset:19456
	ds_read_b128 v[224:227], v155 offset:20480
	ds_read_b128 v[228:231], v155 offset:21504
	ds_read_b128 v[232:235], v155 offset:22528
	ds_read_b128 v[236:239], v155 offset:23552
	global_load_lds_dwordx4 v[180:181], off
	s_add_i32 m0, s4, 0x2000
	s_add_u32 s4, s34, 0x20000
	v_lshl_add_u64 v[202:203], s[34:35], 0, v[132:133]
	s_addc_u32 s5, s35, 0
	s_add_i32 s74, s75, s63
	global_load_lds_dwordx4 v[202:203], off
	v_lshl_add_u64 v[240:241], s[4:5], 0, v[144:145]
	s_mov_b32 m0, s74
	v_lshl_add_u64 v[242:243], s[58:59], 0, v[130:131]
	global_load_lds_dwordx4 v[240:241], off
	v_lshl_add_u64 v[240:241], s[4:5], 0, v[132:133]
	s_add_i32 m0, s74, 0x2000
	s_nop 0
	global_load_lds_dwordx4 v[240:241], off
	v_lshl_add_u64 v[240:241], s[58:59], 0, v[128:129]
	s_mov_b32 m0, s64
	s_nop 0
	global_load_lds_dwordx4 v[240:241], off
	s_mov_b32 m0, s65
	s_nop 0
	global_load_lds_dwordx4 v[242:243], off
	s_waitcnt vmcnt(8)
	s_waitcnt lgkmcnt(0)
	s_barrier
	v_mfma_f32_16x16x32_bf16 v[60:63], v[138:141], v[208:211], v[60:63]
	v_mfma_f32_16x16x32_bf16 v[56:59], v[160:163], v[208:211], v[56:59]
	v_mfma_f32_16x16x32_bf16 v[44:47], v[138:141], v[216:219], v[44:47]
	v_mfma_f32_16x16x32_bf16 v[40:43], v[160:163], v[216:219], v[40:43]
	v_mfma_f32_16x16x32_bf16 v[28:31], v[138:141], v[224:227], v[28:31]
	v_mfma_f32_16x16x32_bf16 v[24:27], v[160:163], v[224:227], v[24:27]
	v_mfma_f32_16x16x32_bf16 v[12:15], v[138:141], v[232:235], v[12:15]
	v_mfma_f32_16x16x32_bf16 v[8:11], v[160:163], v[232:235], v[8:11]
	v_mfma_f32_16x16x32_bf16 v[60:63], v[156:159], v[212:215], v[60:63]
	v_mfma_f32_16x16x32_bf16 v[56:59], v[164:167], v[212:215], v[56:59]
	v_mfma_f32_16x16x32_bf16 v[44:47], v[156:159], v[220:223], v[44:47]
	v_mfma_f32_16x16x32_bf16 v[40:43], v[164:167], v[220:223], v[40:43]
	v_mfma_f32_16x16x32_bf16 v[28:31], v[156:159], v[228:231], v[28:31]
	v_mfma_f32_16x16x32_bf16 v[24:27], v[164:167], v[228:231], v[24:27]
	v_mfma_f32_16x16x32_bf16 v[12:15], v[156:159], v[236:239], v[12:15]
	v_mfma_f32_16x16x32_bf16 v[8:11], v[164:167], v[236:239], v[8:11]
	v_mfma_f32_16x16x32_bf16 v[52:55], v[168:171], v[208:211], v[52:55]
	v_mfma_f32_16x16x32_bf16 v[48:51], v[176:179], v[208:211], v[48:51]
	v_mfma_f32_16x16x32_bf16 v[36:39], v[168:171], v[216:219], v[36:39]
	v_mfma_f32_16x16x32_bf16 v[32:35], v[176:179], v[216:219], v[32:35]
	v_mfma_f32_16x16x32_bf16 v[20:23], v[168:171], v[224:227], v[20:23]
	v_mfma_f32_16x16x32_bf16 v[16:19], v[176:179], v[224:227], v[16:19]
	v_mfma_f32_16x16x32_bf16 v[4:7], v[168:171], v[232:235], v[4:7]
	v_mfma_f32_16x16x32_bf16 v[0:3], v[176:179], v[232:235], v[0:3]
	v_mfma_f32_16x16x32_bf16 v[52:55], v[172:175], v[212:215], v[52:55]
	v_mfma_f32_16x16x32_bf16 v[48:51], v[204:207], v[212:215], v[48:51]
	v_mfma_f32_16x16x32_bf16 v[36:39], v[172:175], v[220:223], v[36:39]
	v_mfma_f32_16x16x32_bf16 v[32:35], v[204:207], v[220:223], v[32:35]
	v_mfma_f32_16x16x32_bf16 v[20:23], v[172:175], v[228:231], v[20:23]
	v_mfma_f32_16x16x32_bf16 v[16:19], v[204:207], v[228:231], v[16:19]
	v_mfma_f32_16x16x32_bf16 v[4:7], v[172:175], v[236:239], v[4:7]
	v_mfma_f32_16x16x32_bf16 v[0:3], v[204:207], v[236:239], v[0:3]
	s_barrier
	v_add_u32_e32 v164, 0x18000, v143
	v_add_u32_e32 v204, 0x1c000, v143
	ds_read_b128 v[138:141], v164
	ds_read_b128 v[156:159], v164 offset:1024
	ds_read_b128 v[160:163], v164 offset:2048
	ds_read_b128 v[164:167], v164 offset:3072
	ds_read_b128 v[168:171], v204
	ds_read_b128 v[172:175], v204 offset:1024
	ds_read_b128 v[176:179], v204 offset:2048
	ds_read_b128 v[204:207], v204 offset:3072
	ds_read_b128 v[208:211], v155 offset:32768
	ds_read_b128 v[212:215], v155 offset:33792
	ds_read_b128 v[216:219], v155 offset:34816
	ds_read_b128 v[220:223], v155 offset:35840
	ds_read_b128 v[224:227], v155 offset:36864
	ds_read_b128 v[228:231], v155 offset:37888
	ds_read_b128 v[232:235], v155 offset:38912
	ds_read_b128 v[236:239], v155 offset:39936
	s_add_i32 s74, 0, 0x18000
	s_add_i32 s75, 0, 0x1c000
	s_add_u32 s4, s58, 0x20000
	s_addc_u32 s5, s59, 0
	s_mov_b32 m0, s66
	v_lshl_add_u64 v[244:245], s[4:5], 0, v[128:129]
	global_load_lds_dwordx4 v[244:245], off
	v_lshl_add_u64 v[244:245], s[4:5], 0, v[130:131]
	s_mov_b32 m0, s67
	s_nop 0
	global_load_lds_dwordx4 v[244:245], off
	s_waitcnt vmcnt(8)
	s_waitcnt lgkmcnt(0)
	s_barrier
	v_mfma_f32_16x16x32_bf16 v[124:127], v[138:141], v[208:211], v[124:127]
	v_mfma_f32_16x16x32_bf16 v[120:123], v[160:163], v[208:211], v[120:123]
	v_mfma_f32_16x16x32_bf16 v[108:111], v[138:141], v[216:219], v[108:111]
	v_mfma_f32_16x16x32_bf16 v[104:107], v[160:163], v[216:219], v[104:107]
	v_mfma_f32_16x16x32_bf16 v[92:95], v[138:141], v[224:227], v[92:95]
	v_mfma_f32_16x16x32_bf16 v[88:91], v[160:163], v[224:227], v[88:91]
	v_mfma_f32_16x16x32_bf16 v[76:79], v[138:141], v[232:235], v[76:79]
	v_mfma_f32_16x16x32_bf16 v[72:75], v[160:163], v[232:235], v[72:75]
	v_mfma_f32_16x16x32_bf16 v[124:127], v[156:159], v[212:215], v[124:127]
	v_mfma_f32_16x16x32_bf16 v[120:123], v[164:167], v[212:215], v[120:123]
	v_mfma_f32_16x16x32_bf16 v[108:111], v[156:159], v[220:223], v[108:111]
	v_mfma_f32_16x16x32_bf16 v[104:107], v[164:167], v[220:223], v[104:107]
	v_mfma_f32_16x16x32_bf16 v[92:95], v[156:159], v[228:231], v[92:95]
	v_mfma_f32_16x16x32_bf16 v[88:91], v[164:167], v[228:231], v[88:91]
	v_mfma_f32_16x16x32_bf16 v[76:79], v[156:159], v[236:239], v[76:79]
	v_mfma_f32_16x16x32_bf16 v[72:75], v[164:167], v[236:239], v[72:75]
	v_mfma_f32_16x16x32_bf16 v[116:119], v[168:171], v[208:211], v[116:119]
	v_mfma_f32_16x16x32_bf16 v[112:115], v[176:179], v[208:211], v[112:115]
	v_mfma_f32_16x16x32_bf16 v[100:103], v[168:171], v[216:219], v[100:103]
	v_mfma_f32_16x16x32_bf16 v[96:99], v[176:179], v[216:219], v[96:99]
	v_mfma_f32_16x16x32_bf16 v[84:87], v[168:171], v[224:227], v[84:87]
	v_mfma_f32_16x16x32_bf16 v[80:83], v[176:179], v[224:227], v[80:83]
	v_mfma_f32_16x16x32_bf16 v[68:71], v[168:171], v[232:235], v[68:71]
	v_mfma_f32_16x16x32_bf16 v[64:67], v[176:179], v[232:235], v[64:67]
	v_mfma_f32_16x16x32_bf16 v[116:119], v[172:175], v[212:215], v[116:119]
	v_mfma_f32_16x16x32_bf16 v[112:115], v[204:207], v[212:215], v[112:115]
	v_mfma_f32_16x16x32_bf16 v[100:103], v[172:175], v[220:223], v[100:103]
	v_mfma_f32_16x16x32_bf16 v[96:99], v[204:207], v[220:223], v[96:99]
	v_mfma_f32_16x16x32_bf16 v[84:87], v[172:175], v[228:231], v[84:87]
	v_mfma_f32_16x16x32_bf16 v[80:83], v[204:207], v[228:231], v[80:83]
	v_mfma_f32_16x16x32_bf16 v[68:71], v[172:175], v[236:239], v[68:71]
	v_mfma_f32_16x16x32_bf16 v[64:67], v[204:207], v[236:239], v[64:67]
	s_barrier
	s_add_i32 s4, s74, s63
	v_lshl_add_u64 v[180:181], v[180:181], 0, s[26:27]
	s_mov_b32 m0, s4
	ds_read_b128 v[208:211], v155 offset:49152
	ds_read_b128 v[212:215], v155 offset:50176
	ds_read_b128 v[216:219], v155 offset:51200
	ds_read_b128 v[220:223], v155 offset:52224
	ds_read_b128 v[224:227], v155 offset:53248
	ds_read_b128 v[228:231], v155 offset:54272
	ds_read_b128 v[232:235], v155 offset:55296
	ds_read_b128 v[236:239], v155 offset:56320
	global_load_lds_dwordx4 v[180:181], off
	s_add_i32 m0, s4, 0x2000
	s_add_u32 s4, s34, 0x20080
	v_lshl_add_u64 v[180:181], v[202:203], 0, s[26:27]
	s_addc_u32 s5, s35, 0
	s_add_i32 s34, s75, s63
	global_load_lds_dwordx4 v[180:181], off
	v_lshl_add_u64 v[180:181], s[4:5], 0, v[144:145]
	s_mov_b32 m0, s34
	s_nop 0
	global_load_lds_dwordx4 v[180:181], off
	v_lshl_add_u64 v[180:181], s[4:5], 0, v[132:133]
	s_add_i32 m0, s34, 0x2000
	s_nop 0
	global_load_lds_dwordx4 v[180:181], off
	v_lshl_add_u64 v[180:181], v[240:241], 0, s[26:27]
	s_mov_b32 m0, s68
	s_nop 0
	global_load_lds_dwordx4 v[180:181], off
	v_lshl_add_u64 v[180:181], v[242:243], 0, s[26:27]
	s_mov_b32 m0, s69
	s_nop 0
	global_load_lds_dwordx4 v[180:181], off
	s_add_i32 s73, s73, 2
	s_add_u32 s54, s54, 0x100
	s_addc_u32 s55, s55, 0
	s_add_u32 s71, s71, 0x100
	s_addc_u32 s72, s72, 0
	s_cmp_gt_u32 s73, 5
	s_waitcnt vmcnt(8)
	s_waitcnt lgkmcnt(0)
	s_barrier
	v_mfma_f32_16x16x32_bf16 v[60:63], v[138:141], v[208:211], v[60:63]
	v_mfma_f32_16x16x32_bf16 v[56:59], v[160:163], v[208:211], v[56:59]
	v_mfma_f32_16x16x32_bf16 v[44:47], v[138:141], v[216:219], v[44:47]
	v_mfma_f32_16x16x32_bf16 v[40:43], v[160:163], v[216:219], v[40:43]
	v_mfma_f32_16x16x32_bf16 v[28:31], v[138:141], v[224:227], v[28:31]
	v_mfma_f32_16x16x32_bf16 v[24:27], v[160:163], v[224:227], v[24:27]
	v_mfma_f32_16x16x32_bf16 v[12:15], v[138:141], v[232:235], v[12:15]
	v_mfma_f32_16x16x32_bf16 v[8:11], v[160:163], v[232:235], v[8:11]
	v_mfma_f32_16x16x32_bf16 v[60:63], v[156:159], v[212:215], v[60:63]
	v_mfma_f32_16x16x32_bf16 v[56:59], v[164:167], v[212:215], v[56:59]
	v_mfma_f32_16x16x32_bf16 v[44:47], v[156:159], v[220:223], v[44:47]
	v_mfma_f32_16x16x32_bf16 v[40:43], v[164:167], v[220:223], v[40:43]
	v_mfma_f32_16x16x32_bf16 v[28:31], v[156:159], v[228:231], v[28:31]
	v_mfma_f32_16x16x32_bf16 v[24:27], v[164:167], v[228:231], v[24:27]
	v_mfma_f32_16x16x32_bf16 v[12:15], v[156:159], v[236:239], v[12:15]
	v_mfma_f32_16x16x32_bf16 v[8:11], v[164:167], v[236:239], v[8:11]
	v_mfma_f32_16x16x32_bf16 v[52:55], v[168:171], v[208:211], v[52:55]
	v_mfma_f32_16x16x32_bf16 v[48:51], v[176:179], v[208:211], v[48:51]
	v_mfma_f32_16x16x32_bf16 v[36:39], v[168:171], v[216:219], v[36:39]
	v_mfma_f32_16x16x32_bf16 v[32:35], v[176:179], v[216:219], v[32:35]
	v_mfma_f32_16x16x32_bf16 v[20:23], v[168:171], v[224:227], v[20:23]
	v_mfma_f32_16x16x32_bf16 v[16:19], v[176:179], v[224:227], v[16:19]
	v_mfma_f32_16x16x32_bf16 v[4:7], v[168:171], v[232:235], v[4:7]
	v_mfma_f32_16x16x32_bf16 v[0:3], v[176:179], v[232:235], v[0:3]
	v_mfma_f32_16x16x32_bf16 v[52:55], v[172:175], v[212:215], v[52:55]
	v_mfma_f32_16x16x32_bf16 v[48:51], v[204:207], v[212:215], v[48:51]
	v_mfma_f32_16x16x32_bf16 v[36:39], v[172:175], v[220:223], v[36:39]
	v_mfma_f32_16x16x32_bf16 v[32:35], v[204:207], v[220:223], v[32:35]
	v_mfma_f32_16x16x32_bf16 v[20:23], v[172:175], v[228:231], v[20:23]
	v_mfma_f32_16x16x32_bf16 v[16:19], v[204:207], v[228:231], v[16:19]
	v_mfma_f32_16x16x32_bf16 v[4:7], v[172:175], v[236:239], v[4:7]
	v_mfma_f32_16x16x32_bf16 v[0:3], v[204:207], v[236:239], v[0:3]
	s_barrier
	s_cbranch_scc0 .LBB0_1117
	s_setprio 0
	s_and_b64 vcc, exec, s[44:45]
	s_cbranch_vccz .LBB0_1120
	s_barrier

.Lkprio_1207:
.LBB0_1207:
	v_add_u32_e32 v142, 0x10000, v160
	ds_read_b128 v[138:141], v142
	ds_read_b128 v[154:157], v142 offset:1024
	ds_read_b128 v[172:175], v142 offset:2048
	ds_read_b128 v[176:179], v142 offset:3072
	v_add_u32_e32 v142, 0x14000, v160
	ds_read_b128 v[204:207], v142
	ds_read_b128 v[208:211], v142 offset:1024
	ds_read_b128 v[212:215], v142 offset:2048
	ds_read_b128 v[216:219], v142 offset:3072
	ds_read_b128 v[220:223], v170
	ds_read_b128 v[224:227], v170 offset:1024
	ds_read_b128 v[228:231], v170 offset:2048
	ds_read_b128 v[232:235], v170 offset:3072
	ds_read_b128 v[236:239], v170 offset:4096
	ds_read_b128 v[240:243], v170 offset:5120
	ds_read_b128 v[244:247], v170 offset:6144
	ds_read_b128 v[248:251], v170 offset:7168
	s_add_u32 s62, s60, 0x100
	s_addc_u32 s63, s61, 0
	s_add_i32 s4, 0, 0x10000
	s_cmp_eq_u32 s29, 12
	s_cselect_b32 s65, s55, s63
	s_cselect_b32 s64, s54, s62
	s_cselect_b32 s35, s59, s28
	s_cselect_b32 s34, s58, s3
	s_add_i32 s45, 0, 0x14000
	v_lshl_add_u64 v[142:143], s[60:61], 0, v[134:135]
	s_add_i32 m0, s69, 0xc000
	s_nop 0
	global_load_lds_dwordx4 v[142:143], off
	v_lshl_add_u64 v[142:143], s[60:61], 0, v[136:137]
	s_add_i32 m0, s69, 0xe000
	s_nop 0
	global_load_lds_dwordx4 v[142:143], off
	s_waitcnt vmcnt(8)
	s_waitcnt lgkmcnt(0)
	s_barrier
	v_mfma_f32_16x16x32_bf16 v[124:127], v[138:141], v[220:223], v[124:127]
	v_mfma_f32_16x16x32_bf16 v[120:123], v[172:175], v[220:223], v[120:123]
	v_mfma_f32_16x16x32_bf16 v[108:111], v[138:141], v[228:231], v[108:111]
	v_mfma_f32_16x16x32_bf16 v[104:107], v[172:175], v[228:231], v[104:107]
	v_mfma_f32_16x16x32_bf16 v[92:95], v[138:141], v[236:239], v[92:95]
	v_mfma_f32_16x16x32_bf16 v[88:91], v[172:175], v[236:239], v[88:91]
	v_mfma_f32_16x16x32_bf16 v[76:79], v[138:141], v[244:247], v[76:79]
	v_mfma_f32_16x16x32_bf16 v[72:75], v[172:175], v[244:247], v[72:75]
	v_mfma_f32_16x16x32_bf16 v[124:127], v[154:157], v[224:227], v[124:127]
	v_mfma_f32_16x16x32_bf16 v[120:123], v[176:179], v[224:227], v[120:123]
	v_mfma_f32_16x16x32_bf16 v[108:111], v[154:157], v[232:235], v[108:111]
	v_mfma_f32_16x16x32_bf16 v[104:107], v[176:179], v[232:235], v[104:107]
	v_mfma_f32_16x16x32_bf16 v[92:95], v[154:157], v[240:243], v[92:95]
	v_mfma_f32_16x16x32_bf16 v[88:91], v[176:179], v[240:243], v[88:91]
	v_mfma_f32_16x16x32_bf16 v[76:79], v[154:157], v[248:251], v[76:79]
	v_mfma_f32_16x16x32_bf16 v[72:75], v[176:179], v[248:251], v[72:75]
	v_mfma_f32_16x16x32_bf16 v[116:119], v[204:207], v[220:223], v[116:119]
	v_mfma_f32_16x16x32_bf16 v[112:115], v[212:215], v[220:223], v[112:115]
	v_mfma_f32_16x16x32_bf16 v[100:103], v[204:207], v[228:231], v[100:103]
	v_mfma_f32_16x16x32_bf16 v[96:99], v[212:215], v[228:231], v[96:99]
	v_mfma_f32_16x16x32_bf16 v[84:87], v[204:207], v[236:239], v[84:87]
	v_mfma_f32_16x16x32_bf16 v[80:83], v[212:215], v[236:239], v[80:83]
	v_mfma_f32_16x16x32_bf16 v[68:71], v[204:207], v[244:247], v[68:71]
	v_mfma_f32_16x16x32_bf16 v[64:67], v[212:215], v[244:247], v[64:67]
	v_mfma_f32_16x16x32_bf16 v[116:119], v[208:211], v[224:227], v[116:119]
	v_mfma_f32_16x16x32_bf16 v[112:115], v[216:219], v[224:227], v[112:115]
	v_mfma_f32_16x16x32_bf16 v[100:103], v[208:211], v[232:235], v[100:103]
	v_mfma_f32_16x16x32_bf16 v[96:99], v[216:219], v[232:235], v[96:99]
	v_mfma_f32_16x16x32_bf16 v[84:87], v[208:211], v[240:243], v[84:87]
	v_mfma_f32_16x16x32_bf16 v[80:83], v[216:219], v[240:243], v[80:83]
	v_mfma_f32_16x16x32_bf16 v[68:71], v[208:211], v[248:251], v[68:71]
	v_mfma_f32_16x16x32_bf16 v[64:67], v[216:219], v[248:251], v[64:67]
	s_barrier
	s_add_i32 s4, s4, s33
	v_lshl_add_u64 v[142:143], s[34:35], 0, v[128:129]
	s_mov_b32 m0, s4
	ds_read_b128 v[220:223], v170 offset:16384
	ds_read_b128 v[224:227], v170 offset:17408
	ds_read_b128 v[228:231], v170 offset:18432
	ds_read_b128 v[232:235], v170 offset:19456
	ds_read_b128 v[236:239], v170 offset:20480
	ds_read_b128 v[240:243], v170 offset:21504
	ds_read_b128 v[244:247], v170 offset:22528
	ds_read_b128 v[248:251], v170 offset:23552
	global_load_lds_dwordx4 v[142:143], off
	s_add_i32 m0, s4, 0x2000
	s_add_u32 s4, s34, 0x40000
	v_lshl_add_u64 v[158:159], s[34:35], 0, v[130:131]
	s_addc_u32 s5, s35, 0
	s_add_i32 s45, s45, s33
	global_load_lds_dwordx4 v[158:159], off
	v_lshl_add_u64 v[180:181], s[4:5], 0, v[128:129]
	s_mov_b32 m0, s45
	v_lshl_add_u64 v[202:203], s[64:65], 0, v[130:131]
	global_load_lds_dwordx4 v[180:181], off
	v_lshl_add_u64 v[180:181], s[4:5], 0, v[130:131]
	s_add_i32 m0, s45, 0x2000
	s_nop 0
	global_load_lds_dwordx4 v[180:181], off
	v_lshl_add_u64 v[180:181], s[64:65], 0, v[128:129]
	s_mov_b32 m0, s69
	s_nop 0
	global_load_lds_dwordx4 v[180:181], off
	s_mov_b32 m0, s70
	s_nop 0
	global_load_lds_dwordx4 v[202:203], off
	s_waitcnt vmcnt(8)
	s_waitcnt lgkmcnt(0)
	s_barrier
	v_mfma_f32_16x16x32_bf16 v[60:63], v[138:141], v[220:223], v[60:63]
	v_mfma_f32_16x16x32_bf16 v[56:59], v[172:175], v[220:223], v[56:59]
	v_mfma_f32_16x16x32_bf16 v[44:47], v[138:141], v[228:231], v[44:47]
	v_mfma_f32_16x16x32_bf16 v[40:43], v[172:175], v[228:231], v[40:43]
	v_mfma_f32_16x16x32_bf16 v[28:31], v[138:141], v[236:239], v[28:31]
	v_mfma_f32_16x16x32_bf16 v[24:27], v[172:175], v[236:239], v[24:27]
	v_mfma_f32_16x16x32_bf16 v[12:15], v[138:141], v[244:247], v[12:15]
	v_mfma_f32_16x16x32_bf16 v[8:11], v[172:175], v[244:247], v[8:11]
	v_mfma_f32_16x16x32_bf16 v[60:63], v[154:157], v[224:227], v[60:63]
	v_mfma_f32_16x16x32_bf16 v[56:59], v[176:179], v[224:227], v[56:59]
	v_mfma_f32_16x16x32_bf16 v[44:47], v[154:157], v[232:235], v[44:47]
	v_mfma_f32_16x16x32_bf16 v[40:43], v[176:179], v[232:235], v[40:43]
	v_mfma_f32_16x16x32_bf16 v[28:31], v[154:157], v[240:243], v[28:31]
	v_mfma_f32_16x16x32_bf16 v[24:27], v[176:179], v[240:243], v[24:27]
	v_mfma_f32_16x16x32_bf16 v[12:15], v[154:157], v[248:251], v[12:15]
	v_mfma_f32_16x16x32_bf16 v[8:11], v[176:179], v[248:251], v[8:11]
	v_mfma_f32_16x16x32_bf16 v[52:55], v[204:207], v[220:223], v[52:55]
	v_mfma_f32_16x16x32_bf16 v[48:51], v[212:215], v[220:223], v[48:51]
	v_mfma_f32_16x16x32_bf16 v[36:39], v[204:207], v[228:231], v[36:39]
	v_mfma_f32_16x16x32_bf16 v[32:35], v[212:215], v[228:231], v[32:35]
	v_mfma_f32_16x16x32_bf16 v[20:23], v[204:207], v[236:239], v[20:23]
	v_mfma_f32_16x16x32_bf16 v[16:19], v[212:215], v[236:239], v[16:19]
	v_mfma_f32_16x16x32_bf16 v[4:7], v[204:207], v[244:247], v[4:7]
	v_mfma_f32_16x16x32_bf16 v[0:3], v[212:215], v[244:247], v[0:3]
	v_mfma_f32_16x16x32_bf16 v[52:55], v[208:211], v[224:227], v[52:55]
	v_mfma_f32_16x16x32_bf16 v[48:51], v[216:219], v[224:227], v[48:51]
	v_mfma_f32_16x16x32_bf16 v[36:39], v[208:211], v[232:235], v[36:39]
	v_mfma_f32_16x16x32_bf16 v[32:35], v[216:219], v[232:235], v[32:35]
	v_mfma_f32_16x16x32_bf16 v[20:23], v[208:211], v[240:243], v[20:23]
	v_mfma_f32_16x16x32_bf16 v[16:19], v[216:219], v[240:243], v[16:19]
	v_mfma_f32_16x16x32_bf16 v[4:7], v[208:211], v[248:251], v[4:7]
	v_mfma_f32_16x16x32_bf16 v[0:3], v[216:219], v[248:251], v[0:3]
	s_barrier
	v_add_u32_e32 v144, 0x18000, v160
	ds_read_b128 v[138:141], v144
	ds_read_b128 v[154:157], v144 offset:1024
	ds_read_b128 v[172:175], v144 offset:2048
	ds_read_b128 v[176:179], v144 offset:3072
	v_add_u32_e32 v144, 0x1c000, v160
	ds_read_b128 v[204:207], v144
	ds_read_b128 v[208:211], v144 offset:1024
	ds_read_b128 v[212:215], v144 offset:2048
	ds_read_b128 v[216:219], v144 offset:3072
	ds_read_b128 v[220:223], v170 offset:32768
	ds_read_b128 v[224:227], v170 offset:33792
	ds_read_b128 v[228:231], v170 offset:34816
	ds_read_b128 v[232:235], v170 offset:35840
	ds_read_b128 v[236:239], v170 offset:36864
	ds_read_b128 v[240:243], v170 offset:37888
	ds_read_b128 v[244:247], v170 offset:38912
	ds_read_b128 v[248:251], v170 offset:39936
	s_add_i32 s45, 0, 0x18000
	s_add_i32 s51, 0, 0x1c000
	s_add_u32 s4, s64, 0x40000
	s_addc_u32 s5, s65, 0
	s_mov_b32 m0, s71
	v_lshl_add_u64 v[252:253], s[4:5], 0, v[128:129]
	global_load_lds_dwordx4 v[252:253], off
	v_lshl_add_u64 v[252:253], s[4:5], 0, v[130:131]
	s_mov_b32 m0, s72
	s_nop 0
	global_load_lds_dwordx4 v[252:253], off
	s_waitcnt vmcnt(8)
	s_waitcnt lgkmcnt(0)
	s_barrier
	v_mfma_f32_16x16x32_bf16 v[124:127], v[138:141], v[220:223], v[124:127]
	v_mfma_f32_16x16x32_bf16 v[120:123], v[172:175], v[220:223], v[120:123]
	v_mfma_f32_16x16x32_bf16 v[108:111], v[138:141], v[228:231], v[108:111]
	v_mfma_f32_16x16x32_bf16 v[104:107], v[172:175], v[228:231], v[104:107]
	v_mfma_f32_16x16x32_bf16 v[92:95], v[138:141], v[236:239], v[92:95]
	v_mfma_f32_16x16x32_bf16 v[88:91], v[172:175], v[236:239], v[88:91]
	v_mfma_f32_16x16x32_bf16 v[76:79], v[138:141], v[244:247], v[76:79]
	v_mfma_f32_16x16x32_bf16 v[72:75], v[172:175], v[244:247], v[72:75]
	v_mfma_f32_16x16x32_bf16 v[124:127], v[154:157], v[224:227], v[124:127]
	v_mfma_f32_16x16x32_bf16 v[120:123], v[176:179], v[224:227], v[120:123]
	v_mfma_f32_16x16x32_bf16 v[108:111], v[154:157], v[232:235], v[108:111]
	v_mfma_f32_16x16x32_bf16 v[104:107], v[176:179], v[232:235], v[104:107]
	v_mfma_f32_16x16x32_bf16 v[92:95], v[154:157], v[240:243], v[92:95]
	v_mfma_f32_16x16x32_bf16 v[88:91], v[176:179], v[240:243], v[88:91]
	v_mfma_f32_16x16x32_bf16 v[76:79], v[154:157], v[248:251], v[76:79]
	v_mfma_f32_16x16x32_bf16 v[72:75], v[176:179], v[248:251], v[72:75]
	v_mfma_f32_16x16x32_bf16 v[116:119], v[204:207], v[220:223], v[116:119]
	v_mfma_f32_16x16x32_bf16 v[112:115], v[212:215], v[220:223], v[112:115]
	v_mfma_f32_16x16x32_bf16 v[100:103], v[204:207], v[228:231], v[100:103]
	v_mfma_f32_16x16x32_bf16 v[96:99], v[212:215], v[228:231], v[96:99]
	v_mfma_f32_16x16x32_bf16 v[84:87], v[204:207], v[236:239], v[84:87]
	v_mfma_f32_16x16x32_bf16 v[80:83], v[212:215], v[236:239], v[80:83]
	v_mfma_f32_16x16x32_bf16 v[68:71], v[204:207], v[244:247], v[68:71]
	v_mfma_f32_16x16x32_bf16 v[64:67], v[212:215], v[244:247], v[64:67]
	v_mfma_f32_16x16x32_bf16 v[116:119], v[208:211], v[224:227], v[116:119]
	v_mfma_f32_16x16x32_bf16 v[112:115], v[216:219], v[224:227], v[112:115]
	v_mfma_f32_16x16x32_bf16 v[100:103], v[208:211], v[232:235], v[100:103]
	v_mfma_f32_16x16x32_bf16 v[96:99], v[216:219], v[232:235], v[96:99]
	v_mfma_f32_16x16x32_bf16 v[84:87], v[208:211], v[240:243], v[84:87]
	v_mfma_f32_16x16x32_bf16 v[80:83], v[216:219], v[240:243], v[80:83]
	v_mfma_f32_16x16x32_bf16 v[68:71], v[208:211], v[248:251], v[68:71]
	v_mfma_f32_16x16x32_bf16 v[64:67], v[216:219], v[248:251], v[64:67]
	s_barrier
	s_add_i32 s4, s45, s33
	v_lshl_add_u64 v[142:143], v[142:143], 0, s[26:27]
	s_mov_b32 m0, s4
	ds_read_b128 v[220:223], v170 offset:49152
	ds_read_b128 v[224:227], v170 offset:50176
	ds_read_b128 v[228:231], v170 offset:51200
	ds_read_b128 v[232:235], v170 offset:52224
	ds_read_b128 v[236:239], v170 offset:53248
	ds_read_b128 v[240:243], v170 offset:54272
	ds_read_b128 v[244:247], v170 offset:55296
	ds_read_b128 v[248:251], v170 offset:56320
	global_load_lds_dwordx4 v[142:143], off
	s_add_i32 m0, s4, 0x2000
	s_add_u32 s4, s34, 0x40080
	v_lshl_add_u64 v[142:143], v[158:159], 0, s[26:27]
	s_addc_u32 s5, s35, 0
	s_add_i32 s34, s51, s33
	global_load_lds_dwordx4 v[142:143], off
	v_lshl_add_u64 v[142:143], s[4:5], 0, v[128:129]
	s_mov_b32 m0, s34
	s_nop 0
	global_load_lds_dwordx4 v[142:143], off
	v_lshl_add_u64 v[142:143], s[4:5], 0, v[130:131]
	s_add_i32 m0, s34, 0x2000
	s_nop 0
	global_load_lds_dwordx4 v[142:143], off
	v_lshl_add_u64 v[142:143], v[180:181], 0, s[26:27]
	s_mov_b32 m0, s73
	s_nop 0
	global_load_lds_dwordx4 v[142:143], off
	v_lshl_add_u64 v[142:143], v[202:203], 0, s[26:27]
	s_mov_b32 m0, s74
	s_nop 0
	global_load_lds_dwordx4 v[142:143], off
	s_add_i32 s29, s29, 2
	s_add_u32 s3, s3, 0x100
	s_addc_u32 s28, s28, 0
	s_cmp_gt_u32 s29, 13
	s_mov_b64 s[60:61], s[62:63]
	s_waitcnt vmcnt(8)
	s_waitcnt lgkmcnt(0)
	s_barrier
	v_mfma_f32_16x16x32_bf16 v[60:63], v[138:141], v[220:223], v[60:63]
	v_mfma_f32_16x16x32_bf16 v[56:59], v[172:175], v[220:223], v[56:59]
	v_mfma_f32_16x16x32_bf16 v[44:47], v[138:141], v[228:231], v[44:47]
	v_mfma_f32_16x16x32_bf16 v[40:43], v[172:175], v[228:231], v[40:43]
	v_mfma_f32_16x16x32_bf16 v[28:31], v[138:141], v[236:239], v[28:31]
	v_mfma_f32_16x16x32_bf16 v[24:27], v[172:175], v[236:239], v[24:27]
	v_mfma_f32_16x16x32_bf16 v[12:15], v[138:141], v[244:247], v[12:15]
	v_mfma_f32_16x16x32_bf16 v[8:11], v[172:175], v[244:247], v[8:11]
	v_mfma_f32_16x16x32_bf16 v[60:63], v[154:157], v[224:227], v[60:63]
	v_mfma_f32_16x16x32_bf16 v[56:59], v[176:179], v[224:227], v[56:59]
	v_mfma_f32_16x16x32_bf16 v[44:47], v[154:157], v[232:235], v[44:47]
	v_mfma_f32_16x16x32_bf16 v[40:43], v[176:179], v[232:235], v[40:43]
	v_mfma_f32_16x16x32_bf16 v[28:31], v[154:157], v[240:243], v[28:31]
	v_mfma_f32_16x16x32_bf16 v[24:27], v[176:179], v[240:243], v[24:27]
	v_mfma_f32_16x16x32_bf16 v[12:15], v[154:157], v[248:251], v[12:15]
	v_mfma_f32_16x16x32_bf16 v[8:11], v[176:179], v[248:251], v[8:11]
	v_mfma_f32_16x16x32_bf16 v[52:55], v[204:207], v[220:223], v[52:55]
	v_mfma_f32_16x16x32_bf16 v[48:51], v[212:215], v[220:223], v[48:51]
	v_mfma_f32_16x16x32_bf16 v[36:39], v[204:207], v[228:231], v[36:39]
	v_mfma_f32_16x16x32_bf16 v[32:35], v[212:215], v[228:231], v[32:35]
	v_mfma_f32_16x16x32_bf16 v[20:23], v[204:207], v[236:239], v[20:23]
	v_mfma_f32_16x16x32_bf16 v[16:19], v[212:215], v[236:239], v[16:19]
	v_mfma_f32_16x16x32_bf16 v[4:7], v[204:207], v[244:247], v[4:7]
	v_mfma_f32_16x16x32_bf16 v[0:3], v[212:215], v[244:247], v[0:3]
	v_mfma_f32_16x16x32_bf16 v[52:55], v[208:211], v[224:227], v[52:55]
	v_mfma_f32_16x16x32_bf16 v[48:51], v[216:219], v[224:227], v[48:51]
	v_mfma_f32_16x16x32_bf16 v[36:39], v[208:211], v[232:235], v[36:39]
	v_mfma_f32_16x16x32_bf16 v[32:35], v[216:219], v[232:235], v[32:35]
	v_mfma_f32_16x16x32_bf16 v[20:23], v[208:211], v[240:243], v[20:23]
	v_mfma_f32_16x16x32_bf16 v[16:19], v[216:219], v[240:243], v[16:19]
	v_mfma_f32_16x16x32_bf16 v[4:7], v[208:211], v[248:251], v[4:7]
	v_mfma_f32_16x16x32_bf16 v[0:3], v[216:219], v[248:251], v[0:3]
	s_barrier
	s_cbranch_scc0 .LBB0_1207
	s_setprio 0
	s_and_b64 vcc, exec, s[48:49]
	s_cbranch_vccz .LBB0_1210
	s_barrier

.Lkprio_1305:
.LBB0_1305:
	v_add_u32_e32 v164, 0x10000, v143
	v_add_u32_e32 v180, 0x14000, v143
	ds_read_b128 v[138:141], v164
	ds_read_b128 v[156:159], v164 offset:1024
	ds_read_b128 v[160:163], v164 offset:2048
	ds_read_b128 v[164:167], v164 offset:3072
	ds_read_b128 v[168:171], v180
	ds_read_b128 v[172:175], v180 offset:1024
	ds_read_b128 v[176:179], v180 offset:2048
	ds_read_b128 v[204:207], v180 offset:3072
	ds_read_b128 v[208:211], v155
	ds_read_b128 v[212:215], v155 offset:1024
	ds_read_b128 v[216:219], v155 offset:2048
	ds_read_b128 v[220:223], v155 offset:3072
	ds_read_b128 v[224:227], v155 offset:4096
	ds_read_b128 v[228:231], v155 offset:5120
	ds_read_b128 v[232:235], v155 offset:6144
	ds_read_b128 v[236:239], v155 offset:7168
	s_add_u32 s4, s2, 0xfffc0080
	s_addc_u32 s5, s3, -1
	s_add_i32 s74, 0, 0x10000
	s_cmp_eq_u32 s73, 12
	s_cselect_b32 s61, s36, s5
	s_cselect_b32 s60, s51, s4
	s_cselect_b32 s35, s49, s72
	s_cselect_b32 s34, s70, s71
	s_add_i32 s75, 0, 0x14000
	v_lshl_add_u64 v[180:181], s[2:3], 0, v[134:135]
	s_add_i32 m0, s59, 0xc000
	s_nop 0
	global_load_lds_dwordx4 v[180:181], off
	v_lshl_add_u64 v[180:181], s[2:3], 0, v[136:137]
	s_add_i32 m0, s59, 0xe000
	s_nop 0
	global_load_lds_dwordx4 v[180:181], off
	s_waitcnt vmcnt(8)
	s_waitcnt lgkmcnt(0)
	s_barrier
	v_mfma_f32_16x16x32_bf16 v[124:127], v[138:141], v[208:211], v[124:127]
	v_mfma_f32_16x16x32_bf16 v[120:123], v[160:163], v[208:211], v[120:123]
	v_mfma_f32_16x16x32_bf16 v[108:111], v[138:141], v[216:219], v[108:111]
	v_mfma_f32_16x16x32_bf16 v[104:107], v[160:163], v[216:219], v[104:107]
	v_mfma_f32_16x16x32_bf16 v[92:95], v[138:141], v[224:227], v[92:95]
	v_mfma_f32_16x16x32_bf16 v[88:91], v[160:163], v[224:227], v[88:91]
	v_mfma_f32_16x16x32_bf16 v[76:79], v[138:141], v[232:235], v[76:79]
	v_mfma_f32_16x16x32_bf16 v[72:75], v[160:163], v[232:235], v[72:75]
	v_mfma_f32_16x16x32_bf16 v[124:127], v[156:159], v[212:215], v[124:127]
	v_mfma_f32_16x16x32_bf16 v[120:123], v[164:167], v[212:215], v[120:123]
	v_mfma_f32_16x16x32_bf16 v[108:111], v[156:159], v[220:223], v[108:111]
	v_mfma_f32_16x16x32_bf16 v[104:107], v[164:167], v[220:223], v[104:107]
	v_mfma_f32_16x16x32_bf16 v[92:95], v[156:159], v[228:231], v[92:95]
	v_mfma_f32_16x16x32_bf16 v[88:91], v[164:167], v[228:231], v[88:91]
	v_mfma_f32_16x16x32_bf16 v[76:79], v[156:159], v[236:239], v[76:79]
	v_mfma_f32_16x16x32_bf16 v[72:75], v[164:167], v[236:239], v[72:75]
	v_mfma_f32_16x16x32_bf16 v[116:119], v[168:171], v[208:211], v[116:119]
	v_mfma_f32_16x16x32_bf16 v[112:115], v[176:179], v[208:211], v[112:115]
	v_mfma_f32_16x16x32_bf16 v[100:103], v[168:171], v[216:219], v[100:103]
	v_mfma_f32_16x16x32_bf16 v[96:99], v[176:179], v[216:219], v[96:99]
	v_mfma_f32_16x16x32_bf16 v[84:87], v[168:171], v[224:227], v[84:87]
	v_mfma_f32_16x16x32_bf16 v[80:83], v[176:179], v[224:227], v[80:83]
	v_mfma_f32_16x16x32_bf16 v[68:71], v[168:171], v[232:235], v[68:71]
	v_mfma_f32_16x16x32_bf16 v[64:67], v[176:179], v[232:235], v[64:67]
	v_mfma_f32_16x16x32_bf16 v[116:119], v[172:175], v[212:215], v[116:119]
	v_mfma_f32_16x16x32_bf16 v[112:115], v[204:207], v[212:215], v[112:115]
	v_mfma_f32_16x16x32_bf16 v[100:103], v[172:175], v[220:223], v[100:103]
	v_mfma_f32_16x16x32_bf16 v[96:99], v[204:207], v[220:223], v[96:99]
	v_mfma_f32_16x16x32_bf16 v[84:87], v[172:175], v[228:231], v[84:87]
	v_mfma_f32_16x16x32_bf16 v[80:83], v[204:207], v[228:231], v[80:83]
	v_mfma_f32_16x16x32_bf16 v[68:71], v[172:175], v[236:239], v[68:71]
	v_mfma_f32_16x16x32_bf16 v[64:67], v[204:207], v[236:239], v[64:67]
	s_barrier
	s_add_i32 s4, s74, s1
	v_lshl_add_u64 v[180:181], s[34:35], 0, v[144:145]
	s_mov_b32 m0, s4
	ds_read_b128 v[208:211], v155 offset:16384
	ds_read_b128 v[212:215], v155 offset:17408
	ds_read_b128 v[216:219], v155 offset:18432
	ds_read_b128 v[220:223], v155 offset:19456
	ds_read_b128 v[224:227], v155 offset:20480
	ds_read_b128 v[228:231], v155 offset:21504
	ds_read_b128 v[232:235], v155 offset:22528
	ds_read_b128 v[236:239], v155 offset:23552
	global_load_lds_dwordx4 v[180:181], off
	s_add_i32 m0, s4, 0x2000
	s_add_u32 s4, s34, 0x40000
	v_lshl_add_u64 v[202:203], s[34:35], 0, v[128:129]
	s_addc_u32 s5, s35, 0
	s_add_i32 s74, s75, s1
	global_load_lds_dwordx4 v[202:203], off
	v_lshl_add_u64 v[240:241], s[4:5], 0, v[144:145]
	s_mov_b32 m0, s74
	v_lshl_add_u64 v[242:243], s[60:61], 0, v[130:131]
	global_load_lds_dwordx4 v[240:241], off
	v_lshl_add_u64 v[240:241], s[4:5], 0, v[128:129]
	s_add_i32 m0, s74, 0x2000
	s_nop 0
	global_load_lds_dwordx4 v[240:241], off
	v_lshl_add_u64 v[240:241], s[60:61], 0, v[132:133]
	s_mov_b32 m0, s59
	s_nop 0
	global_load_lds_dwordx4 v[240:241], off
	s_mov_b32 m0, s64
	s_nop 0
	global_load_lds_dwordx4 v[242:243], off
	s_waitcnt vmcnt(8)
	s_waitcnt lgkmcnt(0)
	s_barrier
	v_mfma_f32_16x16x32_bf16 v[60:63], v[138:141], v[208:211], v[60:63]
	v_mfma_f32_16x16x32_bf16 v[56:59], v[160:163], v[208:211], v[56:59]
	v_mfma_f32_16x16x32_bf16 v[44:47], v[138:141], v[216:219], v[44:47]
	v_mfma_f32_16x16x32_bf16 v[40:43], v[160:163], v[216:219], v[40:43]
	v_mfma_f32_16x16x32_bf16 v[28:31], v[138:141], v[224:227], v[28:31]
	v_mfma_f32_16x16x32_bf16 v[24:27], v[160:163], v[224:227], v[24:27]
	v_mfma_f32_16x16x32_bf16 v[12:15], v[138:141], v[232:235], v[12:15]
	v_mfma_f32_16x16x32_bf16 v[8:11], v[160:163], v[232:235], v[8:11]
	v_mfma_f32_16x16x32_bf16 v[60:63], v[156:159], v[212:215], v[60:63]
	v_mfma_f32_16x16x32_bf16 v[56:59], v[164:167], v[212:215], v[56:59]
	v_mfma_f32_16x16x32_bf16 v[44:47], v[156:159], v[220:223], v[44:47]
	v_mfma_f32_16x16x32_bf16 v[40:43], v[164:167], v[220:223], v[40:43]
	v_mfma_f32_16x16x32_bf16 v[28:31], v[156:159], v[228:231], v[28:31]
	v_mfma_f32_16x16x32_bf16 v[24:27], v[164:167], v[228:231], v[24:27]
	v_mfma_f32_16x16x32_bf16 v[12:15], v[156:159], v[236:239], v[12:15]
	v_mfma_f32_16x16x32_bf16 v[8:11], v[164:167], v[236:239], v[8:11]
	v_mfma_f32_16x16x32_bf16 v[52:55], v[168:171], v[208:211], v[52:55]
	v_mfma_f32_16x16x32_bf16 v[48:51], v[176:179], v[208:211], v[48:51]
	v_mfma_f32_16x16x32_bf16 v[36:39], v[168:171], v[216:219], v[36:39]
	v_mfma_f32_16x16x32_bf16 v[32:35], v[176:179], v[216:219], v[32:35]
	v_mfma_f32_16x16x32_bf16 v[20:23], v[168:171], v[224:227], v[20:23]
	v_mfma_f32_16x16x32_bf16 v[16:19], v[176:179], v[224:227], v[16:19]
	v_mfma_f32_16x16x32_bf16 v[4:7], v[168:171], v[232:235], v[4:7]
	v_mfma_f32_16x16x32_bf16 v[0:3], v[176:179], v[232:235], v[0:3]
	v_mfma_f32_16x16x32_bf16 v[52:55], v[172:175], v[212:215], v[52:55]
	v_mfma_f32_16x16x32_bf16 v[48:51], v[204:207], v[212:215], v[48:51]
	v_mfma_f32_16x16x32_bf16 v[36:39], v[172:175], v[220:223], v[36:39]
	v_mfma_f32_16x16x32_bf16 v[32:35], v[204:207], v[220:223], v[32:35]
	v_mfma_f32_16x16x32_bf16 v[20:23], v[172:175], v[228:231], v[20:23]
	v_mfma_f32_16x16x32_bf16 v[16:19], v[204:207], v[228:231], v[16:19]
	v_mfma_f32_16x16x32_bf16 v[4:7], v[172:175], v[236:239], v[4:7]
	v_mfma_f32_16x16x32_bf16 v[0:3], v[204:207], v[236:239], v[0:3]
	s_barrier
	v_add_u32_e32 v164, 0x18000, v143
	v_add_u32_e32 v204, 0x1c000, v143
	ds_read_b128 v[138:141], v164
	ds_read_b128 v[156:159], v164 offset:1024
	ds_read_b128 v[160:163], v164 offset:2048
	ds_read_b128 v[164:167], v164 offset:3072
	ds_read_b128 v[168:171], v204
	ds_read_b128 v[172:175], v204 offset:1024
	ds_read_b128 v[176:179], v204 offset:2048
	ds_read_b128 v[204:207], v204 offset:3072
	ds_read_b128 v[208:211], v155 offset:32768
	ds_read_b128 v[212:215], v155 offset:33792
	ds_read_b128 v[216:219], v155 offset:34816
	ds_read_b128 v[220:223], v155 offset:35840
	ds_read_b128 v[224:227], v155 offset:36864
	ds_read_b128 v[228:231], v155 offset:37888
	ds_read_b128 v[232:235], v155 offset:38912
	ds_read_b128 v[236:239], v155 offset:39936
	s_add_i32 s74, 0, 0x18000
	s_add_i32 s75, 0, 0x1c000
	s_add_u32 s4, s60, 0x40000
	s_addc_u32 s5, s61, 0
	s_mov_b32 m0, s65
	v_lshl_add_u64 v[244:245], s[4:5], 0, v[132:133]
	global_load_lds_dwordx4 v[244:245], off
	v_lshl_add_u64 v[244:245], s[4:5], 0, v[130:131]
	s_mov_b32 m0, s66
	s_nop 0
	global_load_lds_dwordx4 v[244:245], off
	s_waitcnt vmcnt(8)
	s_waitcnt lgkmcnt(0)
	s_barrier
	v_mfma_f32_16x16x32_bf16 v[124:127], v[138:141], v[208:211], v[124:127]
	v_mfma_f32_16x16x32_bf16 v[120:123], v[160:163], v[208:211], v[120:123]
	v_mfma_f32_16x16x32_bf16 v[108:111], v[138:141], v[216:219], v[108:111]
	v_mfma_f32_16x16x32_bf16 v[104:107], v[160:163], v[216:219], v[104:107]
	v_mfma_f32_16x16x32_bf16 v[92:95], v[138:141], v[224:227], v[92:95]
	v_mfma_f32_16x16x32_bf16 v[88:91], v[160:163], v[224:227], v[88:91]
	v_mfma_f32_16x16x32_bf16 v[76:79], v[138:141], v[232:235], v[76:79]
	v_mfma_f32_16x16x32_bf16 v[72:75], v[160:163], v[232:235], v[72:75]
	v_mfma_f32_16x16x32_bf16 v[124:127], v[156:159], v[212:215], v[124:127]
	v_mfma_f32_16x16x32_bf16 v[120:123], v[164:167], v[212:215], v[120:123]
	v_mfma_f32_16x16x32_bf16 v[108:111], v[156:159], v[220:223], v[108:111]
	v_mfma_f32_16x16x32_bf16 v[104:107], v[164:167], v[220:223], v[104:107]
	v_mfma_f32_16x16x32_bf16 v[92:95], v[156:159], v[228:231], v[92:95]
	v_mfma_f32_16x16x32_bf16 v[88:91], v[164:167], v[228:231], v[88:91]
	v_mfma_f32_16x16x32_bf16 v[76:79], v[156:159], v[236:239], v[76:79]
	v_mfma_f32_16x16x32_bf16 v[72:75], v[164:167], v[236:239], v[72:75]
	v_mfma_f32_16x16x32_bf16 v[116:119], v[168:171], v[208:211], v[116:119]
	v_mfma_f32_16x16x32_bf16 v[112:115], v[176:179], v[208:211], v[112:115]
	v_mfma_f32_16x16x32_bf16 v[100:103], v[168:171], v[216:219], v[100:103]
	v_mfma_f32_16x16x32_bf16 v[96:99], v[176:179], v[216:219], v[96:99]
	v_mfma_f32_16x16x32_bf16 v[84:87], v[168:171], v[224:227], v[84:87]
	v_mfma_f32_16x16x32_bf16 v[80:83], v[176:179], v[224:227], v[80:83]
	v_mfma_f32_16x16x32_bf16 v[68:71], v[168:171], v[232:235], v[68:71]
	v_mfma_f32_16x16x32_bf16 v[64:67], v[176:179], v[232:235], v[64:67]
	v_mfma_f32_16x16x32_bf16 v[116:119], v[172:175], v[212:215], v[116:119]
	v_mfma_f32_16x16x32_bf16 v[112:115], v[204:207], v[212:215], v[112:115]
	v_mfma_f32_16x16x32_bf16 v[100:103], v[172:175], v[220:223], v[100:103]
	v_mfma_f32_16x16x32_bf16 v[96:99], v[204:207], v[220:223], v[96:99]
	v_mfma_f32_16x16x32_bf16 v[84:87], v[172:175], v[228:231], v[84:87]
	v_mfma_f32_16x16x32_bf16 v[80:83], v[204:207], v[228:231], v[80:83]
	v_mfma_f32_16x16x32_bf16 v[68:71], v[172:175], v[236:239], v[68:71]
	v_mfma_f32_16x16x32_bf16 v[64:67], v[204:207], v[236:239], v[64:67]
	s_barrier
	s_add_i32 s4, s74, s1
	v_lshl_add_u64 v[180:181], v[180:181], 0, s[26:27]
	s_mov_b32 m0, s4
	ds_read_b128 v[208:211], v155 offset:49152
	ds_read_b128 v[212:215], v155 offset:50176
	ds_read_b128 v[216:219], v155 offset:51200
	ds_read_b128 v[220:223], v155 offset:52224
	ds_read_b128 v[224:227], v155 offset:53248
	ds_read_b128 v[228:231], v155 offset:54272
	ds_read_b128 v[232:235], v155 offset:55296
	ds_read_b128 v[236:239], v155 offset:56320
	global_load_lds_dwordx4 v[180:181], off
	s_add_i32 m0, s4, 0x2000
	s_add_u32 s4, s34, 0x40080
	v_lshl_add_u64 v[180:181], v[202:203], 0, s[26:27]
	s_addc_u32 s5, s35, 0
	s_add_i32 s34, s75, s1
	global_load_lds_dwordx4 v[180:181], off
	v_lshl_add_u64 v[180:181], s[4:5], 0, v[144:145]
	s_mov_b32 m0, s34
	s_nop 0
	global_load_lds_dwordx4 v[180:181], off
	v_lshl_add_u64 v[180:181], s[4:5], 0, v[128:129]
	s_add_i32 m0, s34, 0x2000
	s_nop 0
	global_load_lds_dwordx4 v[180:181], off
	v_lshl_add_u64 v[180:181], v[240:241], 0, s[26:27]
	s_mov_b32 m0, s67
	s_nop 0
	global_load_lds_dwordx4 v[180:181], off
	v_lshl_add_u64 v[180:181], v[242:243], 0, s[26:27]
	s_mov_b32 m0, s68
	s_nop 0
	global_load_lds_dwordx4 v[180:181], off
	s_add_i32 s73, s73, 2
	s_add_u32 s2, s2, 0x100
	s_addc_u32 s3, s3, 0
	s_add_u32 s71, s71, 0x100
	s_addc_u32 s72, s72, 0
	s_cmp_gt_u32 s73, 13
	s_waitcnt vmcnt(8)
	s_waitcnt lgkmcnt(0)
	s_barrier
	v_mfma_f32_16x16x32_bf16 v[60:63], v[138:141], v[208:211], v[60:63]
	v_mfma_f32_16x16x32_bf16 v[56:59], v[160:163], v[208:211], v[56:59]
	v_mfma_f32_16x16x32_bf16 v[44:47], v[138:141], v[216:219], v[44:47]
	v_mfma_f32_16x16x32_bf16 v[40:43], v[160:163], v[216:219], v[40:43]
	v_mfma_f32_16x16x32_bf16 v[28:31], v[138:141], v[224:227], v[28:31]
	v_mfma_f32_16x16x32_bf16 v[24:27], v[160:163], v[224:227], v[24:27]
	v_mfma_f32_16x16x32_bf16 v[12:15], v[138:141], v[232:235], v[12:15]
	v_mfma_f32_16x16x32_bf16 v[8:11], v[160:163], v[232:235], v[8:11]
	v_mfma_f32_16x16x32_bf16 v[60:63], v[156:159], v[212:215], v[60:63]
	v_mfma_f32_16x16x32_bf16 v[56:59], v[164:167], v[212:215], v[56:59]
	v_mfma_f32_16x16x32_bf16 v[44:47], v[156:159], v[220:223], v[44:47]
	v_mfma_f32_16x16x32_bf16 v[40:43], v[164:167], v[220:223], v[40:43]
	v_mfma_f32_16x16x32_bf16 v[28:31], v[156:159], v[228:231], v[28:31]
	v_mfma_f32_16x16x32_bf16 v[24:27], v[164:167], v[228:231], v[24:27]
	v_mfma_f32_16x16x32_bf16 v[12:15], v[156:159], v[236:239], v[12:15]
	v_mfma_f32_16x16x32_bf16 v[8:11], v[164:167], v[236:239], v[8:11]
	v_mfma_f32_16x16x32_bf16 v[52:55], v[168:171], v[208:211], v[52:55]
	v_mfma_f32_16x16x32_bf16 v[48:51], v[176:179], v[208:211], v[48:51]
	v_mfma_f32_16x16x32_bf16 v[36:39], v[168:171], v[216:219], v[36:39]
	v_mfma_f32_16x16x32_bf16 v[32:35], v[176:179], v[216:219], v[32:35]
	v_mfma_f32_16x16x32_bf16 v[20:23], v[168:171], v[224:227], v[20:23]
	v_mfma_f32_16x16x32_bf16 v[16:19], v[176:179], v[224:227], v[16:19]
	v_mfma_f32_16x16x32_bf16 v[4:7], v[168:171], v[232:235], v[4:7]
	v_mfma_f32_16x16x32_bf16 v[0:3], v[176:179], v[232:235], v[0:3]
	v_mfma_f32_16x16x32_bf16 v[52:55], v[172:175], v[212:215], v[52:55]
	v_mfma_f32_16x16x32_bf16 v[48:51], v[204:207], v[212:215], v[48:51]
	v_mfma_f32_16x16x32_bf16 v[36:39], v[172:175], v[220:223], v[36:39]
	v_mfma_f32_16x16x32_bf16 v[32:35], v[204:207], v[220:223], v[32:35]
	v_mfma_f32_16x16x32_bf16 v[20:23], v[172:175], v[228:231], v[20:23]
	v_mfma_f32_16x16x32_bf16 v[16:19], v[204:207], v[228:231], v[16:19]
	v_mfma_f32_16x16x32_bf16 v[4:7], v[172:175], v[236:239], v[4:7]
	v_mfma_f32_16x16x32_bf16 v[0:3], v[204:207], v[236:239], v[0:3]
	s_barrier
	s_cbranch_scc0 .LBB0_1305
	s_setprio 0
	v_lshl_add_u32 v140, s58, 8, v142
	v_ashrrev_i32_e32 v141, 31, v140
	v_lshl_add_u64 v[156:157], v[140:141], 4, s[44:45]
	global_load_dwordx4 v[208:211], v[156:157], off
	global_load_dwordx4 v[212:215], v[156:157], off offset:256
	global_load_dwordx4 v[216:219], v[156:157], off offset:512
	global_load_dwordx4 v[220:223], v[156:157], off offset:768
	global_load_dwordx4 v[224:227], v[156:157], off offset:2048
	global_load_dwordx4 v[228:231], v[156:157], off offset:2304
	global_load_dwordx4 v[232:235], v[156:157], off offset:2560
	global_load_dwordx4 v[236:239], v[156:157], off offset:2816
	s_and_b64 vcc, exec, s[46:47]
	s_cbranch_vccz .LBB0_1308
	s_barrier

.Lkprio_1399:
.LBB0_1399:
	v_add_u32_e32 v142, 0x10000, v160
	ds_read_b128 v[138:141], v142
	ds_read_b128 v[154:157], v142 offset:1024
	ds_read_b128 v[172:175], v142 offset:2048
	ds_read_b128 v[176:179], v142 offset:3072
	v_add_u32_e32 v142, 0x14000, v160
	ds_read_b128 v[204:207], v142
	ds_read_b128 v[208:211], v142 offset:1024
	ds_read_b128 v[212:215], v142 offset:2048
	ds_read_b128 v[216:219], v142 offset:3072
	ds_read_b128 v[220:223], v170
	ds_read_b128 v[224:227], v170 offset:1024
	ds_read_b128 v[228:231], v170 offset:2048
	ds_read_b128 v[232:235], v170 offset:3072
	ds_read_b128 v[236:239], v170 offset:4096
	ds_read_b128 v[240:243], v170 offset:5120
	ds_read_b128 v[244:247], v170 offset:6144
	ds_read_b128 v[248:251], v170 offset:7168
	s_add_u32 s58, s54, 0x100
	s_addc_u32 s59, s55, 0
	s_add_i32 s4, 0, 0x10000
	s_cmp_eq_u32 s29, 40
	s_cselect_b32 s61, s45, s59
	s_cselect_b32 s60, s44, s58
	s_cselect_b32 s35, s53, s28
	s_cselect_b32 s34, s52, s3
	s_add_i32 s47, 0, 0x14000
	v_lshl_add_u64 v[142:143], s[54:55], 0, v[134:135]
	s_add_i32 m0, s65, 0xc000
	s_nop 0
	global_load_lds_dwordx4 v[142:143], off
	v_lshl_add_u64 v[142:143], s[54:55], 0, v[136:137]
	s_add_i32 m0, s65, 0xe000
	s_nop 0
	global_load_lds_dwordx4 v[142:143], off
	s_waitcnt vmcnt(8)
	s_waitcnt lgkmcnt(0)
	s_barrier
	v_mfma_f32_16x16x32_bf16 v[124:127], v[138:141], v[220:223], v[124:127]
	v_mfma_f32_16x16x32_bf16 v[120:123], v[172:175], v[220:223], v[120:123]
	v_mfma_f32_16x16x32_bf16 v[108:111], v[138:141], v[228:231], v[108:111]
	v_mfma_f32_16x16x32_bf16 v[104:107], v[172:175], v[228:231], v[104:107]
	v_mfma_f32_16x16x32_bf16 v[92:95], v[138:141], v[236:239], v[92:95]
	v_mfma_f32_16x16x32_bf16 v[88:91], v[172:175], v[236:239], v[88:91]
	v_mfma_f32_16x16x32_bf16 v[76:79], v[138:141], v[244:247], v[76:79]
	v_mfma_f32_16x16x32_bf16 v[72:75], v[172:175], v[244:247], v[72:75]
	v_mfma_f32_16x16x32_bf16 v[124:127], v[154:157], v[224:227], v[124:127]
	v_mfma_f32_16x16x32_bf16 v[120:123], v[176:179], v[224:227], v[120:123]
	v_mfma_f32_16x16x32_bf16 v[108:111], v[154:157], v[232:235], v[108:111]
	v_mfma_f32_16x16x32_bf16 v[104:107], v[176:179], v[232:235], v[104:107]
	v_mfma_f32_16x16x32_bf16 v[92:95], v[154:157], v[240:243], v[92:95]
	v_mfma_f32_16x16x32_bf16 v[88:91], v[176:179], v[240:243], v[88:91]
	v_mfma_f32_16x16x32_bf16 v[76:79], v[154:157], v[248:251], v[76:79]
	v_mfma_f32_16x16x32_bf16 v[72:75], v[176:179], v[248:251], v[72:75]
	v_mfma_f32_16x16x32_bf16 v[116:119], v[204:207], v[220:223], v[116:119]
	v_mfma_f32_16x16x32_bf16 v[112:115], v[212:215], v[220:223], v[112:115]
	v_mfma_f32_16x16x32_bf16 v[100:103], v[204:207], v[228:231], v[100:103]
	v_mfma_f32_16x16x32_bf16 v[96:99], v[212:215], v[228:231], v[96:99]
	v_mfma_f32_16x16x32_bf16 v[84:87], v[204:207], v[236:239], v[84:87]
	v_mfma_f32_16x16x32_bf16 v[80:83], v[212:215], v[236:239], v[80:83]
	v_mfma_f32_16x16x32_bf16 v[68:71], v[204:207], v[244:247], v[68:71]
	v_mfma_f32_16x16x32_bf16 v[64:67], v[212:215], v[244:247], v[64:67]
	v_mfma_f32_16x16x32_bf16 v[116:119], v[208:211], v[224:227], v[116:119]
	v_mfma_f32_16x16x32_bf16 v[112:115], v[216:219], v[224:227], v[112:115]
	v_mfma_f32_16x16x32_bf16 v[100:103], v[208:211], v[232:235], v[100:103]
	v_mfma_f32_16x16x32_bf16 v[96:99], v[216:219], v[232:235], v[96:99]
	v_mfma_f32_16x16x32_bf16 v[84:87], v[208:211], v[240:243], v[84:87]
	v_mfma_f32_16x16x32_bf16 v[80:83], v[216:219], v[240:243], v[80:83]
	v_mfma_f32_16x16x32_bf16 v[68:71], v[208:211], v[248:251], v[68:71]
	v_mfma_f32_16x16x32_bf16 v[64:67], v[216:219], v[248:251], v[64:67]
	s_barrier
	s_add_i32 s4, s4, s33
	v_lshl_add_u64 v[142:143], s[34:35], 0, v[128:129]
	s_mov_b32 m0, s4
	ds_read_b128 v[220:223], v170 offset:16384
	ds_read_b128 v[224:227], v170 offset:17408
	ds_read_b128 v[228:231], v170 offset:18432
	ds_read_b128 v[232:235], v170 offset:19456
	ds_read_b128 v[236:239], v170 offset:20480
	ds_read_b128 v[240:243], v170 offset:21504
	ds_read_b128 v[244:247], v170 offset:22528
	ds_read_b128 v[248:251], v170 offset:23552
	global_load_lds_dwordx4 v[142:143], off
	s_add_i32 m0, s4, 0x2000
	s_add_u32 s4, s34, 0xb0000
	v_lshl_add_u64 v[158:159], s[34:35], 0, v[130:131]
	s_addc_u32 s5, s35, 0
	s_add_i32 s47, s47, s33
	global_load_lds_dwordx4 v[158:159], off
	v_lshl_add_u64 v[180:181], s[4:5], 0, v[128:129]
	s_mov_b32 m0, s47
	v_lshl_add_u64 v[202:203], s[60:61], 0, v[130:131]
	global_load_lds_dwordx4 v[180:181], off
	v_lshl_add_u64 v[180:181], s[4:5], 0, v[130:131]
	s_add_i32 m0, s47, 0x2000
	s_nop 0
	global_load_lds_dwordx4 v[180:181], off
	v_lshl_add_u64 v[180:181], s[60:61], 0, v[128:129]
	s_mov_b32 m0, s65
	s_nop 0
	global_load_lds_dwordx4 v[180:181], off
	s_mov_b32 m0, s66
	s_nop 0
	global_load_lds_dwordx4 v[202:203], off
	s_waitcnt vmcnt(8)
	s_waitcnt lgkmcnt(0)
	s_barrier
	v_mfma_f32_16x16x32_bf16 v[60:63], v[138:141], v[220:223], v[60:63]
	v_mfma_f32_16x16x32_bf16 v[56:59], v[172:175], v[220:223], v[56:59]
	v_mfma_f32_16x16x32_bf16 v[44:47], v[138:141], v[228:231], v[44:47]
	v_mfma_f32_16x16x32_bf16 v[40:43], v[172:175], v[228:231], v[40:43]
	v_mfma_f32_16x16x32_bf16 v[28:31], v[138:141], v[236:239], v[28:31]
	v_mfma_f32_16x16x32_bf16 v[24:27], v[172:175], v[236:239], v[24:27]
	v_mfma_f32_16x16x32_bf16 v[12:15], v[138:141], v[244:247], v[12:15]
	v_mfma_f32_16x16x32_bf16 v[8:11], v[172:175], v[244:247], v[8:11]
	v_mfma_f32_16x16x32_bf16 v[60:63], v[154:157], v[224:227], v[60:63]
	v_mfma_f32_16x16x32_bf16 v[56:59], v[176:179], v[224:227], v[56:59]
	v_mfma_f32_16x16x32_bf16 v[44:47], v[154:157], v[232:235], v[44:47]
	v_mfma_f32_16x16x32_bf16 v[40:43], v[176:179], v[232:235], v[40:43]
	v_mfma_f32_16x16x32_bf16 v[28:31], v[154:157], v[240:243], v[28:31]
	v_mfma_f32_16x16x32_bf16 v[24:27], v[176:179], v[240:243], v[24:27]
	v_mfma_f32_16x16x32_bf16 v[12:15], v[154:157], v[248:251], v[12:15]
	v_mfma_f32_16x16x32_bf16 v[8:11], v[176:179], v[248:251], v[8:11]
	v_mfma_f32_16x16x32_bf16 v[52:55], v[204:207], v[220:223], v[52:55]
	v_mfma_f32_16x16x32_bf16 v[48:51], v[212:215], v[220:223], v[48:51]
	v_mfma_f32_16x16x32_bf16 v[36:39], v[204:207], v[228:231], v[36:39]
	v_mfma_f32_16x16x32_bf16 v[32:35], v[212:215], v[228:231], v[32:35]
	v_mfma_f32_16x16x32_bf16 v[20:23], v[204:207], v[236:239], v[20:23]
	v_mfma_f32_16x16x32_bf16 v[16:19], v[212:215], v[236:239], v[16:19]
	v_mfma_f32_16x16x32_bf16 v[4:7], v[204:207], v[244:247], v[4:7]
	v_mfma_f32_16x16x32_bf16 v[0:3], v[212:215], v[244:247], v[0:3]
	v_mfma_f32_16x16x32_bf16 v[52:55], v[208:211], v[224:227], v[52:55]
	v_mfma_f32_16x16x32_bf16 v[48:51], v[216:219], v[224:227], v[48:51]
	v_mfma_f32_16x16x32_bf16 v[36:39], v[208:211], v[232:235], v[36:39]
	v_mfma_f32_16x16x32_bf16 v[32:35], v[216:219], v[232:235], v[32:35]
	v_mfma_f32_16x16x32_bf16 v[20:23], v[208:211], v[240:243], v[20:23]
	v_mfma_f32_16x16x32_bf16 v[16:19], v[216:219], v[240:243], v[16:19]
	v_mfma_f32_16x16x32_bf16 v[4:7], v[208:211], v[248:251], v[4:7]
	v_mfma_f32_16x16x32_bf16 v[0:3], v[216:219], v[248:251], v[0:3]
	s_barrier
	v_add_u32_e32 v144, 0x18000, v160
	ds_read_b128 v[138:141], v144
	ds_read_b128 v[154:157], v144 offset:1024
	ds_read_b128 v[172:175], v144 offset:2048
	ds_read_b128 v[176:179], v144 offset:3072
	v_add_u32_e32 v144, 0x1c000, v160
	ds_read_b128 v[204:207], v144
	ds_read_b128 v[208:211], v144 offset:1024
	ds_read_b128 v[212:215], v144 offset:2048
	ds_read_b128 v[216:219], v144 offset:3072
	ds_read_b128 v[220:223], v170 offset:32768
	ds_read_b128 v[224:227], v170 offset:33792
	ds_read_b128 v[228:231], v170 offset:34816
	ds_read_b128 v[232:235], v170 offset:35840
	ds_read_b128 v[236:239], v170 offset:36864
	ds_read_b128 v[240:243], v170 offset:37888
	ds_read_b128 v[244:247], v170 offset:38912
	ds_read_b128 v[248:251], v170 offset:39936
	s_add_i32 s47, 0, 0x18000
	s_add_i32 s54, 0, 0x1c000
	s_add_u32 s4, s60, 0xb0000
	s_addc_u32 s5, s61, 0
	s_mov_b32 m0, s67
	v_lshl_add_u64 v[252:253], s[4:5], 0, v[128:129]
	global_load_lds_dwordx4 v[252:253], off
	v_lshl_add_u64 v[252:253], s[4:5], 0, v[130:131]
	s_mov_b32 m0, s68
	s_nop 0
	global_load_lds_dwordx4 v[252:253], off
	s_waitcnt vmcnt(8)
	s_waitcnt lgkmcnt(0)
	s_barrier
	v_mfma_f32_16x16x32_bf16 v[124:127], v[138:141], v[220:223], v[124:127]
	v_mfma_f32_16x16x32_bf16 v[120:123], v[172:175], v[220:223], v[120:123]
	v_mfma_f32_16x16x32_bf16 v[108:111], v[138:141], v[228:231], v[108:111]
	v_mfma_f32_16x16x32_bf16 v[104:107], v[172:175], v[228:231], v[104:107]
	v_mfma_f32_16x16x32_bf16 v[92:95], v[138:141], v[236:239], v[92:95]
	v_mfma_f32_16x16x32_bf16 v[88:91], v[172:175], v[236:239], v[88:91]
	v_mfma_f32_16x16x32_bf16 v[76:79], v[138:141], v[244:247], v[76:79]
	v_mfma_f32_16x16x32_bf16 v[72:75], v[172:175], v[244:247], v[72:75]
	v_mfma_f32_16x16x32_bf16 v[124:127], v[154:157], v[224:227], v[124:127]
	v_mfma_f32_16x16x32_bf16 v[120:123], v[176:179], v[224:227], v[120:123]
	v_mfma_f32_16x16x32_bf16 v[108:111], v[154:157], v[232:235], v[108:111]
	v_mfma_f32_16x16x32_bf16 v[104:107], v[176:179], v[232:235], v[104:107]
	v_mfma_f32_16x16x32_bf16 v[92:95], v[154:157], v[240:243], v[92:95]
	v_mfma_f32_16x16x32_bf16 v[88:91], v[176:179], v[240:243], v[88:91]
	v_mfma_f32_16x16x32_bf16 v[76:79], v[154:157], v[248:251], v[76:79]
	v_mfma_f32_16x16x32_bf16 v[72:75], v[176:179], v[248:251], v[72:75]
	v_mfma_f32_16x16x32_bf16 v[116:119], v[204:207], v[220:223], v[116:119]
	v_mfma_f32_16x16x32_bf16 v[112:115], v[212:215], v[220:223], v[112:115]
	v_mfma_f32_16x16x32_bf16 v[100:103], v[204:207], v[228:231], v[100:103]
	v_mfma_f32_16x16x32_bf16 v[96:99], v[212:215], v[228:231], v[96:99]
	v_mfma_f32_16x16x32_bf16 v[84:87], v[204:207], v[236:239], v[84:87]
	v_mfma_f32_16x16x32_bf16 v[80:83], v[212:215], v[236:239], v[80:83]
	v_mfma_f32_16x16x32_bf16 v[68:71], v[204:207], v[244:247], v[68:71]
	v_mfma_f32_16x16x32_bf16 v[64:67], v[212:215], v[244:247], v[64:67]
	v_mfma_f32_16x16x32_bf16 v[116:119], v[208:211], v[224:227], v[116:119]
	v_mfma_f32_16x16x32_bf16 v[112:115], v[216:219], v[224:227], v[112:115]
	v_mfma_f32_16x16x32_bf16 v[100:103], v[208:211], v[232:235], v[100:103]
	v_mfma_f32_16x16x32_bf16 v[96:99], v[216:219], v[232:235], v[96:99]
	v_mfma_f32_16x16x32_bf16 v[84:87], v[208:211], v[240:243], v[84:87]
	v_mfma_f32_16x16x32_bf16 v[80:83], v[216:219], v[240:243], v[80:83]
	v_mfma_f32_16x16x32_bf16 v[68:71], v[208:211], v[248:251], v[68:71]
	v_mfma_f32_16x16x32_bf16 v[64:67], v[216:219], v[248:251], v[64:67]
	s_barrier
	s_add_i32 s4, s47, s33
	v_lshl_add_u64 v[142:143], v[142:143], 0, s[26:27]
	s_mov_b32 m0, s4
	ds_read_b128 v[220:223], v170 offset:49152
	ds_read_b128 v[224:227], v170 offset:50176
	ds_read_b128 v[228:231], v170 offset:51200
	ds_read_b128 v[232:235], v170 offset:52224
	ds_read_b128 v[236:239], v170 offset:53248
	ds_read_b128 v[240:243], v170 offset:54272
	ds_read_b128 v[244:247], v170 offset:55296
	ds_read_b128 v[248:251], v170 offset:56320
	global_load_lds_dwordx4 v[142:143], off
	s_add_i32 m0, s4, 0x2000
	s_add_u32 s4, s34, 0xb0080
	v_lshl_add_u64 v[142:143], v[158:159], 0, s[26:27]
	s_addc_u32 s5, s35, 0
	s_add_i32 s34, s54, s33
	global_load_lds_dwordx4 v[142:143], off
	v_lshl_add_u64 v[142:143], s[4:5], 0, v[128:129]
	s_mov_b32 m0, s34
	s_nop 0
	global_load_lds_dwordx4 v[142:143], off
	v_lshl_add_u64 v[142:143], s[4:5], 0, v[130:131]
	s_add_i32 m0, s34, 0x2000
	s_nop 0
	global_load_lds_dwordx4 v[142:143], off
	v_lshl_add_u64 v[142:143], v[180:181], 0, s[26:27]
	s_mov_b32 m0, s69
	s_nop 0
	global_load_lds_dwordx4 v[142:143], off
	v_lshl_add_u64 v[142:143], v[202:203], 0, s[26:27]
	s_mov_b32 m0, s70
	s_nop 0
	global_load_lds_dwordx4 v[142:143], off
	s_add_i32 s29, s29, 2
	s_add_u32 s3, s3, 0x100
	s_addc_u32 s28, s28, 0
	s_cmp_gt_u32 s29, 41
	s_mov_b64 s[54:55], s[58:59]
	s_waitcnt vmcnt(8)
	s_waitcnt lgkmcnt(0)
	s_barrier
	v_mfma_f32_16x16x32_bf16 v[60:63], v[138:141], v[220:223], v[60:63]
	v_mfma_f32_16x16x32_bf16 v[56:59], v[172:175], v[220:223], v[56:59]
	v_mfma_f32_16x16x32_bf16 v[44:47], v[138:141], v[228:231], v[44:47]
	v_mfma_f32_16x16x32_bf16 v[40:43], v[172:175], v[228:231], v[40:43]
	v_mfma_f32_16x16x32_bf16 v[28:31], v[138:141], v[236:239], v[28:31]
	v_mfma_f32_16x16x32_bf16 v[24:27], v[172:175], v[236:239], v[24:27]
	v_mfma_f32_16x16x32_bf16 v[12:15], v[138:141], v[244:247], v[12:15]
	v_mfma_f32_16x16x32_bf16 v[8:11], v[172:175], v[244:247], v[8:11]
	v_mfma_f32_16x16x32_bf16 v[60:63], v[154:157], v[224:227], v[60:63]
	v_mfma_f32_16x16x32_bf16 v[56:59], v[176:179], v[224:227], v[56:59]
	v_mfma_f32_16x16x32_bf16 v[44:47], v[154:157], v[232:235], v[44:47]
	v_mfma_f32_16x16x32_bf16 v[40:43], v[176:179], v[232:235], v[40:43]
	v_mfma_f32_16x16x32_bf16 v[28:31], v[154:157], v[240:243], v[28:31]
	v_mfma_f32_16x16x32_bf16 v[24:27], v[176:179], v[240:243], v[24:27]
	v_mfma_f32_16x16x32_bf16 v[12:15], v[154:157], v[248:251], v[12:15]
	v_mfma_f32_16x16x32_bf16 v[8:11], v[176:179], v[248:251], v[8:11]
	v_mfma_f32_16x16x32_bf16 v[52:55], v[204:207], v[220:223], v[52:55]
	v_mfma_f32_16x16x32_bf16 v[48:51], v[212:215], v[220:223], v[48:51]
	v_mfma_f32_16x16x32_bf16 v[36:39], v[204:207], v[228:231], v[36:39]
	v_mfma_f32_16x16x32_bf16 v[32:35], v[212:215], v[228:231], v[32:35]
	v_mfma_f32_16x16x32_bf16 v[20:23], v[204:207], v[236:239], v[20:23]
	v_mfma_f32_16x16x32_bf16 v[16:19], v[212:215], v[236:239], v[16:19]
	v_mfma_f32_16x16x32_bf16 v[4:7], v[204:207], v[244:247], v[4:7]
	v_mfma_f32_16x16x32_bf16 v[0:3], v[212:215], v[244:247], v[0:3]
	v_mfma_f32_16x16x32_bf16 v[52:55], v[208:211], v[224:227], v[52:55]
	v_mfma_f32_16x16x32_bf16 v[48:51], v[216:219], v[224:227], v[48:51]
	v_mfma_f32_16x16x32_bf16 v[36:39], v[208:211], v[232:235], v[36:39]
	v_mfma_f32_16x16x32_bf16 v[32:35], v[216:219], v[232:235], v[32:35]
	v_mfma_f32_16x16x32_bf16 v[20:23], v[208:211], v[240:243], v[20:23]
	v_mfma_f32_16x16x32_bf16 v[16:19], v[216:219], v[240:243], v[16:19]
	v_mfma_f32_16x16x32_bf16 v[4:7], v[208:211], v[248:251], v[4:7]
	v_mfma_f32_16x16x32_bf16 v[0:3], v[216:219], v[248:251], v[0:3]
	s_barrier
	s_cbranch_scc0 .LBB0_1399
	s_setprio 0
	s_and_b64 vcc, exec, s[50:51]
	s_cbranch_vccz .LBB0_1402
	s_barrier
